# v16 + the load segment's vmcnt and lgkmcnt waits merged into one s_waitcnt (after s_setprio 1) in front of the opening barrier
# baseline (speedup 1.0000x reference)
; #define GAS __attribute__((address_space(1)))
; #define PG8_STAGE(bufoff, gbase, voff) do { _Pragma("unroll") for (int _i = 0; _i < 2; ++_i) \
;         __builtin_amdgcn_global_load_lds((const GAS unsigned*)((const GAS char*)(gbase) + (voff)[_i]), (LAS unsigned*)(lds + (bufoff) + ldsw + _i * 8192), 16, 0, 0); } while (0)
; #define PG8_LDA(dst, b, h) do { _Pragma("unroll") for (int m = 0; m < 4; ++m) _Pragma("unroll") for (int k = 0; k < 2; ++k) dst[m][k] = *(const LAS bf16x8*)(lds + PG8_SA(b, h) + aoff + m * 2048 + k * 1024); } while (0)
; #define PG8_LDB(dst, b, h) do { _Pragma("unroll") for (int n = 0; n < 2; ++n) _Pragma("unroll") for (int k = 0; k < 2; ++k) dst[n][k] = *(const LAS bf16x8*)(lds + PG8_SB(b, h) + boff + n * 2048 + k * 1024); } while (0)
; #define PG8_MMA(ai, bj, At, Bt) do { __builtin_amdgcn_s_setprio(1); _Pragma("unroll") for (int m = 0; m < 4; ++m) _Pragma("unroll") for (int n = 0; n < 2; ++n) _Pragma("unroll") for (int k = 0; k < 2; ++k) \
;         acc[ai][bj][m][n] = __builtin_amdgcn_mfma_f32_16x16x32_bf16(Bt[n][k], At[m][k], acc[ai][bj][m][n], 0, 0, 0); __builtin_amdgcn_s_setprio(0); } while (0)
; #define PG8_WAIT_V(n) asm volatile("s_waitcnt vmcnt(" #n ")" ::: "memory")
; #define PG8_WAIT_L(n) asm volatile("s_waitcnt lgkmcnt(" #n ")" ::: "memory")
; #define PG8_BAR __builtin_amdgcn_s_barrier()
; template <class Epi, class Sched, bool ALIGN_EPI>
; __device__ __forceinline__ void gemm_phase(LAS unsigned char* lds, const Gemm g, const Sched& S, const Epi& E, int wave_id) {
;     ...
;             const bool last = (t == nt - 2);
;             const GAS char* a1 = cA + (size_t)(t + 1) * kstep;
;             const GAS char* a2 = last ? nA : cA + (size_t)(t + 2) * kstep; const GAS char* b2 = last ? nB : cB + (size_t)(t + 2) * kstep;
;             const GAS char* a3 = a2 + kstep; const GAS char* b3 = b2 + kstep;
;             PG8_LDB(B0, 0, 0); PG8_LDB(B1, 0, 1); PG8_SCHED; PG8_LDA(At, 0, 0); PG8_STAGE(PG8_SA(1, 1), a1 + hsA, voffA);
;             PG8_WAIT_V(8); PG8_WAIT_L(0); PG8_BAR; PG8_MMA(0, 0, At, B0); PG8_MMA(0, 1, At, B1); PG8_BAR; PG8_SCHED;
;             PG8_LDA(At, 0, 1); PG8_STAGE(PG8_SB(0, 0), b2, voffB); PG8_STAGE(PG8_SB(0, 1), b2 + hsB, voffB); PG8_STAGE(PG8_SA(0, 0), a2, voffA);
;             PG8_WAIT_V(8); PG8_WAIT_L(0); PG8_BAR; PG8_MMA(1, 0, At, B0); PG8_MMA(1, 1, At, B1); PG8_BAR; PG8_SCHED;
.LBB0_1117:
	s_add_u32 s58, s0, 0xfff80080
	s_addc_u32 s59, s1, -1
	s_cmp_eq_u32 s76, 28
	s_cselect_b32 s61, s33, s59
	s_cselect_b32 s60, s47, s58
	s_cselect_b32 s59, s49, s74
	s_cselect_b32 s58, s57, s71
	s_mov_b32 m0, s87
	v_lshl_add_u64 v[206:207], s[0:1], 0, v[204:205]
	global_load_lds_dwordx4 v[206:207], off
	v_lshl_add_u64 v[206:207], s[0:1], 0, v[202:203]
	s_mov_b32 m0, s88
	s_nop 0
	global_load_lds_dwordx4 v[206:207], off
	v_add_u32_e32 v0, 0x10400, v250
	ds_read_b128 v[130:133], v0
	ds_read_b128 v[134:137], v0 offset:1024
	ds_read_b128 v[138:141], v0 offset:2048
	ds_read_b128 v[142:145], v0 offset:3072
	v_add_u32_e32 v0, 0x14400, v250
	ds_read_b128 v[146:149], v0
	ds_read_b128 v[150:153], v0 offset:1024
	ds_read_b128 v[154:157], v0 offset:2048
	ds_read_b128 v[158:161], v0 offset:3072
	ds_read_b128 v[162:165], v253 offset:1024
	ds_read_b128 v[166:169], v253 offset:2048
	ds_read_b128 v[170:173], v253 offset:3072
	ds_read_b128 v[174:177], v253 offset:4096
	ds_read_b128 v[178:181], v253 offset:5120
	ds_read_b128 v[182:185], v253 offset:6144
	ds_read_b128 v[186:189], v253 offset:7168
	ds_read_b128 v[190:193], v253 offset:8192
	s_setprio 1
	s_waitcnt vmcnt(8) lgkmcnt(0)
	s_barrier
	v_mfma_f32_16x16x32_bf16 v[126:129], v[130:133], v[162:165], v[126:129]
	v_mfma_f32_16x16x32_bf16 v[122:125], v[138:141], v[162:165], v[122:125]
	v_mfma_f32_16x16x32_bf16 v[110:113], v[130:133], v[170:173], v[110:113]
	v_mfma_f32_16x16x32_bf16 v[106:109], v[138:141], v[170:173], v[106:109]
	v_mfma_f32_16x16x32_bf16 v[94:97], v[130:133], v[178:181], v[94:97]
	v_mfma_f32_16x16x32_bf16 v[90:93], v[138:141], v[178:181], v[90:93]
	v_mfma_f32_16x16x32_bf16 v[78:81], v[130:133], v[186:189], v[78:81]
	v_mfma_f32_16x16x32_bf16 v[74:77], v[138:141], v[186:189], v[74:77]
	v_mfma_f32_16x16x32_bf16 v[126:129], v[134:137], v[166:169], v[126:129]
	v_mfma_f32_16x16x32_bf16 v[122:125], v[142:145], v[166:169], v[122:125]
	v_mfma_f32_16x16x32_bf16 v[110:113], v[134:137], v[174:177], v[110:113]
	v_mfma_f32_16x16x32_bf16 v[106:109], v[142:145], v[174:177], v[106:109]
	v_mfma_f32_16x16x32_bf16 v[94:97], v[134:137], v[182:185], v[94:97]
	v_mfma_f32_16x16x32_bf16 v[90:93], v[142:145], v[182:185], v[90:93]
	v_mfma_f32_16x16x32_bf16 v[78:81], v[134:137], v[190:193], v[78:81]
	v_mfma_f32_16x16x32_bf16 v[74:77], v[142:145], v[190:193], v[74:77]
	s_setprio 0
	s_setprio 1
	v_mfma_f32_16x16x32_bf16 v[118:121], v[146:149], v[162:165], v[118:121]
	v_mfma_f32_16x16x32_bf16 v[114:117], v[154:157], v[162:165], v[114:117]
	v_mfma_f32_16x16x32_bf16 v[102:105], v[146:149], v[170:173], v[102:105]
	v_mfma_f32_16x16x32_bf16 v[98:101], v[154:157], v[170:173], v[98:101]
	v_mfma_f32_16x16x32_bf16 v[86:89], v[146:149], v[178:181], v[86:89]
	v_mfma_f32_16x16x32_bf16 v[82:85], v[154:157], v[178:181], v[82:85]
	v_mfma_f32_16x16x32_bf16 v[70:73], v[146:149], v[186:189], v[70:73]
	v_mfma_f32_16x16x32_bf16 v[66:69], v[154:157], v[186:189], v[66:69]
	v_mfma_f32_16x16x32_bf16 v[118:121], v[150:153], v[166:169], v[118:121]
	v_mfma_f32_16x16x32_bf16 v[114:117], v[158:161], v[166:169], v[114:117]
	v_mfma_f32_16x16x32_bf16 v[102:105], v[150:153], v[174:177], v[102:105]
	v_mfma_f32_16x16x32_bf16 v[98:101], v[158:161], v[174:177], v[98:101]
	v_mfma_f32_16x16x32_bf16 v[86:89], v[150:153], v[182:185], v[86:89]
	v_mfma_f32_16x16x32_bf16 v[82:85], v[158:161], v[182:185], v[82:85]
	v_mfma_f32_16x16x32_bf16 v[70:73], v[150:153], v[190:193], v[70:73]
	v_mfma_f32_16x16x32_bf16 v[66:69], v[158:161], v[190:193], v[66:69]
	s_setprio 0
	s_barrier
	s_mov_b32 m0, s15
	v_lshl_add_u64 v[206:207], s[58:59], 0, v[196:197]
	s_add_u32 vcc_lo, s58, 0x80000
	global_load_lds_dwordx4 v[206:207], off
	v_lshl_add_u64 v[208:209], s[58:59], 0, v[200:201]
	s_mov_b32 m0, s73
	s_addc_u32 vcc_hi, s59, 0
	global_load_lds_dwordx4 v[208:209], off
	v_lshl_add_u64 v[210:211], vcc, 0, v[196:197]
	s_mov_b32 m0, s75
	v_lshl_add_u64 v[212:213], s[60:61], 0, v[198:199]
	global_load_lds_dwordx4 v[210:211], off
	v_lshl_add_u64 v[210:211], vcc, 0, v[200:201]
	s_mov_b32 m0, s80
	s_nop 0
	global_load_lds_dwordx4 v[210:211], off
	v_lshl_add_u64 v[210:211], s[60:61], 0, v[194:195]
	s_mov_b32 m0, s81
	s_nop 0
	global_load_lds_dwordx4 v[210:211], off
	s_mov_b32 m0, s82
	s_nop 0
	global_load_lds_dwordx4 v[212:213], off
	ds_read_b128 v[162:165], v253 offset:17408
	ds_read_b128 v[166:169], v253 offset:18432
	ds_read_b128 v[170:173], v253 offset:19456
	ds_read_b128 v[174:177], v253 offset:20480
	ds_read_b128 v[178:181], v253 offset:21504
	ds_read_b128 v[182:185], v253 offset:22528
	ds_read_b128 v[186:189], v253 offset:23552
	ds_read_b128 v[190:193], v253 offset:24576
	s_setprio 1
	s_waitcnt vmcnt(8) lgkmcnt(0)
	s_barrier
; #define PG8_STAGE(bufoff, gbase, voff) do { _Pragma("unroll") for (int _i = 0; _i < 2; ++_i) \
;         __builtin_amdgcn_global_load_lds((const GAS unsigned*)((const GAS char*)(gbase) + (voff)[_i]), (LAS unsigned*)(lds + (bufoff) + ldsw + _i * 8192), 16, 0, 0); } while (0)
; #define PG8_LDA(dst, b, h) do { _Pragma("unroll") for (int m = 0; m < 4; ++m) _Pragma("unroll") for (int k = 0; k < 2; ++k) dst[m][k] = *(const LAS bf16x8*)(lds + PG8_SA(b, h) + aoff + m * 2048 + k * 1024); } while (0)
; #define PG8_LDB(dst, b, h) do { _Pragma("unroll") for (int n = 0; n < 2; ++n) _Pragma("unroll") for (int k = 0; k < 2; ++k) dst[n][k] = *(const LAS bf16x8*)(lds + PG8_SB(b, h) + boff + n * 2048 + k * 1024); } while (0)
; #define PG8_MMA(ai, bj, At, Bt) do { __builtin_amdgcn_s_setprio(1); _Pragma("unroll") for (int m = 0; m < 4; ++m) _Pragma("unroll") for (int n = 0; n < 2; ++n) _Pragma("unroll") for (int k = 0; k < 2; ++k) \
;         acc[ai][bj][m][n] = __builtin_amdgcn_mfma_f32_16x16x32_bf16(Bt[n][k], At[m][k], acc[ai][bj][m][n], 0, 0, 0); __builtin_amdgcn_s_setprio(0); } while (0)
; #define PG8_WAIT_V(n) asm volatile("s_waitcnt vmcnt(" #n ")" ::: "memory")
; #define PG8_WAIT_L(n) asm volatile("s_waitcnt lgkmcnt(" #n ")" ::: "memory")
; #define PG8_BAR __builtin_amdgcn_s_barrier()
; #define PG8_SCHED __builtin_amdgcn_sched_barrier(0)
; template <class Epi, class Sched, bool ALIGN_EPI>
; __device__ __forceinline__ void gemm_phase(LAS unsigned char* lds, const Gemm g, const Sched& S, const Epi& E, int wave_id) {
;     ...
;             PG8_WAIT_V(8); PG8_WAIT_L(0); PG8_BAR; PG8_MMA(1, 0, At, B0); PG8_MMA(1, 1, At, B1); PG8_BAR; PG8_SCHED;
;             PG8_LDB(B0, 1, 0); PG8_LDB(B1, 1, 1); PG8_SCHED; PG8_LDA(At, 1, 0); PG8_STAGE(PG8_SA(0, 1), a2 + hsA, voffA);
;             PG8_WAIT_V(8); PG8_WAIT_L(0); PG8_BAR; PG8_MMA(0, 0, At, B0); PG8_MMA(0, 1, At, B1); PG8_BAR; PG8_SCHED;
	v_mfma_f32_16x16x32_bf16 v[62:65], v[130:133], v[162:165], v[62:65]
	v_mfma_f32_16x16x32_bf16 v[58:61], v[138:141], v[162:165], v[58:61]
	v_mfma_f32_16x16x32_bf16 v[46:49], v[130:133], v[170:173], v[46:49]
	v_mfma_f32_16x16x32_bf16 v[42:45], v[138:141], v[170:173], v[42:45]
	v_mfma_f32_16x16x32_bf16 v[30:33], v[130:133], v[178:181], v[30:33]
	v_mfma_f32_16x16x32_bf16 v[26:29], v[138:141], v[178:181], v[26:29]
	v_mfma_f32_16x16x32_bf16 v[14:17], v[130:133], v[186:189], v[14:17]
	v_mfma_f32_16x16x32_bf16 v[10:13], v[138:141], v[186:189], v[10:13]
	v_mfma_f32_16x16x32_bf16 v[62:65], v[134:137], v[166:169], v[62:65]
	v_mfma_f32_16x16x32_bf16 v[58:61], v[142:145], v[166:169], v[58:61]
	v_mfma_f32_16x16x32_bf16 v[46:49], v[134:137], v[174:177], v[46:49]
	v_mfma_f32_16x16x32_bf16 v[42:45], v[142:145], v[174:177], v[42:45]
	v_mfma_f32_16x16x32_bf16 v[30:33], v[134:137], v[182:185], v[30:33]
	v_mfma_f32_16x16x32_bf16 v[26:29], v[142:145], v[182:185], v[26:29]
	v_mfma_f32_16x16x32_bf16 v[14:17], v[134:137], v[190:193], v[14:17]
	v_mfma_f32_16x16x32_bf16 v[10:13], v[142:145], v[190:193], v[10:13]
	s_setprio 0
	s_setprio 1
	v_mfma_f32_16x16x32_bf16 v[54:57], v[146:149], v[162:165], v[54:57]
	v_mfma_f32_16x16x32_bf16 v[50:53], v[154:157], v[162:165], v[50:53]
	v_mfma_f32_16x16x32_bf16 v[38:41], v[146:149], v[170:173], v[38:41]
	v_mfma_f32_16x16x32_bf16 v[34:37], v[154:157], v[170:173], v[34:37]
	v_mfma_f32_16x16x32_bf16 v[22:25], v[146:149], v[178:181], v[22:25]
	v_mfma_f32_16x16x32_bf16 v[18:21], v[154:157], v[178:181], v[18:21]
	v_mfma_f32_16x16x32_bf16 v[6:9], v[146:149], v[186:189], v[6:9]
	v_mfma_f32_16x16x32_bf16 v[2:5], v[154:157], v[186:189], v[2:5]
	v_mfma_f32_16x16x32_bf16 v[54:57], v[150:153], v[166:169], v[54:57]
	v_mfma_f32_16x16x32_bf16 v[50:53], v[158:161], v[166:169], v[50:53]
	v_mfma_f32_16x16x32_bf16 v[38:41], v[150:153], v[174:177], v[38:41]
	v_mfma_f32_16x16x32_bf16 v[34:37], v[158:161], v[174:177], v[34:37]
	v_mfma_f32_16x16x32_bf16 v[22:25], v[150:153], v[182:185], v[22:25]
	v_mfma_f32_16x16x32_bf16 v[18:21], v[158:161], v[182:185], v[18:21]
	v_mfma_f32_16x16x32_bf16 v[6:9], v[150:153], v[190:193], v[6:9]
	v_mfma_f32_16x16x32_bf16 v[2:5], v[158:161], v[190:193], v[2:5]
	s_setprio 0
	s_barrier
	s_add_u32 s60, s60, 0x80000
	s_addc_u32 s61, s61, 0
	s_mov_b32 m0, s83
	v_lshl_add_u64 v[214:215], s[60:61], 0, v[194:195]
	global_load_lds_dwordx4 v[214:215], off
	v_lshl_add_u64 v[214:215], s[60:61], 0, v[198:199]
	s_mov_b32 m0, s84
	s_nop 0
	global_load_lds_dwordx4 v[214:215], off
	v_add_u32_e32 v0, 0x18400, v250
	ds_read_b128 v[130:133], v0
	ds_read_b128 v[134:137], v0 offset:1024
	ds_read_b128 v[138:141], v0 offset:2048
	ds_read_b128 v[142:145], v0 offset:3072
	v_add_u32_e32 v0, 0x1c400, v250
	ds_read_b128 v[146:149], v0
	ds_read_b128 v[150:153], v0 offset:1024
	ds_read_b128 v[154:157], v0 offset:2048
	ds_read_b128 v[158:161], v0 offset:3072
	ds_read_b128 v[162:165], v253 offset:33792
	ds_read_b128 v[166:169], v253 offset:34816
	ds_read_b128 v[170:173], v253 offset:35840
	ds_read_b128 v[174:177], v253 offset:36864
	ds_read_b128 v[178:181], v253 offset:37888
	ds_read_b128 v[182:185], v253 offset:38912
	ds_read_b128 v[186:189], v253 offset:39936
	ds_read_b128 v[190:193], v253 offset:40960
	s_setprio 1
	s_waitcnt vmcnt(8) lgkmcnt(0)
	s_barrier
	v_mfma_f32_16x16x32_bf16 v[126:129], v[130:133], v[162:165], v[126:129]
	v_mfma_f32_16x16x32_bf16 v[122:125], v[138:141], v[162:165], v[122:125]
	v_mfma_f32_16x16x32_bf16 v[110:113], v[130:133], v[170:173], v[110:113]
	v_mfma_f32_16x16x32_bf16 v[106:109], v[138:141], v[170:173], v[106:109]
	v_mfma_f32_16x16x32_bf16 v[94:97], v[130:133], v[178:181], v[94:97]
	v_mfma_f32_16x16x32_bf16 v[90:93], v[138:141], v[178:181], v[90:93]
	v_mfma_f32_16x16x32_bf16 v[78:81], v[130:133], v[186:189], v[78:81]
	v_mfma_f32_16x16x32_bf16 v[74:77], v[138:141], v[186:189], v[74:77]
	v_mfma_f32_16x16x32_bf16 v[126:129], v[134:137], v[166:169], v[126:129]
	v_mfma_f32_16x16x32_bf16 v[122:125], v[142:145], v[166:169], v[122:125]
	v_mfma_f32_16x16x32_bf16 v[110:113], v[134:137], v[174:177], v[110:113]
	v_mfma_f32_16x16x32_bf16 v[106:109], v[142:145], v[174:177], v[106:109]
	v_mfma_f32_16x16x32_bf16 v[94:97], v[134:137], v[182:185], v[94:97]
	v_mfma_f32_16x16x32_bf16 v[90:93], v[142:145], v[182:185], v[90:93]
	v_mfma_f32_16x16x32_bf16 v[78:81], v[134:137], v[190:193], v[78:81]
	v_mfma_f32_16x16x32_bf16 v[74:77], v[142:145], v[190:193], v[74:77]
	s_setprio 0
	s_setprio 1
	v_mfma_f32_16x16x32_bf16 v[118:121], v[146:149], v[162:165], v[118:121]
	v_mfma_f32_16x16x32_bf16 v[114:117], v[154:157], v[162:165], v[114:117]
	v_mfma_f32_16x16x32_bf16 v[102:105], v[146:149], v[170:173], v[102:105]
	v_mfma_f32_16x16x32_bf16 v[98:101], v[154:157], v[170:173], v[98:101]
	v_mfma_f32_16x16x32_bf16 v[86:89], v[146:149], v[178:181], v[86:89]
	v_mfma_f32_16x16x32_bf16 v[82:85], v[154:157], v[178:181], v[82:85]
	v_mfma_f32_16x16x32_bf16 v[70:73], v[146:149], v[186:189], v[70:73]
	v_mfma_f32_16x16x32_bf16 v[66:69], v[154:157], v[186:189], v[66:69]
	v_mfma_f32_16x16x32_bf16 v[118:121], v[150:153], v[166:169], v[118:121]
	v_mfma_f32_16x16x32_bf16 v[114:117], v[158:161], v[166:169], v[114:117]
	v_mfma_f32_16x16x32_bf16 v[102:105], v[150:153], v[174:177], v[102:105]
	v_mfma_f32_16x16x32_bf16 v[98:101], v[158:161], v[174:177], v[98:101]
	v_mfma_f32_16x16x32_bf16 v[86:89], v[150:153], v[182:185], v[86:89]
	v_mfma_f32_16x16x32_bf16 v[82:85], v[158:161], v[182:185], v[82:85]
	v_mfma_f32_16x16x32_bf16 v[70:73], v[150:153], v[190:193], v[70:73]
	v_mfma_f32_16x16x32_bf16 v[66:69], v[158:161], v[190:193], v[66:69]
	s_setprio 0
	s_barrier
; #define PG8_STAGE(bufoff, gbase, voff) do { _Pragma("unroll") for (int _i = 0; _i < 2; ++_i) \
;         __builtin_amdgcn_global_load_lds((const GAS unsigned*)((const GAS char*)(gbase) + (voff)[_i]), (LAS unsigned*)(lds + (bufoff) + ldsw + _i * 8192), 16, 0, 0); } while (0)
; #define PG8_LDA(dst, b, h) do { _Pragma("unroll") for (int m = 0; m < 4; ++m) _Pragma("unroll") for (int k = 0; k < 2; ++k) dst[m][k] = *(const LAS bf16x8*)(lds + PG8_SA(b, h) + aoff + m * 2048 + k * 1024); } while (0)
; #define PG8_MMA(ai, bj, At, Bt) do { __builtin_amdgcn_s_setprio(1); _Pragma("unroll") for (int m = 0; m < 4; ++m) _Pragma("unroll") for (int n = 0; n < 2; ++n) _Pragma("unroll") for (int k = 0; k < 2; ++k) \
;         acc[ai][bj][m][n] = __builtin_amdgcn_mfma_f32_16x16x32_bf16(Bt[n][k], At[m][k], acc[ai][bj][m][n], 0, 0, 0); __builtin_amdgcn_s_setprio(0); } while (0)
; #define PG8_WAIT_V(n) asm volatile("s_waitcnt vmcnt(" #n ")" ::: "memory")
; #define PG8_WAIT_L(n) asm volatile("s_waitcnt lgkmcnt(" #n ")" ::: "memory")
; #define PG8_BAR __builtin_amdgcn_s_barrier()
; #define PG8_SCHED __builtin_amdgcn_sched_barrier(0)
; template <class Epi, class Sched, bool ALIGN_EPI>
; __device__ __forceinline__ void gemm_phase(LAS unsigned char* lds, const Gemm g, const Sched& S, const Epi& E, int wave_id) {
;     ...
;             PG8_LDA(At, 1, 1); PG8_STAGE(PG8_SB(1, 0), b3, voffB); PG8_STAGE(PG8_SB(1, 1), b3 + hsB, voffB); PG8_STAGE(PG8_SA(1, 0), a3, voffA);
;             PG8_WAIT_V(8); PG8_WAIT_L(0); PG8_BAR; PG8_MMA(1, 0, At, B0); PG8_MMA(1, 1, At, B1); PG8_BAR; PG8_SCHED;
;         }
;         if constexpr (ALIGN_EPI) { if (wr == 0) PG8_BAR; }
	s_mov_b32 m0, s95
	v_lshl_add_u64 v[206:207], v[206:207], 0, s[92:93]
	s_add_u32 s58, s58, 0x80080
	global_load_lds_dwordx4 v[206:207], off
	v_lshl_add_u64 v[206:207], v[208:209], 0, s[92:93]
	s_mov_b32 m0, s96
	s_addc_u32 s59, s59, 0
	global_load_lds_dwordx4 v[206:207], off
	v_lshl_add_u64 v[206:207], s[58:59], 0, v[196:197]
	s_mov_b32 m0, s17
	s_nop 0
	global_load_lds_dwordx4 v[206:207], off
	v_lshl_add_u64 v[206:207], s[58:59], 0, v[200:201]
	s_mov_b32 m0, s18
	s_nop 0
	global_load_lds_dwordx4 v[206:207], off
	v_lshl_add_u64 v[206:207], v[210:211], 0, s[92:93]
	s_mov_b32 m0, s97
	s_nop 0
	global_load_lds_dwordx4 v[206:207], off
	v_lshl_add_u64 v[206:207], v[212:213], 0, s[92:93]
	s_mov_b32 m0, s16
	s_nop 0
	global_load_lds_dwordx4 v[206:207], off
	ds_read_b128 v[162:165], v253 offset:50176
	ds_read_b128 v[166:169], v253 offset:51200
	ds_read_b128 v[170:173], v253 offset:52224
	ds_read_b128 v[174:177], v253 offset:53248
	ds_read_b128 v[178:181], v253 offset:54272
	ds_read_b128 v[182:185], v253 offset:55296
	ds_read_b128 v[186:189], v253 offset:56320
	ds_read_b128 v[190:193], v253 offset:57344
	s_setprio 1
	s_waitcnt vmcnt(8) lgkmcnt(0)
	s_barrier
	v_mfma_f32_16x16x32_bf16 v[62:65], v[130:133], v[162:165], v[62:65]
	v_mfma_f32_16x16x32_bf16 v[58:61], v[138:141], v[162:165], v[58:61]
	v_mfma_f32_16x16x32_bf16 v[46:49], v[130:133], v[170:173], v[46:49]
	v_mfma_f32_16x16x32_bf16 v[42:45], v[138:141], v[170:173], v[42:45]
	v_mfma_f32_16x16x32_bf16 v[30:33], v[130:133], v[178:181], v[30:33]
	v_mfma_f32_16x16x32_bf16 v[26:29], v[138:141], v[178:181], v[26:29]
	v_mfma_f32_16x16x32_bf16 v[14:17], v[130:133], v[186:189], v[14:17]
	v_mfma_f32_16x16x32_bf16 v[10:13], v[138:141], v[186:189], v[10:13]
	v_mfma_f32_16x16x32_bf16 v[62:65], v[134:137], v[166:169], v[62:65]
	v_mfma_f32_16x16x32_bf16 v[58:61], v[142:145], v[166:169], v[58:61]
	v_mfma_f32_16x16x32_bf16 v[46:49], v[134:137], v[174:177], v[46:49]
	v_mfma_f32_16x16x32_bf16 v[42:45], v[142:145], v[174:177], v[42:45]
	v_mfma_f32_16x16x32_bf16 v[30:33], v[134:137], v[182:185], v[30:33]
	v_mfma_f32_16x16x32_bf16 v[26:29], v[142:145], v[182:185], v[26:29]
	v_mfma_f32_16x16x32_bf16 v[14:17], v[134:137], v[190:193], v[14:17]
	v_mfma_f32_16x16x32_bf16 v[10:13], v[142:145], v[190:193], v[10:13]
	s_setprio 0
	s_setprio 1
	v_mfma_f32_16x16x32_bf16 v[54:57], v[146:149], v[162:165], v[54:57]
	v_mfma_f32_16x16x32_bf16 v[50:53], v[154:157], v[162:165], v[50:53]
	v_mfma_f32_16x16x32_bf16 v[38:41], v[146:149], v[170:173], v[38:41]
	v_mfma_f32_16x16x32_bf16 v[34:37], v[154:157], v[170:173], v[34:37]
	v_mfma_f32_16x16x32_bf16 v[22:25], v[146:149], v[178:181], v[22:25]
	v_mfma_f32_16x16x32_bf16 v[18:21], v[154:157], v[178:181], v[18:21]
	v_mfma_f32_16x16x32_bf16 v[6:9], v[146:149], v[186:189], v[6:9]
	v_mfma_f32_16x16x32_bf16 v[2:5], v[154:157], v[186:189], v[2:5]
	v_mfma_f32_16x16x32_bf16 v[54:57], v[150:153], v[166:169], v[54:57]
	v_mfma_f32_16x16x32_bf16 v[50:53], v[158:161], v[166:169], v[50:53]
	v_mfma_f32_16x16x32_bf16 v[38:41], v[150:153], v[174:177], v[38:41]
	v_mfma_f32_16x16x32_bf16 v[34:37], v[158:161], v[174:177], v[34:37]
	v_mfma_f32_16x16x32_bf16 v[22:25], v[150:153], v[182:185], v[22:25]
	v_mfma_f32_16x16x32_bf16 v[18:21], v[158:161], v[182:185], v[18:21]
	v_mfma_f32_16x16x32_bf16 v[6:9], v[150:153], v[190:193], v[6:9]
	v_mfma_f32_16x16x32_bf16 v[2:5], v[158:161], v[190:193], v[2:5]
	s_setprio 0
	s_barrier
	s_add_i32 s76, s76, 2
	s_add_u32 s71, s71, 0x100
	s_addc_u32 s74, s74, 0
	s_add_u32 s0, s0, 0x100
	s_addc_u32 s1, s1, 0
	s_cmp_gt_u32 s76, 29
	s_cbranch_scc0 .LBB0_1117
	s_and_b64 vcc, exec, s[44:45]
	s_cbranch_vccz .LBB0_1120
	s_barrier

; #define GAS __attribute__((address_space(1)))
; #define PG8_STAGE(bufoff, gbase, voff) do { _Pragma("unroll") for (int _i = 0; _i < 2; ++_i) \
;         __builtin_amdgcn_global_load_lds((const GAS unsigned*)((const GAS char*)(gbase) + (voff)[_i]), (LAS unsigned*)(lds + (bufoff) + ldsw + _i * 8192), 16, 0, 0); } while (0)
; #define PG8_LDA(dst, b, h) do { _Pragma("unroll") for (int m = 0; m < 4; ++m) _Pragma("unroll") for (int k = 0; k < 2; ++k) dst[m][k] = *(const LAS bf16x8*)(lds + PG8_SA(b, h) + aoff + m * 2048 + k * 1024); } while (0)
; #define PG8_LDB(dst, b, h) do { _Pragma("unroll") for (int n = 0; n < 2; ++n) _Pragma("unroll") for (int k = 0; k < 2; ++k) dst[n][k] = *(const LAS bf16x8*)(lds + PG8_SB(b, h) + boff + n * 2048 + k * 1024); } while (0)
; #define PG8_MMA(ai, bj, At, Bt) do { __builtin_amdgcn_s_setprio(1); _Pragma("unroll") for (int m = 0; m < 4; ++m) _Pragma("unroll") for (int n = 0; n < 2; ++n) _Pragma("unroll") for (int k = 0; k < 2; ++k) \
;         acc[ai][bj][m][n] = __builtin_amdgcn_mfma_f32_16x16x32_bf16(Bt[n][k], At[m][k], acc[ai][bj][m][n], 0, 0, 0); __builtin_amdgcn_s_setprio(0); } while (0)
; #define PG8_WAIT_V(n) asm volatile("s_waitcnt vmcnt(" #n ")" ::: "memory")
; #define PG8_WAIT_L(n) asm volatile("s_waitcnt lgkmcnt(" #n ")" ::: "memory")
; #define PG8_BAR __builtin_amdgcn_s_barrier()
; template <class Epi, class Sched, bool ALIGN_EPI>
; __device__ __forceinline__ void gemm_phase(LAS unsigned char* lds, const Gemm g, const Sched& S, const Epi& E, int wave_id) {
;     ...
;             const bool last = (t == nt - 2);
;             const GAS char* a1 = cA + (size_t)(t + 1) * kstep;
;             const GAS char* a2 = last ? nA : cA + (size_t)(t + 2) * kstep; const GAS char* b2 = last ? nB : cB + (size_t)(t + 2) * kstep;
;             const GAS char* a3 = a2 + kstep; const GAS char* b3 = b2 + kstep;
;             PG8_LDB(B0, 0, 0); PG8_LDB(B1, 0, 1); PG8_SCHED; PG8_LDA(At, 0, 0); PG8_STAGE(PG8_SA(1, 1), a1 + hsA, voffA);
;             PG8_WAIT_V(8); PG8_WAIT_L(0); PG8_BAR; PG8_MMA(0, 0, At, B0); PG8_MMA(0, 1, At, B1); PG8_BAR; PG8_SCHED;
;             PG8_LDA(At, 0, 1); PG8_STAGE(PG8_SB(0, 0), b2, voffB); PG8_STAGE(PG8_SB(0, 1), b2 + hsB, voffB); PG8_STAGE(PG8_SA(0, 0), a2, voffA);
;             PG8_WAIT_V(8); PG8_WAIT_L(0); PG8_BAR; PG8_MMA(1, 0, At, B0); PG8_MMA(1, 1, At, B1); PG8_BAR; PG8_SCHED;
.LBB0_1335:
	s_add_u32 s34, s12, s26
	s_addc_u32 s35, s13, s27
	s_add_u32 s30, s34, 0x100
	s_addc_u32 s31, s35, 0
	s_and_b64 s[28:29], s[24:25], exec
	s_cselect_b32 s29, s17, s31
	s_cselect_b32 s28, s16, s30
	s_add_u32 s26, s10, s26
	s_addc_u32 s27, s11, s27
	s_add_u32 s26, s26, 0x100
	s_addc_u32 s27, s27, 0
	s_and_b64 s[24:25], s[24:25], exec
	s_cselect_b32 s31, s60, s27
	s_cselect_b32 s30, s61, s26
	s_add_u32 s36, s34, 0x18080
	s_addc_u32 s37, s35, 0
	s_add_i32 m0, s40, 0xc400
	s_add_i32 s62, s40, 0xe400
	s_add_u32 s34, s30, 0x10000
	s_addc_u32 s35, s31, 0
	s_add_u32 s26, s28, 0x18000
	s_addc_u32 s27, s29, 0
	s_add_u32 s24, s30, 0x10080
	s_addc_u32 s25, s31, 0
	v_lshl_add_u64 v[122:123], s[36:37], 0, v[70:71]
	global_load_lds_dwordx4 v[122:123], off
	v_lshl_add_u64 v[122:123], s[36:37], 0, v[68:69]
	s_mov_b32 m0, s62
	s_nop 0
	global_load_lds_dwordx4 v[122:123], off
	v_add_u32_e32 v86, 0x10400, v73
	ds_read_b128 v[74:77], v86
	ds_read_b128 v[78:81], v86 offset:1024
	ds_read_b128 v[82:85], v86 offset:2048
	ds_read_b128 v[86:89], v86 offset:3072
	ds_read_b128 v[90:93], v72 offset:1024
	ds_read_b128 v[94:97], v72 offset:2048
	ds_read_b128 v[98:101], v72 offset:3072
	ds_read_b128 v[102:105], v72 offset:4096
	ds_read_b128 v[106:109], v72 offset:5120
	ds_read_b128 v[110:113], v72 offset:6144
	ds_read_b128 v[114:117], v72 offset:7168
	ds_read_b128 v[118:121], v72 offset:8192
	s_setprio 1
	s_waitcnt vmcnt(8) lgkmcnt(0)
	s_barrier
	v_mfma_f32_16x16x32_bf16 v[62:65], v[74:77], v[90:93], v[62:65]
	v_mfma_f32_16x16x32_bf16 v[58:61], v[82:85], v[90:93], v[58:61]
	v_mfma_f32_16x16x32_bf16 v[54:57], v[74:77], v[98:101], v[54:57]
	v_mfma_f32_16x16x32_bf16 v[50:53], v[82:85], v[98:101], v[50:53]
	v_mfma_f32_16x16x32_bf16 v[46:49], v[74:77], v[106:109], v[46:49]
	v_mfma_f32_16x16x32_bf16 v[42:45], v[82:85], v[106:109], v[42:45]
	v_mfma_f32_16x16x32_bf16 v[38:41], v[74:77], v[114:117], v[38:41]
	v_mfma_f32_16x16x32_bf16 v[34:37], v[82:85], v[114:117], v[34:37]
	v_mfma_f32_16x16x32_bf16 v[62:65], v[78:81], v[94:97], v[62:65]
	v_mfma_f32_16x16x32_bf16 v[58:61], v[86:89], v[94:97], v[58:61]
	v_mfma_f32_16x16x32_bf16 v[54:57], v[78:81], v[102:105], v[54:57]
	v_mfma_f32_16x16x32_bf16 v[50:53], v[86:89], v[102:105], v[50:53]
	v_mfma_f32_16x16x32_bf16 v[46:49], v[78:81], v[110:113], v[46:49]
	v_mfma_f32_16x16x32_bf16 v[42:45], v[86:89], v[110:113], v[42:45]
	v_mfma_f32_16x16x32_bf16 v[38:41], v[78:81], v[118:121], v[38:41]
	v_mfma_f32_16x16x32_bf16 v[34:37], v[86:89], v[118:121], v[34:37]
	s_setprio 0
	s_setprio 1
	s_setprio 0
	s_barrier
	s_mov_b32 m0, s41
	v_lshl_add_u64 v[122:123], s[30:31], 0, v[0:1]
	global_load_lds_dwordx4 v[122:123], off
	v_lshl_add_u64 v[124:125], s[30:31], 0, v[66:67]
	s_mov_b32 m0, s42
	v_lshl_add_u64 v[126:127], s[34:35], 0, v[0:1]
	global_load_lds_dwordx4 v[124:125], off
	s_mov_b32 m0, s43
	v_lshl_add_u64 v[128:129], s[28:29], 0, v[68:69]
	global_load_lds_dwordx4 v[126:127], off
	v_lshl_add_u64 v[126:127], s[34:35], 0, v[66:67]
	s_mov_b32 m0, s44
	s_nop 0
	global_load_lds_dwordx4 v[126:127], off
	v_lshl_add_u64 v[126:127], s[28:29], 0, v[70:71]
	s_mov_b32 m0, s45
	s_nop 0
	global_load_lds_dwordx4 v[126:127], off
	s_mov_b32 m0, s46
	s_nop 0
	global_load_lds_dwordx4 v[128:129], off
	ds_read_b128 v[90:93], v72 offset:17408
	ds_read_b128 v[94:97], v72 offset:18432
	ds_read_b128 v[98:101], v72 offset:19456
	ds_read_b128 v[102:105], v72 offset:20480
	ds_read_b128 v[106:109], v72 offset:21504
	ds_read_b128 v[110:113], v72 offset:22528
	ds_read_b128 v[114:117], v72 offset:23552
	ds_read_b128 v[118:121], v72 offset:24576
	s_setprio 1
	s_waitcnt vmcnt(8) lgkmcnt(0)
	s_barrier
	v_mfma_f32_16x16x32_bf16 v[30:33], v[74:77], v[90:93], v[30:33]
	v_mfma_f32_16x16x32_bf16 v[26:29], v[82:85], v[90:93], v[26:29]
	v_mfma_f32_16x16x32_bf16 v[22:25], v[74:77], v[98:101], v[22:25]
	v_mfma_f32_16x16x32_bf16 v[18:21], v[82:85], v[98:101], v[18:21]
	v_mfma_f32_16x16x32_bf16 v[14:17], v[74:77], v[106:109], v[14:17]
	v_mfma_f32_16x16x32_bf16 v[10:13], v[82:85], v[106:109], v[10:13]
	v_mfma_f32_16x16x32_bf16 v[6:9], v[74:77], v[114:117], v[6:9]
	v_mfma_f32_16x16x32_bf16 v[2:5], v[82:85], v[114:117], v[2:5]
	v_mfma_f32_16x16x32_bf16 v[30:33], v[78:81], v[94:97], v[30:33]
	v_mfma_f32_16x16x32_bf16 v[26:29], v[86:89], v[94:97], v[26:29]
	v_mfma_f32_16x16x32_bf16 v[22:25], v[78:81], v[102:105], v[22:25]
	v_mfma_f32_16x16x32_bf16 v[18:21], v[86:89], v[102:105], v[18:21]
	v_mfma_f32_16x16x32_bf16 v[14:17], v[78:81], v[110:113], v[14:17]
	v_mfma_f32_16x16x32_bf16 v[10:13], v[86:89], v[110:113], v[10:13]
	v_mfma_f32_16x16x32_bf16 v[6:9], v[78:81], v[118:121], v[6:9]
	v_mfma_f32_16x16x32_bf16 v[2:5], v[86:89], v[118:121], v[2:5]
	s_setprio 0
	s_setprio 1
	s_setprio 0
	s_barrier
; #define PG8_STAGE(bufoff, gbase, voff) do { _Pragma("unroll") for (int _i = 0; _i < 2; ++_i) \
;         __builtin_amdgcn_global_load_lds((const GAS unsigned*)((const GAS char*)(gbase) + (voff)[_i]), (LAS unsigned*)(lds + (bufoff) + ldsw + _i * 8192), 16, 0, 0); } while (0)
; #define PG8_LDA(dst, b, h) do { _Pragma("unroll") for (int m = 0; m < 4; ++m) _Pragma("unroll") for (int k = 0; k < 2; ++k) dst[m][k] = *(const LAS bf16x8*)(lds + PG8_SA(b, h) + aoff + m * 2048 + k * 1024); } while (0)
; #define PG8_LDB(dst, b, h) do { _Pragma("unroll") for (int n = 0; n < 2; ++n) _Pragma("unroll") for (int k = 0; k < 2; ++k) dst[n][k] = *(const LAS bf16x8*)(lds + PG8_SB(b, h) + boff + n * 2048 + k * 1024); } while (0)
; #define PG8_MMA(ai, bj, At, Bt) do { __builtin_amdgcn_s_setprio(1); _Pragma("unroll") for (int m = 0; m < 4; ++m) _Pragma("unroll") for (int n = 0; n < 2; ++n) _Pragma("unroll") for (int k = 0; k < 2; ++k) \
;         acc[ai][bj][m][n] = __builtin_amdgcn_mfma_f32_16x16x32_bf16(Bt[n][k], At[m][k], acc[ai][bj][m][n], 0, 0, 0); __builtin_amdgcn_s_setprio(0); } while (0)
; #define PG8_WAIT_V(n) asm volatile("s_waitcnt vmcnt(" #n ")" ::: "memory")
; #define PG8_WAIT_L(n) asm volatile("s_waitcnt lgkmcnt(" #n ")" ::: "memory")
; #define PG8_BAR __builtin_amdgcn_s_barrier()
; #define PG8_SCHED __builtin_amdgcn_sched_barrier(0)
; template <class Epi, class Sched, bool ALIGN_EPI>
; __device__ __forceinline__ void gemm_phase(LAS unsigned char* lds, const Gemm g, const Sched& S, const Epi& E, int wave_id) {
;     ...
;             PG8_LDB(B0, 1, 0); PG8_LDB(B1, 1, 1); PG8_SCHED; PG8_LDA(At, 1, 0); PG8_STAGE(PG8_SA(0, 1), a2 + hsA, voffA);
;             PG8_WAIT_V(8); PG8_WAIT_L(0); PG8_BAR; PG8_MMA(0, 0, At, B0); PG8_MMA(0, 1, At, B1); PG8_BAR; PG8_SCHED;
;             PG8_LDA(At, 1, 1); PG8_STAGE(PG8_SB(1, 0), b3, voffB); PG8_STAGE(PG8_SB(1, 1), b3 + hsB, voffB); PG8_STAGE(PG8_SA(1, 0), a3, voffA);
;             PG8_WAIT_V(8); PG8_WAIT_L(0); PG8_BAR; PG8_MMA(1, 0, At, B0); PG8_MMA(1, 1, At, B1); PG8_BAR; PG8_SCHED;
;         }
;         if constexpr (ALIGN_EPI) { if (wr == 0) PG8_BAR; }
	s_mov_b32 m0, s47
	v_lshl_add_u64 v[130:131], s[26:27], 0, v[70:71]
	global_load_lds_dwordx4 v[130:131], off
	v_lshl_add_u64 v[130:131], s[26:27], 0, v[68:69]
	s_mov_b32 m0, s48
	s_nop 0
	global_load_lds_dwordx4 v[130:131], off
	v_add_u32_e32 v86, 0x18400, v73
	ds_read_b128 v[74:77], v86
	ds_read_b128 v[78:81], v86 offset:1024
	ds_read_b128 v[82:85], v86 offset:2048
	ds_read_b128 v[86:89], v86 offset:3072
	ds_read_b128 v[90:93], v72 offset:33792
	ds_read_b128 v[94:97], v72 offset:34816
	ds_read_b128 v[98:101], v72 offset:35840
	ds_read_b128 v[102:105], v72 offset:36864
	ds_read_b128 v[106:109], v72 offset:37888
	ds_read_b128 v[110:113], v72 offset:38912
	ds_read_b128 v[114:117], v72 offset:39936
	ds_read_b128 v[118:121], v72 offset:40960
	s_setprio 1
	s_waitcnt vmcnt(8) lgkmcnt(0)
	s_barrier
	v_mfma_f32_16x16x32_bf16 v[62:65], v[74:77], v[90:93], v[62:65]
	v_mfma_f32_16x16x32_bf16 v[58:61], v[82:85], v[90:93], v[58:61]
	v_mfma_f32_16x16x32_bf16 v[54:57], v[74:77], v[98:101], v[54:57]
	v_mfma_f32_16x16x32_bf16 v[50:53], v[82:85], v[98:101], v[50:53]
	v_mfma_f32_16x16x32_bf16 v[46:49], v[74:77], v[106:109], v[46:49]
	v_mfma_f32_16x16x32_bf16 v[42:45], v[82:85], v[106:109], v[42:45]
	v_mfma_f32_16x16x32_bf16 v[38:41], v[74:77], v[114:117], v[38:41]
	v_mfma_f32_16x16x32_bf16 v[34:37], v[82:85], v[114:117], v[34:37]
	v_mfma_f32_16x16x32_bf16 v[62:65], v[78:81], v[94:97], v[62:65]
	v_mfma_f32_16x16x32_bf16 v[58:61], v[86:89], v[94:97], v[58:61]
	v_mfma_f32_16x16x32_bf16 v[54:57], v[78:81], v[102:105], v[54:57]
	v_mfma_f32_16x16x32_bf16 v[50:53], v[86:89], v[102:105], v[50:53]
	v_mfma_f32_16x16x32_bf16 v[46:49], v[78:81], v[110:113], v[46:49]
	v_mfma_f32_16x16x32_bf16 v[42:45], v[86:89], v[110:113], v[42:45]
	v_mfma_f32_16x16x32_bf16 v[38:41], v[78:81], v[118:121], v[38:41]
	v_mfma_f32_16x16x32_bf16 v[34:37], v[86:89], v[118:121], v[34:37]
	s_setprio 0
	s_setprio 1
	s_setprio 0
	s_barrier
	s_mov_b32 m0, s51
	v_lshl_add_u64 v[122:123], v[122:123], 0, s[92:93]
	global_load_lds_dwordx4 v[122:123], off
	v_lshl_add_u64 v[122:123], v[124:125], 0, s[92:93]
	s_mov_b32 m0, s52
	s_nop 0
	global_load_lds_dwordx4 v[122:123], off
	v_lshl_add_u64 v[122:123], s[24:25], 0, v[0:1]
	s_mov_b32 m0, s55
	s_nop 0
	global_load_lds_dwordx4 v[122:123], off
	v_lshl_add_u64 v[122:123], s[24:25], 0, v[66:67]
	s_mov_b32 m0, s56
	s_nop 0
	global_load_lds_dwordx4 v[122:123], off
	v_lshl_add_u64 v[122:123], v[126:127], 0, s[92:93]
	s_mov_b32 m0, s53
	s_nop 0
	global_load_lds_dwordx4 v[122:123], off
	v_lshl_add_u64 v[122:123], v[128:129], 0, s[92:93]
	s_mov_b32 m0, s54
	s_nop 0
	global_load_lds_dwordx4 v[122:123], off
	ds_read_b128 v[90:93], v72 offset:50176
	ds_read_b128 v[94:97], v72 offset:51200
	ds_read_b128 v[98:101], v72 offset:52224
	ds_read_b128 v[102:105], v72 offset:53248
	ds_read_b128 v[106:109], v72 offset:54272
	ds_read_b128 v[110:113], v72 offset:55296
	ds_read_b128 v[114:117], v72 offset:56320
	ds_read_b128 v[118:121], v72 offset:57344
	s_setprio 1
	s_waitcnt vmcnt(8) lgkmcnt(0)
	s_barrier
	v_mfma_f32_16x16x32_bf16 v[30:33], v[74:77], v[90:93], v[30:33]
	v_mfma_f32_16x16x32_bf16 v[26:29], v[82:85], v[90:93], v[26:29]
	v_mfma_f32_16x16x32_bf16 v[22:25], v[74:77], v[98:101], v[22:25]
	v_mfma_f32_16x16x32_bf16 v[18:21], v[82:85], v[98:101], v[18:21]
	v_mfma_f32_16x16x32_bf16 v[14:17], v[74:77], v[106:109], v[14:17]
	v_mfma_f32_16x16x32_bf16 v[10:13], v[82:85], v[106:109], v[10:13]
	v_mfma_f32_16x16x32_bf16 v[6:9], v[74:77], v[114:117], v[6:9]
	v_mfma_f32_16x16x32_bf16 v[2:5], v[82:85], v[114:117], v[2:5]
	v_mfma_f32_16x16x32_bf16 v[30:33], v[78:81], v[94:97], v[30:33]
	v_mfma_f32_16x16x32_bf16 v[26:29], v[86:89], v[94:97], v[26:29]
	v_mfma_f32_16x16x32_bf16 v[22:25], v[78:81], v[102:105], v[22:25]
	v_mfma_f32_16x16x32_bf16 v[18:21], v[86:89], v[102:105], v[18:21]
	v_mfma_f32_16x16x32_bf16 v[14:17], v[78:81], v[110:113], v[14:17]
	v_mfma_f32_16x16x32_bf16 v[10:13], v[86:89], v[110:113], v[10:13]
	v_mfma_f32_16x16x32_bf16 v[6:9], v[78:81], v[118:121], v[6:9]
	v_mfma_f32_16x16x32_bf16 v[2:5], v[86:89], v[118:121], v[2:5]
	s_setprio 0
	s_setprio 1
	s_setprio 0
	s_barrier
	s_andn2_b64 vcc, exec, s[22:23]
	s_mov_b64 s[24:25], -1
	s_mov_b64 s[22:23], 0
	s_mov_b64 s[26:27], 0x100
	s_cbranch_vccz .LBB0_1335
	s_and_b64 vcc, exec, s[14:15]
	s_cbranch_vccz .LBB0_1338
	s_barrier

; #define GAS __attribute__((address_space(1)))
; #define PG8_STAGE(bufoff, gbase, voff) do { _Pragma("unroll") for (int _i = 0; _i < 2; ++_i) \
;         __builtin_amdgcn_global_load_lds((const GAS unsigned*)((const GAS char*)(gbase) + (voff)[_i]), (LAS unsigned*)(lds + (bufoff) + ldsw + _i * 8192), 16, 0, 0); } while (0)
; #define PG8_LDA(dst, b, h) do { _Pragma("unroll") for (int m = 0; m < 4; ++m) _Pragma("unroll") for (int k = 0; k < 2; ++k) dst[m][k] = *(const LAS bf16x8*)(lds + PG8_SA(b, h) + aoff + m * 2048 + k * 1024); } while (0)
; #define PG8_LDB(dst, b, h) do { _Pragma("unroll") for (int n = 0; n < 2; ++n) _Pragma("unroll") for (int k = 0; k < 2; ++k) dst[n][k] = *(const LAS bf16x8*)(lds + PG8_SB(b, h) + boff + n * 2048 + k * 1024); } while (0)
; #define PG8_MMA(ai, bj, At, Bt) do { __builtin_amdgcn_s_setprio(1); _Pragma("unroll") for (int m = 0; m < 4; ++m) _Pragma("unroll") for (int n = 0; n < 2; ++n) _Pragma("unroll") for (int k = 0; k < 2; ++k) \
;         acc[ai][bj][m][n] = __builtin_amdgcn_mfma_f32_16x16x32_bf16(Bt[n][k], At[m][k], acc[ai][bj][m][n], 0, 0, 0); __builtin_amdgcn_s_setprio(0); } while (0)
; #define PG8_WAIT_V(n) asm volatile("s_waitcnt vmcnt(" #n ")" ::: "memory")
; #define PG8_WAIT_L(n) asm volatile("s_waitcnt lgkmcnt(" #n ")" ::: "memory")
; #define PG8_BAR __builtin_amdgcn_s_barrier()
; template <class Epi, class Sched, bool ALIGN_EPI>
; __device__ __forceinline__ void gemm_phase(LAS unsigned char* lds, const Gemm g, const Sched& S, const Epi& E, int wave_id) {
;     ...
;             const bool last = (t == nt - 2);
;             const GAS char* a1 = cA + (size_t)(t + 1) * kstep;
;             const GAS char* a2 = last ? nA : cA + (size_t)(t + 2) * kstep; const GAS char* b2 = last ? nB : cB + (size_t)(t + 2) * kstep;
;             const GAS char* a3 = a2 + kstep; const GAS char* b3 = b2 + kstep;
;             PG8_LDB(B0, 0, 0); PG8_LDB(B1, 0, 1); PG8_SCHED; PG8_LDA(At, 0, 0); PG8_STAGE(PG8_SA(1, 1), a1 + hsA, voffA);
;             PG8_WAIT_V(8); PG8_WAIT_L(0); PG8_BAR; PG8_MMA(0, 0, At, B0); PG8_MMA(0, 1, At, B1); PG8_BAR; PG8_SCHED;
;             PG8_LDA(At, 0, 1); PG8_STAGE(PG8_SB(0, 0), b2, voffB); PG8_STAGE(PG8_SB(0, 1), b2 + hsB, voffB); PG8_STAGE(PG8_SA(0, 0), a2, voffA);
;             PG8_WAIT_V(8); PG8_WAIT_L(0); PG8_BAR; PG8_MMA(1, 0, At, B0); PG8_MMA(1, 1, At, B1); PG8_BAR; PG8_SCHED;
.LBB0_1458:
	s_add_u32 s21, s26, s34
	s_addc_u32 s33, s27, s35
	s_add_u32 s38, s21, 0x100
	s_addc_u32 s39, s33, 0
	s_and_b64 s[36:37], s[30:31], exec
	s_cselect_b32 s37, s3, s39
	s_cselect_b32 s36, s5, s38
	s_add_u32 s34, s6, s34
	s_addc_u32 s35, s7, s35
	s_add_u32 s34, s34, 0x100
	s_addc_u32 s35, s35, 0
	s_and_b64 s[30:31], s[30:31], exec
	s_cselect_b32 s39, s9, s35
	s_cselect_b32 s38, s19, s34
	s_add_u32 s42, s21, 0x10080
	s_addc_u32 s43, s33, 0
	s_add_i32 m0, s49, 0xc400
	s_add_i32 s21, s49, 0xe400
	s_add_u32 s40, s38, 0x10000
	s_addc_u32 s41, s39, 0
	s_add_u32 s34, s36, 0x10000
	s_addc_u32 s35, s37, 0
	s_add_u32 s30, s38, 0x10080
	s_addc_u32 s31, s39, 0
	v_lshl_add_u64 v[2:3], s[42:43], 0, v[140:141]
	global_load_lds_dwordx4 v[2:3], off
	v_lshl_add_u64 v[2:3], s[42:43], 0, v[144:145]
	s_mov_b32 m0, s21
	s_nop 0
	global_load_lds_dwordx4 v[2:3], off
	v_add_u32_e32 v0, 0x10400, v159
	ds_read_b128 v[100:103], v0
	ds_read_b128 v[108:111], v0 offset:1024
	ds_read_b128 v[148:151], v0 offset:2048
	ds_read_b128 v[152:155], v0 offset:3072
	v_add_u32_e32 v0, 0x14400, v159
	ds_read_b128 v[160:163], v0
	ds_read_b128 v[164:167], v0 offset:1024
	ds_read_b128 v[168:171], v0 offset:2048
	ds_read_b128 v[172:175], v0 offset:3072
	ds_read_b128 v[176:179], v158 offset:1024
	ds_read_b128 v[180:183], v158 offset:2048
	ds_read_b128 v[184:187], v158 offset:3072
	ds_read_b128 v[188:191], v158 offset:4096
	ds_read_b128 v[192:195], v158 offset:5120
	ds_read_b128 v[196:199], v158 offset:6144
	ds_read_b128 v[200:203], v158 offset:7168
	ds_read_b128 v[204:207], v158 offset:8192
	s_setprio 1
	s_waitcnt vmcnt(8) lgkmcnt(0)
	s_barrier
	v_mfma_f32_16x16x32_bf16 v[136:139], v[100:103], v[176:179], v[136:139]
	v_mfma_f32_16x16x32_bf16 v[132:135], v[148:151], v[176:179], v[132:135]
	v_mfma_f32_16x16x32_bf16 v[128:131], v[100:103], v[184:187], v[128:131]
	v_mfma_f32_16x16x32_bf16 v[124:127], v[148:151], v[184:187], v[124:127]
	v_mfma_f32_16x16x32_bf16 v[120:123], v[100:103], v[192:195], v[120:123]
	v_mfma_f32_16x16x32_bf16 v[116:119], v[148:151], v[192:195], v[116:119]
	v_mfma_f32_16x16x32_bf16 v[112:115], v[100:103], v[200:203], v[112:115]
	v_mfma_f32_16x16x32_bf16 v[104:107], v[148:151], v[200:203], v[104:107]
	v_mfma_f32_16x16x32_bf16 v[136:139], v[108:111], v[180:183], v[136:139]
	v_mfma_f32_16x16x32_bf16 v[132:135], v[152:155], v[180:183], v[132:135]
	v_mfma_f32_16x16x32_bf16 v[128:131], v[108:111], v[188:191], v[128:131]
	v_mfma_f32_16x16x32_bf16 v[124:127], v[152:155], v[188:191], v[124:127]
	v_mfma_f32_16x16x32_bf16 v[120:123], v[108:111], v[196:199], v[120:123]
	v_mfma_f32_16x16x32_bf16 v[116:119], v[152:155], v[196:199], v[116:119]
	v_mfma_f32_16x16x32_bf16 v[112:115], v[108:111], v[204:207], v[112:115]
	v_mfma_f32_16x16x32_bf16 v[104:107], v[152:155], v[204:207], v[104:107]
	s_setprio 0
	s_setprio 1
	v_mfma_f32_16x16x32_bf16 v[64:67], v[160:163], v[176:179], v[64:67]
	v_mfma_f32_16x16x32_bf16 v[60:63], v[168:171], v[176:179], v[60:63]
	v_mfma_f32_16x16x32_bf16 v[56:59], v[160:163], v[184:187], v[56:59]
	v_mfma_f32_16x16x32_bf16 v[52:55], v[168:171], v[184:187], v[52:55]
	v_mfma_f32_16x16x32_bf16 v[48:51], v[160:163], v[192:195], v[48:51]
	v_mfma_f32_16x16x32_bf16 v[44:47], v[168:171], v[192:195], v[44:47]
	v_mfma_f32_16x16x32_bf16 v[40:43], v[160:163], v[200:203], v[40:43]
	v_mfma_f32_16x16x32_bf16 v[36:39], v[168:171], v[200:203], v[36:39]
	v_mfma_f32_16x16x32_bf16 v[64:67], v[164:167], v[180:183], v[64:67]
	v_mfma_f32_16x16x32_bf16 v[60:63], v[172:175], v[180:183], v[60:63]
	v_mfma_f32_16x16x32_bf16 v[56:59], v[164:167], v[188:191], v[56:59]
	v_mfma_f32_16x16x32_bf16 v[52:55], v[172:175], v[188:191], v[52:55]
	v_mfma_f32_16x16x32_bf16 v[48:51], v[164:167], v[196:199], v[48:51]
	v_mfma_f32_16x16x32_bf16 v[44:47], v[172:175], v[196:199], v[44:47]
	v_mfma_f32_16x16x32_bf16 v[40:43], v[164:167], v[204:207], v[40:43]
	v_mfma_f32_16x16x32_bf16 v[36:39], v[172:175], v[204:207], v[36:39]
	s_setprio 0
	s_barrier
	s_mov_b32 m0, s50
	v_lshl_add_u64 v[156:157], s[38:39], 0, v[142:143]
	global_load_lds_dwordx4 v[156:157], off
	v_lshl_add_u64 v[208:209], s[38:39], 0, v[146:147]
	s_mov_b32 m0, s51
	v_lshl_add_u64 v[2:3], s[40:41], 0, v[142:143]
	global_load_lds_dwordx4 v[208:209], off
	s_mov_b32 m0, s52
	v_lshl_add_u64 v[210:211], s[36:37], 0, v[140:141]
	global_load_lds_dwordx4 v[2:3], off
	v_lshl_add_u64 v[2:3], s[40:41], 0, v[146:147]
	s_mov_b32 m0, s53
	v_lshl_add_u64 v[212:213], s[36:37], 0, v[144:145]
	global_load_lds_dwordx4 v[2:3], off
	s_mov_b32 m0, s54
	s_nop 0
	global_load_lds_dwordx4 v[210:211], off
	s_mov_b32 m0, s55
	s_nop 0
	global_load_lds_dwordx4 v[212:213], off
	ds_read_b128 v[176:179], v158 offset:17408
	ds_read_b128 v[180:183], v158 offset:18432
	ds_read_b128 v[184:187], v158 offset:19456
	ds_read_b128 v[188:191], v158 offset:20480
	ds_read_b128 v[192:195], v158 offset:21504
	ds_read_b128 v[196:199], v158 offset:22528
	ds_read_b128 v[200:203], v158 offset:23552
	ds_read_b128 v[204:207], v158 offset:24576
	s_setprio 1
	s_waitcnt vmcnt(8) lgkmcnt(0)
	s_barrier
; #define PG8_STAGE(bufoff, gbase, voff) do { _Pragma("unroll") for (int _i = 0; _i < 2; ++_i) \
;         __builtin_amdgcn_global_load_lds((const GAS unsigned*)((const GAS char*)(gbase) + (voff)[_i]), (LAS unsigned*)(lds + (bufoff) + ldsw + _i * 8192), 16, 0, 0); } while (0)
; #define PG8_LDA(dst, b, h) do { _Pragma("unroll") for (int m = 0; m < 4; ++m) _Pragma("unroll") for (int k = 0; k < 2; ++k) dst[m][k] = *(const LAS bf16x8*)(lds + PG8_SA(b, h) + aoff + m * 2048 + k * 1024); } while (0)
; #define PG8_LDB(dst, b, h) do { _Pragma("unroll") for (int n = 0; n < 2; ++n) _Pragma("unroll") for (int k = 0; k < 2; ++k) dst[n][k] = *(const LAS bf16x8*)(lds + PG8_SB(b, h) + boff + n * 2048 + k * 1024); } while (0)
; #define PG8_MMA(ai, bj, At, Bt) do { __builtin_amdgcn_s_setprio(1); _Pragma("unroll") for (int m = 0; m < 4; ++m) _Pragma("unroll") for (int n = 0; n < 2; ++n) _Pragma("unroll") for (int k = 0; k < 2; ++k) \
;         acc[ai][bj][m][n] = __builtin_amdgcn_mfma_f32_16x16x32_bf16(Bt[n][k], At[m][k], acc[ai][bj][m][n], 0, 0, 0); __builtin_amdgcn_s_setprio(0); } while (0)
; #define PG8_WAIT_V(n) asm volatile("s_waitcnt vmcnt(" #n ")" ::: "memory")
; #define PG8_WAIT_L(n) asm volatile("s_waitcnt lgkmcnt(" #n ")" ::: "memory")
; #define PG8_BAR __builtin_amdgcn_s_barrier()
; #define PG8_SCHED __builtin_amdgcn_sched_barrier(0)
; template <class Epi, class Sched, bool ALIGN_EPI>
; __device__ __forceinline__ void gemm_phase(LAS unsigned char* lds, const Gemm g, const Sched& S, const Epi& E, int wave_id) {
;     ...
;             PG8_WAIT_V(8); PG8_WAIT_L(0); PG8_BAR; PG8_MMA(1, 0, At, B0); PG8_MMA(1, 1, At, B1); PG8_BAR; PG8_SCHED;
;             PG8_LDB(B0, 1, 0); PG8_LDB(B1, 1, 1); PG8_SCHED; PG8_LDA(At, 1, 0); PG8_STAGE(PG8_SA(0, 1), a2 + hsA, voffA);
;             PG8_WAIT_V(8); PG8_WAIT_L(0); PG8_BAR; PG8_MMA(0, 0, At, B0); PG8_MMA(0, 1, At, B1); PG8_BAR; PG8_SCHED;
	v_mfma_f32_16x16x32_bf16 v[96:99], v[100:103], v[176:179], v[96:99]
	v_mfma_f32_16x16x32_bf16 v[92:95], v[148:151], v[176:179], v[92:95]
	v_mfma_f32_16x16x32_bf16 v[88:91], v[100:103], v[184:187], v[88:91]
	v_mfma_f32_16x16x32_bf16 v[84:87], v[148:151], v[184:187], v[84:87]
	v_mfma_f32_16x16x32_bf16 v[80:83], v[100:103], v[192:195], v[80:83]
	v_mfma_f32_16x16x32_bf16 v[76:79], v[148:151], v[192:195], v[76:79]
	v_mfma_f32_16x16x32_bf16 v[72:75], v[100:103], v[200:203], v[72:75]
	v_mfma_f32_16x16x32_bf16 v[68:71], v[148:151], v[200:203], v[68:71]
	v_mfma_f32_16x16x32_bf16 v[96:99], v[108:111], v[180:183], v[96:99]
	v_mfma_f32_16x16x32_bf16 v[92:95], v[152:155], v[180:183], v[92:95]
	v_mfma_f32_16x16x32_bf16 v[88:91], v[108:111], v[188:191], v[88:91]
	v_mfma_f32_16x16x32_bf16 v[84:87], v[152:155], v[188:191], v[84:87]
	v_mfma_f32_16x16x32_bf16 v[80:83], v[108:111], v[196:199], v[80:83]
	v_mfma_f32_16x16x32_bf16 v[76:79], v[152:155], v[196:199], v[76:79]
	v_mfma_f32_16x16x32_bf16 v[72:75], v[108:111], v[204:207], v[72:75]
	v_mfma_f32_16x16x32_bf16 v[68:71], v[152:155], v[204:207], v[68:71]
	s_setprio 0
	s_setprio 1
	v_mfma_f32_16x16x32_bf16 v[32:35], v[160:163], v[176:179], v[32:35]
	v_mfma_f32_16x16x32_bf16 v[28:31], v[168:171], v[176:179], v[28:31]
	v_mfma_f32_16x16x32_bf16 v[24:27], v[160:163], v[184:187], v[24:27]
	v_mfma_f32_16x16x32_bf16 v[20:23], v[168:171], v[184:187], v[20:23]
	v_mfma_f32_16x16x32_bf16 v[16:19], v[160:163], v[192:195], v[16:19]
	v_mfma_f32_16x16x32_bf16 v[12:15], v[168:171], v[192:195], v[12:15]
	v_mfma_f32_16x16x32_bf16 v[8:11], v[160:163], v[200:203], v[8:11]
	v_mfma_f32_16x16x32_bf16 v[2:5], v[168:171], v[200:203], v[4:7]
	v_mfma_f32_16x16x32_bf16 v[32:35], v[164:167], v[180:183], v[32:35]
	v_mfma_f32_16x16x32_bf16 v[28:31], v[172:175], v[180:183], v[28:31]
	v_mfma_f32_16x16x32_bf16 v[24:27], v[164:167], v[188:191], v[24:27]
	v_mfma_f32_16x16x32_bf16 v[20:23], v[172:175], v[188:191], v[20:23]
	v_mfma_f32_16x16x32_bf16 v[16:19], v[164:167], v[196:199], v[16:19]
	v_mfma_f32_16x16x32_bf16 v[12:15], v[172:175], v[196:199], v[12:15]
	v_mfma_f32_16x16x32_bf16 v[8:11], v[164:167], v[204:207], v[8:11]
	v_mfma_f32_16x16x32_bf16 v[2:5], v[172:175], v[204:207], v[2:5]
	s_setprio 0
	s_barrier
	s_mov_b32 m0, s56
	v_lshl_add_u64 v[6:7], s[34:35], 0, v[140:141]
	global_load_lds_dwordx4 v[6:7], off
	v_lshl_add_u64 v[6:7], s[34:35], 0, v[144:145]
	s_mov_b32 m0, s57
	s_nop 0
	global_load_lds_dwordx4 v[6:7], off
	v_add_u32_e32 v0, 0x18400, v159
	ds_read_b128 v[100:103], v0
	ds_read_b128 v[108:111], v0 offset:1024
	ds_read_b128 v[148:151], v0 offset:2048
	ds_read_b128 v[152:155], v0 offset:3072
	v_add_u32_e32 v0, 0x1c400, v159
	ds_read_b128 v[160:163], v0
	ds_read_b128 v[164:167], v0 offset:1024
	ds_read_b128 v[168:171], v0 offset:2048
	ds_read_b128 v[172:175], v0 offset:3072
	ds_read_b128 v[176:179], v158 offset:33792
	ds_read_b128 v[180:183], v158 offset:34816
	ds_read_b128 v[184:187], v158 offset:35840
	ds_read_b128 v[188:191], v158 offset:36864
	ds_read_b128 v[192:195], v158 offset:37888
	ds_read_b128 v[196:199], v158 offset:38912
	ds_read_b128 v[200:203], v158 offset:39936
	ds_read_b128 v[204:207], v158 offset:40960
	s_setprio 1
	s_waitcnt vmcnt(8) lgkmcnt(0)
	s_barrier
	v_mfma_f32_16x16x32_bf16 v[136:139], v[100:103], v[176:179], v[136:139]
	v_mfma_f32_16x16x32_bf16 v[132:135], v[148:151], v[176:179], v[132:135]
	v_mfma_f32_16x16x32_bf16 v[128:131], v[100:103], v[184:187], v[128:131]
	v_mfma_f32_16x16x32_bf16 v[124:127], v[148:151], v[184:187], v[124:127]
	v_mfma_f32_16x16x32_bf16 v[120:123], v[100:103], v[192:195], v[120:123]
	v_mfma_f32_16x16x32_bf16 v[116:119], v[148:151], v[192:195], v[116:119]
	v_mfma_f32_16x16x32_bf16 v[112:115], v[100:103], v[200:203], v[112:115]
	v_mfma_f32_16x16x32_bf16 v[104:107], v[148:151], v[200:203], v[104:107]
	v_mfma_f32_16x16x32_bf16 v[136:139], v[108:111], v[180:183], v[136:139]
	v_mfma_f32_16x16x32_bf16 v[132:135], v[152:155], v[180:183], v[132:135]
	v_mfma_f32_16x16x32_bf16 v[128:131], v[108:111], v[188:191], v[128:131]
	v_mfma_f32_16x16x32_bf16 v[124:127], v[152:155], v[188:191], v[124:127]
	v_mfma_f32_16x16x32_bf16 v[120:123], v[108:111], v[196:199], v[120:123]
	v_mfma_f32_16x16x32_bf16 v[116:119], v[152:155], v[196:199], v[116:119]
	v_mfma_f32_16x16x32_bf16 v[112:115], v[108:111], v[204:207], v[112:115]
	v_mfma_f32_16x16x32_bf16 v[104:107], v[152:155], v[204:207], v[104:107]
	s_setprio 0
	s_setprio 1
	v_mfma_f32_16x16x32_bf16 v[64:67], v[160:163], v[176:179], v[64:67]
	v_mfma_f32_16x16x32_bf16 v[60:63], v[168:171], v[176:179], v[60:63]
	v_mfma_f32_16x16x32_bf16 v[56:59], v[160:163], v[184:187], v[56:59]
	v_mfma_f32_16x16x32_bf16 v[52:55], v[168:171], v[184:187], v[52:55]
	v_mfma_f32_16x16x32_bf16 v[48:51], v[160:163], v[192:195], v[48:51]
	v_mfma_f32_16x16x32_bf16 v[44:47], v[168:171], v[192:195], v[44:47]
	v_mfma_f32_16x16x32_bf16 v[40:43], v[160:163], v[200:203], v[40:43]
	v_mfma_f32_16x16x32_bf16 v[36:39], v[168:171], v[200:203], v[36:39]
	v_mfma_f32_16x16x32_bf16 v[64:67], v[164:167], v[180:183], v[64:67]
	v_mfma_f32_16x16x32_bf16 v[60:63], v[172:175], v[180:183], v[60:63]
	v_mfma_f32_16x16x32_bf16 v[56:59], v[164:167], v[188:191], v[56:59]
	v_mfma_f32_16x16x32_bf16 v[52:55], v[172:175], v[188:191], v[52:55]
	v_mfma_f32_16x16x32_bf16 v[48:51], v[164:167], v[196:199], v[48:51]
	v_mfma_f32_16x16x32_bf16 v[44:47], v[172:175], v[196:199], v[44:47]
	v_mfma_f32_16x16x32_bf16 v[40:43], v[164:167], v[204:207], v[40:43]
	v_mfma_f32_16x16x32_bf16 v[36:39], v[172:175], v[204:207], v[36:39]
	s_setprio 0
	s_barrier
; #define PG8_STAGE(bufoff, gbase, voff) do { _Pragma("unroll") for (int _i = 0; _i < 2; ++_i) \
;         __builtin_amdgcn_global_load_lds((const GAS unsigned*)((const GAS char*)(gbase) + (voff)[_i]), (LAS unsigned*)(lds + (bufoff) + ldsw + _i * 8192), 16, 0, 0); } while (0)
; #define PG8_LDA(dst, b, h) do { _Pragma("unroll") for (int m = 0; m < 4; ++m) _Pragma("unroll") for (int k = 0; k < 2; ++k) dst[m][k] = *(const LAS bf16x8*)(lds + PG8_SA(b, h) + aoff + m * 2048 + k * 1024); } while (0)
; #define PG8_MMA(ai, bj, At, Bt) do { __builtin_amdgcn_s_setprio(1); _Pragma("unroll") for (int m = 0; m < 4; ++m) _Pragma("unroll") for (int n = 0; n < 2; ++n) _Pragma("unroll") for (int k = 0; k < 2; ++k) \
;         acc[ai][bj][m][n] = __builtin_amdgcn_mfma_f32_16x16x32_bf16(Bt[n][k], At[m][k], acc[ai][bj][m][n], 0, 0, 0); __builtin_amdgcn_s_setprio(0); } while (0)
; #define PG8_WAIT_V(n) asm volatile("s_waitcnt vmcnt(" #n ")" ::: "memory")
; #define PG8_WAIT_L(n) asm volatile("s_waitcnt lgkmcnt(" #n ")" ::: "memory")
; #define PG8_BAR __builtin_amdgcn_s_barrier()
; #define PG8_SCHED __builtin_amdgcn_sched_barrier(0)
; template <class Epi, class Sched, bool ALIGN_EPI>
; __device__ __forceinline__ void gemm_phase(LAS unsigned char* lds, const Gemm g, const Sched& S, const Epi& E, int wave_id) {
;     ...
;             PG8_LDA(At, 1, 1); PG8_STAGE(PG8_SB(1, 0), b3, voffB); PG8_STAGE(PG8_SB(1, 1), b3 + hsB, voffB); PG8_STAGE(PG8_SA(1, 0), a3, voffA);
;             PG8_WAIT_V(8); PG8_WAIT_L(0); PG8_BAR; PG8_MMA(1, 0, At, B0); PG8_MMA(1, 1, At, B1); PG8_BAR; PG8_SCHED;
;         }
	s_mov_b32 m0, s63
	v_lshl_add_u64 v[6:7], v[156:157], 0, s[92:93]
	global_load_lds_dwordx4 v[6:7], off
	v_lshl_add_u64 v[6:7], v[208:209], 0, s[92:93]
	s_mov_b32 m0, s64
	s_nop 0
	global_load_lds_dwordx4 v[6:7], off
	v_lshl_add_u64 v[6:7], s[30:31], 0, v[142:143]
	s_mov_b32 m0, s67
	s_nop 0
	global_load_lds_dwordx4 v[6:7], off
	v_lshl_add_u64 v[6:7], s[30:31], 0, v[146:147]
	s_mov_b32 m0, s72
	s_nop 0
	global_load_lds_dwordx4 v[6:7], off
	v_lshl_add_u64 v[6:7], v[210:211], 0, s[92:93]
	s_mov_b32 m0, s65
	s_nop 0
	global_load_lds_dwordx4 v[6:7], off
	v_lshl_add_u64 v[6:7], v[212:213], 0, s[92:93]
	s_mov_b32 m0, s66
	s_nop 0
	global_load_lds_dwordx4 v[6:7], off
	ds_read_b128 v[176:179], v158 offset:50176
	ds_read_b128 v[180:183], v158 offset:51200
	ds_read_b128 v[184:187], v158 offset:52224
	ds_read_b128 v[188:191], v158 offset:53248
	ds_read_b128 v[192:195], v158 offset:54272
	ds_read_b128 v[196:199], v158 offset:55296
	ds_read_b128 v[200:203], v158 offset:56320
	ds_read_b128 v[204:207], v158 offset:57344
	s_setprio 1
	s_waitcnt vmcnt(8) lgkmcnt(0)
	s_barrier
	v_mfma_f32_16x16x32_bf16 v[96:99], v[100:103], v[176:179], v[96:99]
	v_mfma_f32_16x16x32_bf16 v[92:95], v[148:151], v[176:179], v[92:95]
	v_mfma_f32_16x16x32_bf16 v[88:91], v[100:103], v[184:187], v[88:91]
	v_mfma_f32_16x16x32_bf16 v[84:87], v[148:151], v[184:187], v[84:87]
	v_mfma_f32_16x16x32_bf16 v[80:83], v[100:103], v[192:195], v[80:83]
	v_mfma_f32_16x16x32_bf16 v[76:79], v[148:151], v[192:195], v[76:79]
	v_mfma_f32_16x16x32_bf16 v[72:75], v[100:103], v[200:203], v[72:75]
	v_mfma_f32_16x16x32_bf16 v[68:71], v[148:151], v[200:203], v[68:71]
	v_mfma_f32_16x16x32_bf16 v[96:99], v[108:111], v[180:183], v[96:99]
	v_mfma_f32_16x16x32_bf16 v[92:95], v[152:155], v[180:183], v[92:95]
	v_mfma_f32_16x16x32_bf16 v[88:91], v[108:111], v[188:191], v[88:91]
	v_mfma_f32_16x16x32_bf16 v[84:87], v[152:155], v[188:191], v[84:87]
	v_mfma_f32_16x16x32_bf16 v[80:83], v[108:111], v[196:199], v[80:83]
	v_mfma_f32_16x16x32_bf16 v[76:79], v[152:155], v[196:199], v[76:79]
	v_mfma_f32_16x16x32_bf16 v[72:75], v[108:111], v[204:207], v[72:75]
	v_mfma_f32_16x16x32_bf16 v[68:71], v[152:155], v[204:207], v[68:71]
	s_setprio 0
	s_setprio 1
	v_mfma_f32_16x16x32_bf16 v[32:35], v[160:163], v[176:179], v[32:35]
	v_mfma_f32_16x16x32_bf16 v[28:31], v[168:171], v[176:179], v[28:31]
	v_mfma_f32_16x16x32_bf16 v[24:27], v[160:163], v[184:187], v[24:27]
	v_mfma_f32_16x16x32_bf16 v[20:23], v[168:171], v[184:187], v[20:23]
	v_mfma_f32_16x16x32_bf16 v[16:19], v[160:163], v[192:195], v[16:19]
	v_mfma_f32_16x16x32_bf16 v[12:15], v[168:171], v[192:195], v[12:15]
	v_mfma_f32_16x16x32_bf16 v[6:9], v[160:163], v[200:203], v[8:11]
	v_mfma_f32_16x16x32_bf16 v[2:5], v[168:171], v[200:203], v[2:5]
	v_mfma_f32_16x16x32_bf16 v[32:35], v[164:167], v[180:183], v[32:35]
	v_mfma_f32_16x16x32_bf16 v[28:31], v[172:175], v[180:183], v[28:31]
	v_mfma_f32_16x16x32_bf16 v[24:27], v[164:167], v[188:191], v[24:27]
	v_mfma_f32_16x16x32_bf16 v[20:23], v[172:175], v[188:191], v[20:23]
	v_mfma_f32_16x16x32_bf16 v[16:19], v[164:167], v[196:199], v[16:19]
	v_mfma_f32_16x16x32_bf16 v[12:15], v[172:175], v[196:199], v[12:15]
	v_mfma_f32_16x16x32_bf16 v[8:11], v[164:167], v[204:207], v[6:9]
	v_mfma_f32_16x16x32_bf16 v[4:7], v[172:175], v[204:207], v[2:5]
	s_setprio 0
	s_barrier
	s_andn2_b64 vcc, exec, s[28:29]
	s_mov_b64 s[30:31], -1
	s_mov_b64 s[28:29], 0
	s_mov_b64 s[34:35], 0x100
	s_cbranch_vccz .LBB0_1458
	s_and_b64 vcc, exec, s[16:17]
	s_cbranch_vccz .LBB0_1461
	s_barrier

; #define GAS __attribute__((address_space(1)))
; #define PG8_STAGE(bufoff, gbase, voff) do { _Pragma("unroll") for (int _i = 0; _i < 2; ++_i) \
;         __builtin_amdgcn_global_load_lds((const GAS unsigned*)((const GAS char*)(gbase) + (voff)[_i]), (LAS unsigned*)(lds + (bufoff) + ldsw + _i * 8192), 16, 0, 0); } while (0)
; #define PG8_LDA(dst, b, h) do { _Pragma("unroll") for (int m = 0; m < 4; ++m) _Pragma("unroll") for (int k = 0; k < 2; ++k) dst[m][k] = *(const LAS bf16x8*)(lds + PG8_SA(b, h) + aoff + m * 2048 + k * 1024); } while (0)
; #define PG8_LDB(dst, b, h) do { _Pragma("unroll") for (int n = 0; n < 2; ++n) _Pragma("unroll") for (int k = 0; k < 2; ++k) dst[n][k] = *(const LAS bf16x8*)(lds + PG8_SB(b, h) + boff + n * 2048 + k * 1024); } while (0)
; #define PG8_MMA(ai, bj, At, Bt) do { __builtin_amdgcn_s_setprio(1); _Pragma("unroll") for (int m = 0; m < 4; ++m) _Pragma("unroll") for (int n = 0; n < 2; ++n) _Pragma("unroll") for (int k = 0; k < 2; ++k) \
;         acc[ai][bj][m][n] = __builtin_amdgcn_mfma_f32_16x16x32_bf16(Bt[n][k], At[m][k], acc[ai][bj][m][n], 0, 0, 0); __builtin_amdgcn_s_setprio(0); } while (0)
; #define PG8_WAIT_V(n) asm volatile("s_waitcnt vmcnt(" #n ")" ::: "memory")
; #define PG8_WAIT_L(n) asm volatile("s_waitcnt lgkmcnt(" #n ")" ::: "memory")
; #define PG8_BAR __builtin_amdgcn_s_barrier()
; template <class Epi, class Sched, bool ALIGN_EPI>
; __device__ __forceinline__ void gemm_phase(LAS unsigned char* lds, const Gemm g, const Sched& S, const Epi& E, int wave_id) {
;     ...
;             const bool last = (t == nt - 2);
;             const GAS char* a1 = cA + (size_t)(t + 1) * kstep;
;             const GAS char* a2 = last ? nA : cA + (size_t)(t + 2) * kstep; const GAS char* b2 = last ? nB : cB + (size_t)(t + 2) * kstep;
;             const GAS char* a3 = a2 + kstep; const GAS char* b3 = b2 + kstep;
;             PG8_LDB(B0, 0, 0); PG8_LDB(B1, 0, 1); PG8_SCHED; PG8_LDA(At, 0, 0); PG8_STAGE(PG8_SA(1, 1), a1 + hsA, voffA);
;             PG8_WAIT_V(8); PG8_WAIT_L(0); PG8_BAR; PG8_MMA(0, 0, At, B0); PG8_MMA(0, 1, At, B1); PG8_BAR; PG8_SCHED;
;             PG8_LDA(At, 0, 1); PG8_STAGE(PG8_SB(0, 0), b2, voffB); PG8_STAGE(PG8_SB(0, 1), b2 + hsB, voffB); PG8_STAGE(PG8_SA(0, 0), a2, voffA);
;             PG8_WAIT_V(8); PG8_WAIT_L(0); PG8_BAR; PG8_MMA(1, 0, At, B0); PG8_MMA(1, 1, At, B1); PG8_BAR; PG8_SCHED;
.LBB0_1645:
	s_add_u32 s20, s18, 0x100
	s_addc_u32 s21, s19, 0
	s_cmp_eq_u32 s55, 2
	s_cselect_b32 s25, s15, s21
	s_cselect_b32 s24, s14, s20
	s_cselect_b32 s23, s17, s54
	s_cselect_b32 s22, s16, s53
	v_lshl_add_u64 v[192:193], s[18:19], 0, v[170:171]
	s_add_i32 m0, s31, 0xc400
	s_nop 0
	global_load_lds_dwordx4 v[192:193], off
	v_lshl_add_u64 v[192:193], s[18:19], 0, v[168:169]
	s_add_i32 m0, s31, 0xe400
	s_nop 0
	global_load_lds_dwordx4 v[192:193], off
	v_add_u32_e32 v134, 0x10400, v195
	v_add_u32_e32 v158, 0x14400, v195
	ds_read_b128 v[114:117], v134
	ds_read_b128 v[118:121], v134 offset:1024
	ds_read_b128 v[130:133], v134 offset:2048
	ds_read_b128 v[134:137], v134 offset:3072
	ds_read_b128 v[146:149], v158
	ds_read_b128 v[150:153], v158 offset:1024
	ds_read_b128 v[154:157], v158 offset:2048
	ds_read_b128 v[158:161], v158 offset:3072
	ds_read_b128 v[172:175], v194 offset:1024
	ds_read_b128 v[176:179], v194 offset:2048
	ds_read_b128 v[180:183], v194 offset:3072
	ds_read_b128 v[184:187], v194 offset:4096
	ds_read_b128 v[188:191], v194 offset:5120
	ds_read_b128 v[196:199], v194 offset:6144
	ds_read_b128 v[200:203], v194 offset:7168
	ds_read_b128 v[204:207], v194 offset:8192
	s_setprio 1
	s_waitcnt vmcnt(8) lgkmcnt(0)
	s_barrier
	v_mfma_f32_16x16x32_bf16 v[142:145], v[114:117], v[172:175], v[142:145]
	v_mfma_f32_16x16x32_bf16 v[138:141], v[130:133], v[172:175], v[138:141]
	v_mfma_f32_16x16x32_bf16 v[126:129], v[114:117], v[180:183], v[126:129]
	v_mfma_f32_16x16x32_bf16 v[122:125], v[130:133], v[180:183], v[122:125]
	v_mfma_f32_16x16x32_bf16 v[110:113], v[114:117], v[188:191], v[110:113]
	v_mfma_f32_16x16x32_bf16 v[106:109], v[130:133], v[188:191], v[106:109]
	v_mfma_f32_16x16x32_bf16 v[102:105], v[114:117], v[200:203], v[102:105]
	v_mfma_f32_16x16x32_bf16 v[98:101], v[130:133], v[200:203], v[98:101]
	v_mfma_f32_16x16x32_bf16 v[142:145], v[118:121], v[176:179], v[142:145]
	v_mfma_f32_16x16x32_bf16 v[138:141], v[134:137], v[176:179], v[138:141]
	v_mfma_f32_16x16x32_bf16 v[126:129], v[118:121], v[184:187], v[126:129]
	v_mfma_f32_16x16x32_bf16 v[122:125], v[134:137], v[184:187], v[122:125]
	v_mfma_f32_16x16x32_bf16 v[110:113], v[118:121], v[196:199], v[110:113]
	v_mfma_f32_16x16x32_bf16 v[106:109], v[134:137], v[196:199], v[106:109]
	v_mfma_f32_16x16x32_bf16 v[102:105], v[118:121], v[204:207], v[102:105]
	v_mfma_f32_16x16x32_bf16 v[98:101], v[134:137], v[204:207], v[98:101]
	s_setprio 0
	s_setprio 1
	v_mfma_f32_16x16x32_bf16 v[62:65], v[146:149], v[172:175], v[62:65]
	v_mfma_f32_16x16x32_bf16 v[58:61], v[154:157], v[172:175], v[58:61]
	v_mfma_f32_16x16x32_bf16 v[54:57], v[146:149], v[180:183], v[54:57]
	v_mfma_f32_16x16x32_bf16 v[50:53], v[154:157], v[180:183], v[50:53]
	v_mfma_f32_16x16x32_bf16 v[46:49], v[146:149], v[188:191], v[46:49]
	v_mfma_f32_16x16x32_bf16 v[42:45], v[154:157], v[188:191], v[42:45]
	v_mfma_f32_16x16x32_bf16 v[38:41], v[146:149], v[200:203], v[38:41]
	v_mfma_f32_16x16x32_bf16 v[34:37], v[154:157], v[200:203], v[34:37]
	v_mfma_f32_16x16x32_bf16 v[62:65], v[150:153], v[176:179], v[62:65]
	v_mfma_f32_16x16x32_bf16 v[58:61], v[158:161], v[176:179], v[58:61]
	v_mfma_f32_16x16x32_bf16 v[54:57], v[150:153], v[184:187], v[54:57]
	v_mfma_f32_16x16x32_bf16 v[50:53], v[158:161], v[184:187], v[50:53]
	v_mfma_f32_16x16x32_bf16 v[46:49], v[150:153], v[196:199], v[46:49]
	v_mfma_f32_16x16x32_bf16 v[42:45], v[158:161], v[196:199], v[42:45]
	v_mfma_f32_16x16x32_bf16 v[38:41], v[150:153], v[204:207], v[38:41]
	v_mfma_f32_16x16x32_bf16 v[34:37], v[158:161], v[204:207], v[34:37]
	s_setprio 0
	s_barrier
	s_mov_b32 m0, s34
	v_lshl_add_u64 v[192:193], s[22:23], 0, v[0:1]
	s_add_u32 s18, s22, 0x18000
	global_load_lds_dwordx4 v[192:193], off
	v_lshl_add_u64 v[208:209], s[22:23], 0, v[162:163]
	s_mov_b32 m0, s35
	s_addc_u32 s19, s23, 0
	global_load_lds_dwordx4 v[208:209], off
	v_lshl_add_u64 v[210:211], s[18:19], 0, v[0:1]
	s_mov_b32 m0, s36
	v_lshl_add_u64 v[212:213], s[24:25], 0, v[164:165]
	global_load_lds_dwordx4 v[210:211], off
	v_lshl_add_u64 v[210:211], s[18:19], 0, v[162:163]
	s_mov_b32 m0, s37
	s_nop 0
	global_load_lds_dwordx4 v[210:211], off
	v_lshl_add_u64 v[210:211], s[24:25], 0, v[166:167]
	s_mov_b32 m0, s38
	s_nop 0
	global_load_lds_dwordx4 v[210:211], off
	s_mov_b32 m0, s39
	s_nop 0
	global_load_lds_dwordx4 v[212:213], off
	ds_read_b128 v[172:175], v194 offset:17408
	ds_read_b128 v[176:179], v194 offset:18432
	ds_read_b128 v[180:183], v194 offset:19456
	ds_read_b128 v[184:187], v194 offset:20480
	ds_read_b128 v[188:191], v194 offset:21504
	ds_read_b128 v[196:199], v194 offset:22528
	ds_read_b128 v[200:203], v194 offset:23552
	ds_read_b128 v[204:207], v194 offset:24576
	s_setprio 1
	s_waitcnt vmcnt(8) lgkmcnt(0)
	s_barrier
; #define PG8_STAGE(bufoff, gbase, voff) do { _Pragma("unroll") for (int _i = 0; _i < 2; ++_i) \
;         __builtin_amdgcn_global_load_lds((const GAS unsigned*)((const GAS char*)(gbase) + (voff)[_i]), (LAS unsigned*)(lds + (bufoff) + ldsw + _i * 8192), 16, 0, 0); } while (0)
; #define PG8_LDA(dst, b, h) do { _Pragma("unroll") for (int m = 0; m < 4; ++m) _Pragma("unroll") for (int k = 0; k < 2; ++k) dst[m][k] = *(const LAS bf16x8*)(lds + PG8_SA(b, h) + aoff + m * 2048 + k * 1024); } while (0)
; #define PG8_LDB(dst, b, h) do { _Pragma("unroll") for (int n = 0; n < 2; ++n) _Pragma("unroll") for (int k = 0; k < 2; ++k) dst[n][k] = *(const LAS bf16x8*)(lds + PG8_SB(b, h) + boff + n * 2048 + k * 1024); } while (0)
; #define PG8_MMA(ai, bj, At, Bt) do { __builtin_amdgcn_s_setprio(1); _Pragma("unroll") for (int m = 0; m < 4; ++m) _Pragma("unroll") for (int n = 0; n < 2; ++n) _Pragma("unroll") for (int k = 0; k < 2; ++k) \
;         acc[ai][bj][m][n] = __builtin_amdgcn_mfma_f32_16x16x32_bf16(Bt[n][k], At[m][k], acc[ai][bj][m][n], 0, 0, 0); __builtin_amdgcn_s_setprio(0); } while (0)
; #define PG8_WAIT_V(n) asm volatile("s_waitcnt vmcnt(" #n ")" ::: "memory")
; #define PG8_WAIT_L(n) asm volatile("s_waitcnt lgkmcnt(" #n ")" ::: "memory")
; #define PG8_BAR __builtin_amdgcn_s_barrier()
; #define PG8_SCHED __builtin_amdgcn_sched_barrier(0)
; template <class Epi, class Sched, bool ALIGN_EPI>
; __device__ __forceinline__ void gemm_phase(LAS unsigned char* lds, const Gemm g, const Sched& S, const Epi& E, int wave_id) {
;     ...
;             PG8_WAIT_V(8); PG8_WAIT_L(0); PG8_BAR; PG8_MMA(1, 0, At, B0); PG8_MMA(1, 1, At, B1); PG8_BAR; PG8_SCHED;
;             PG8_LDB(B0, 1, 0); PG8_LDB(B1, 1, 1); PG8_SCHED; PG8_LDA(At, 1, 0); PG8_STAGE(PG8_SA(0, 1), a2 + hsA, voffA);
;             PG8_WAIT_V(8); PG8_WAIT_L(0); PG8_BAR; PG8_MMA(0, 0, At, B0); PG8_MMA(0, 1, At, B1); PG8_BAR; PG8_SCHED;
	v_mfma_f32_16x16x32_bf16 v[94:97], v[114:117], v[172:175], v[94:97]
	v_mfma_f32_16x16x32_bf16 v[90:93], v[130:133], v[172:175], v[90:93]
	v_mfma_f32_16x16x32_bf16 v[86:89], v[114:117], v[180:183], v[86:89]
	v_mfma_f32_16x16x32_bf16 v[82:85], v[130:133], v[180:183], v[82:85]
	v_mfma_f32_16x16x32_bf16 v[78:81], v[114:117], v[188:191], v[78:81]
	v_mfma_f32_16x16x32_bf16 v[74:77], v[130:133], v[188:191], v[74:77]
	v_mfma_f32_16x16x32_bf16 v[70:73], v[114:117], v[200:203], v[70:73]
	v_mfma_f32_16x16x32_bf16 v[66:69], v[130:133], v[200:203], v[66:69]
	v_mfma_f32_16x16x32_bf16 v[94:97], v[118:121], v[176:179], v[94:97]
	v_mfma_f32_16x16x32_bf16 v[90:93], v[134:137], v[176:179], v[90:93]
	v_mfma_f32_16x16x32_bf16 v[86:89], v[118:121], v[184:187], v[86:89]
	v_mfma_f32_16x16x32_bf16 v[82:85], v[134:137], v[184:187], v[82:85]
	v_mfma_f32_16x16x32_bf16 v[78:81], v[118:121], v[196:199], v[78:81]
	v_mfma_f32_16x16x32_bf16 v[74:77], v[134:137], v[196:199], v[74:77]
	v_mfma_f32_16x16x32_bf16 v[70:73], v[118:121], v[204:207], v[70:73]
	v_mfma_f32_16x16x32_bf16 v[66:69], v[134:137], v[204:207], v[66:69]
	s_setprio 0
	s_setprio 1
	v_mfma_f32_16x16x32_bf16 v[30:33], v[146:149], v[172:175], v[30:33]
	v_mfma_f32_16x16x32_bf16 v[26:29], v[154:157], v[172:175], v[26:29]
	v_mfma_f32_16x16x32_bf16 v[22:25], v[146:149], v[180:183], v[22:25]
	v_mfma_f32_16x16x32_bf16 v[18:21], v[154:157], v[180:183], v[18:21]
	v_mfma_f32_16x16x32_bf16 v[14:17], v[146:149], v[188:191], v[14:17]
	v_mfma_f32_16x16x32_bf16 v[10:13], v[154:157], v[188:191], v[10:13]
	v_mfma_f32_16x16x32_bf16 v[6:9], v[146:149], v[200:203], v[6:9]
	v_mfma_f32_16x16x32_bf16 v[2:5], v[154:157], v[200:203], v[2:5]
	v_mfma_f32_16x16x32_bf16 v[30:33], v[150:153], v[176:179], v[30:33]
	v_mfma_f32_16x16x32_bf16 v[26:29], v[158:161], v[176:179], v[26:29]
	v_mfma_f32_16x16x32_bf16 v[22:25], v[150:153], v[184:187], v[22:25]
	v_mfma_f32_16x16x32_bf16 v[18:21], v[158:161], v[184:187], v[18:21]
	v_mfma_f32_16x16x32_bf16 v[14:17], v[150:153], v[196:199], v[14:17]
	v_mfma_f32_16x16x32_bf16 v[10:13], v[158:161], v[196:199], v[10:13]
	v_mfma_f32_16x16x32_bf16 v[6:9], v[150:153], v[204:207], v[6:9]
	v_mfma_f32_16x16x32_bf16 v[2:5], v[158:161], v[204:207], v[2:5]
	s_setprio 0
	s_barrier
	s_add_u32 s18, s24, 0x18000
	s_addc_u32 s19, s25, 0
	s_mov_b32 m0, s40
	v_lshl_add_u64 v[214:215], s[18:19], 0, v[166:167]
	global_load_lds_dwordx4 v[214:215], off
	v_lshl_add_u64 v[214:215], s[18:19], 0, v[164:165]
	s_mov_b32 m0, s41
	s_nop 0
	global_load_lds_dwordx4 v[214:215], off
	v_add_u32_e32 v134, 0x18400, v195
	v_add_u32_e32 v158, 0x1c400, v195
	ds_read_b128 v[114:117], v134
	ds_read_b128 v[118:121], v134 offset:1024
	ds_read_b128 v[130:133], v134 offset:2048
	ds_read_b128 v[134:137], v134 offset:3072
	ds_read_b128 v[146:149], v158
	ds_read_b128 v[150:153], v158 offset:1024
	ds_read_b128 v[154:157], v158 offset:2048
	ds_read_b128 v[158:161], v158 offset:3072
	ds_read_b128 v[172:175], v194 offset:33792
	ds_read_b128 v[176:179], v194 offset:34816
	ds_read_b128 v[180:183], v194 offset:35840
	ds_read_b128 v[184:187], v194 offset:36864
	ds_read_b128 v[188:191], v194 offset:37888
	ds_read_b128 v[196:199], v194 offset:38912
	ds_read_b128 v[200:203], v194 offset:39936
	ds_read_b128 v[204:207], v194 offset:40960
	s_setprio 1
	s_waitcnt vmcnt(8) lgkmcnt(0)
	s_barrier
	v_mfma_f32_16x16x32_bf16 v[142:145], v[114:117], v[172:175], v[142:145]
	v_mfma_f32_16x16x32_bf16 v[138:141], v[130:133], v[172:175], v[138:141]
	v_mfma_f32_16x16x32_bf16 v[126:129], v[114:117], v[180:183], v[126:129]
	v_mfma_f32_16x16x32_bf16 v[122:125], v[130:133], v[180:183], v[122:125]
	v_mfma_f32_16x16x32_bf16 v[110:113], v[114:117], v[188:191], v[110:113]
	v_mfma_f32_16x16x32_bf16 v[106:109], v[130:133], v[188:191], v[106:109]
	v_mfma_f32_16x16x32_bf16 v[102:105], v[114:117], v[200:203], v[102:105]
	v_mfma_f32_16x16x32_bf16 v[98:101], v[130:133], v[200:203], v[98:101]
	v_mfma_f32_16x16x32_bf16 v[142:145], v[118:121], v[176:179], v[142:145]
	v_mfma_f32_16x16x32_bf16 v[138:141], v[134:137], v[176:179], v[138:141]
	v_mfma_f32_16x16x32_bf16 v[126:129], v[118:121], v[184:187], v[126:129]
	v_mfma_f32_16x16x32_bf16 v[122:125], v[134:137], v[184:187], v[122:125]
	v_mfma_f32_16x16x32_bf16 v[110:113], v[118:121], v[196:199], v[110:113]
	v_mfma_f32_16x16x32_bf16 v[106:109], v[134:137], v[196:199], v[106:109]
	v_mfma_f32_16x16x32_bf16 v[102:105], v[118:121], v[204:207], v[102:105]
	v_mfma_f32_16x16x32_bf16 v[98:101], v[134:137], v[204:207], v[98:101]
	s_setprio 0
	s_setprio 1
	v_mfma_f32_16x16x32_bf16 v[62:65], v[146:149], v[172:175], v[62:65]
	v_mfma_f32_16x16x32_bf16 v[58:61], v[154:157], v[172:175], v[58:61]
	v_mfma_f32_16x16x32_bf16 v[54:57], v[146:149], v[180:183], v[54:57]
	v_mfma_f32_16x16x32_bf16 v[50:53], v[154:157], v[180:183], v[50:53]
	v_mfma_f32_16x16x32_bf16 v[46:49], v[146:149], v[188:191], v[46:49]
	v_mfma_f32_16x16x32_bf16 v[42:45], v[154:157], v[188:191], v[42:45]
	v_mfma_f32_16x16x32_bf16 v[38:41], v[146:149], v[200:203], v[38:41]
	v_mfma_f32_16x16x32_bf16 v[34:37], v[154:157], v[200:203], v[34:37]
	v_mfma_f32_16x16x32_bf16 v[62:65], v[150:153], v[176:179], v[62:65]
	v_mfma_f32_16x16x32_bf16 v[58:61], v[158:161], v[176:179], v[58:61]
	v_mfma_f32_16x16x32_bf16 v[54:57], v[150:153], v[184:187], v[54:57]
	v_mfma_f32_16x16x32_bf16 v[50:53], v[158:161], v[184:187], v[50:53]
	v_mfma_f32_16x16x32_bf16 v[46:49], v[150:153], v[196:199], v[46:49]
	v_mfma_f32_16x16x32_bf16 v[42:45], v[158:161], v[196:199], v[42:45]
	v_mfma_f32_16x16x32_bf16 v[38:41], v[150:153], v[204:207], v[38:41]
	v_mfma_f32_16x16x32_bf16 v[34:37], v[158:161], v[204:207], v[34:37]
	s_setprio 0
	s_barrier
; #define PG8_STAGE(bufoff, gbase, voff) do { _Pragma("unroll") for (int _i = 0; _i < 2; ++_i) \
;         __builtin_amdgcn_global_load_lds((const GAS unsigned*)((const GAS char*)(gbase) + (voff)[_i]), (LAS unsigned*)(lds + (bufoff) + ldsw + _i * 8192), 16, 0, 0); } while (0)
; #define PG8_LDA(dst, b, h) do { _Pragma("unroll") for (int m = 0; m < 4; ++m) _Pragma("unroll") for (int k = 0; k < 2; ++k) dst[m][k] = *(const LAS bf16x8*)(lds + PG8_SA(b, h) + aoff + m * 2048 + k * 1024); } while (0)
; #define PG8_MMA(ai, bj, At, Bt) do { __builtin_amdgcn_s_setprio(1); _Pragma("unroll") for (int m = 0; m < 4; ++m) _Pragma("unroll") for (int n = 0; n < 2; ++n) _Pragma("unroll") for (int k = 0; k < 2; ++k) \
;         acc[ai][bj][m][n] = __builtin_amdgcn_mfma_f32_16x16x32_bf16(Bt[n][k], At[m][k], acc[ai][bj][m][n], 0, 0, 0); __builtin_amdgcn_s_setprio(0); } while (0)
; #define PG8_WAIT_V(n) asm volatile("s_waitcnt vmcnt(" #n ")" ::: "memory")
; #define PG8_WAIT_L(n) asm volatile("s_waitcnt lgkmcnt(" #n ")" ::: "memory")
; #define PG8_BAR __builtin_amdgcn_s_barrier()
; #define PG8_SCHED __builtin_amdgcn_sched_barrier(0)
; template <class Epi, class Sched, bool ALIGN_EPI>
; __device__ __forceinline__ void gemm_phase(LAS unsigned char* lds, const Gemm g, const Sched& S, const Epi& E, int wave_id) {
;     ...
;             PG8_LDA(At, 1, 1); PG8_STAGE(PG8_SB(1, 0), b3, voffB); PG8_STAGE(PG8_SB(1, 1), b3 + hsB, voffB); PG8_STAGE(PG8_SA(1, 0), a3, voffA);
;             PG8_WAIT_V(8); PG8_WAIT_L(0); PG8_BAR; PG8_MMA(1, 0, At, B0); PG8_MMA(1, 1, At, B1); PG8_BAR; PG8_SCHED;
;         }
	s_mov_b32 m0, s44
	v_lshl_add_u64 v[192:193], v[192:193], 0, s[92:93]
	s_add_u32 s18, s22, 0x18080
	global_load_lds_dwordx4 v[192:193], off
	v_lshl_add_u64 v[192:193], v[208:209], 0, s[92:93]
	s_mov_b32 m0, s45
	s_addc_u32 s19, s23, 0
	global_load_lds_dwordx4 v[192:193], off
	v_lshl_add_u64 v[192:193], s[18:19], 0, v[0:1]
	s_mov_b32 m0, s48
	s_nop 0
	global_load_lds_dwordx4 v[192:193], off
	v_lshl_add_u64 v[192:193], s[18:19], 0, v[162:163]
	s_mov_b32 m0, s49
	s_nop 0
	global_load_lds_dwordx4 v[192:193], off
	v_lshl_add_u64 v[192:193], v[210:211], 0, s[92:93]
	s_mov_b32 m0, s46
	s_nop 0
	global_load_lds_dwordx4 v[192:193], off
	v_lshl_add_u64 v[192:193], v[212:213], 0, s[92:93]
	s_mov_b32 m0, s47
	s_nop 0
	global_load_lds_dwordx4 v[192:193], off
	ds_read_b128 v[172:175], v194 offset:50176
	ds_read_b128 v[176:179], v194 offset:51200
	ds_read_b128 v[180:183], v194 offset:52224
	ds_read_b128 v[184:187], v194 offset:53248
	ds_read_b128 v[188:191], v194 offset:54272
	ds_read_b128 v[196:199], v194 offset:55296
	ds_read_b128 v[200:203], v194 offset:56320
	ds_read_b128 v[204:207], v194 offset:57344
	s_setprio 1
	s_waitcnt vmcnt(8) lgkmcnt(0)
	s_barrier
	v_mfma_f32_16x16x32_bf16 v[94:97], v[114:117], v[172:175], v[94:97]
	v_mfma_f32_16x16x32_bf16 v[90:93], v[130:133], v[172:175], v[90:93]
	v_mfma_f32_16x16x32_bf16 v[86:89], v[114:117], v[180:183], v[86:89]
	v_mfma_f32_16x16x32_bf16 v[82:85], v[130:133], v[180:183], v[82:85]
	v_mfma_f32_16x16x32_bf16 v[78:81], v[114:117], v[188:191], v[78:81]
	v_mfma_f32_16x16x32_bf16 v[74:77], v[130:133], v[188:191], v[74:77]
	v_mfma_f32_16x16x32_bf16 v[70:73], v[114:117], v[200:203], v[70:73]
	v_mfma_f32_16x16x32_bf16 v[66:69], v[130:133], v[200:203], v[66:69]
	v_mfma_f32_16x16x32_bf16 v[94:97], v[118:121], v[176:179], v[94:97]
	v_mfma_f32_16x16x32_bf16 v[90:93], v[134:137], v[176:179], v[90:93]
	v_mfma_f32_16x16x32_bf16 v[86:89], v[118:121], v[184:187], v[86:89]
	v_mfma_f32_16x16x32_bf16 v[82:85], v[134:137], v[184:187], v[82:85]
	v_mfma_f32_16x16x32_bf16 v[78:81], v[118:121], v[196:199], v[78:81]
	v_mfma_f32_16x16x32_bf16 v[74:77], v[134:137], v[196:199], v[74:77]
	v_mfma_f32_16x16x32_bf16 v[70:73], v[118:121], v[204:207], v[70:73]
	v_mfma_f32_16x16x32_bf16 v[66:69], v[134:137], v[204:207], v[66:69]
	s_setprio 0
	s_setprio 1
	v_mfma_f32_16x16x32_bf16 v[30:33], v[146:149], v[172:175], v[30:33]
	v_mfma_f32_16x16x32_bf16 v[26:29], v[154:157], v[172:175], v[26:29]
	v_mfma_f32_16x16x32_bf16 v[22:25], v[146:149], v[180:183], v[22:25]
	v_mfma_f32_16x16x32_bf16 v[18:21], v[154:157], v[180:183], v[18:21]
	v_mfma_f32_16x16x32_bf16 v[14:17], v[146:149], v[188:191], v[14:17]
	v_mfma_f32_16x16x32_bf16 v[10:13], v[154:157], v[188:191], v[10:13]
	v_mfma_f32_16x16x32_bf16 v[6:9], v[146:149], v[200:203], v[6:9]
	v_mfma_f32_16x16x32_bf16 v[2:5], v[154:157], v[200:203], v[2:5]
	v_mfma_f32_16x16x32_bf16 v[30:33], v[150:153], v[176:179], v[30:33]
	v_mfma_f32_16x16x32_bf16 v[26:29], v[158:161], v[176:179], v[26:29]
	v_mfma_f32_16x16x32_bf16 v[22:25], v[150:153], v[184:187], v[22:25]
	v_mfma_f32_16x16x32_bf16 v[18:21], v[158:161], v[184:187], v[18:21]
	v_mfma_f32_16x16x32_bf16 v[14:17], v[150:153], v[196:199], v[14:17]
	v_mfma_f32_16x16x32_bf16 v[10:13], v[158:161], v[196:199], v[10:13]
	v_mfma_f32_16x16x32_bf16 v[6:9], v[150:153], v[204:207], v[6:9]
	v_mfma_f32_16x16x32_bf16 v[2:5], v[158:161], v[204:207], v[2:5]
	s_setprio 0
	s_barrier
	s_add_i32 s55, s55, 2
	s_add_u32 s53, s53, 0x100
	s_addc_u32 s54, s54, 0
	s_cmp_gt_u32 s55, 3
	s_mov_b64 s[18:19], s[20:21]
	s_cbranch_scc0 .LBB0_1645
	s_and_b64 vcc, exec, s[12:13]
	s_cbranch_vccz .LBB0_1648
	s_barrier

; #define GAS __attribute__((address_space(1)))
; #define PG8_STAGE(bufoff, gbase, voff) do { _Pragma("unroll") for (int _i = 0; _i < 2; ++_i) \
;         __builtin_amdgcn_global_load_lds((const GAS unsigned*)((const GAS char*)(gbase) + (voff)[_i]), (LAS unsigned*)(lds + (bufoff) + ldsw + _i * 8192), 16, 0, 0); } while (0)
; #define PG8_LDA(dst, b, h) do { _Pragma("unroll") for (int m = 0; m < 4; ++m) _Pragma("unroll") for (int k = 0; k < 2; ++k) dst[m][k] = *(const LAS bf16x8*)(lds + PG8_SA(b, h) + aoff + m * 2048 + k * 1024); } while (0)
; #define PG8_LDB(dst, b, h) do { _Pragma("unroll") for (int n = 0; n < 2; ++n) _Pragma("unroll") for (int k = 0; k < 2; ++k) dst[n][k] = *(const LAS bf16x8*)(lds + PG8_SB(b, h) + boff + n * 2048 + k * 1024); } while (0)
; #define PG8_MMA(ai, bj, At, Bt) do { __builtin_amdgcn_s_setprio(1); _Pragma("unroll") for (int m = 0; m < 4; ++m) _Pragma("unroll") for (int n = 0; n < 2; ++n) _Pragma("unroll") for (int k = 0; k < 2; ++k) \
;         acc[ai][bj][m][n] = __builtin_amdgcn_mfma_f32_16x16x32_bf16(Bt[n][k], At[m][k], acc[ai][bj][m][n], 0, 0, 0); __builtin_amdgcn_s_setprio(0); } while (0)
; #define PG8_WAIT_V(n) asm volatile("s_waitcnt vmcnt(" #n ")" ::: "memory")
; #define PG8_WAIT_L(n) asm volatile("s_waitcnt lgkmcnt(" #n ")" ::: "memory")
; #define PG8_BAR __builtin_amdgcn_s_barrier()
; template <class Epi, class Sched, bool ALIGN_EPI>
; __device__ __forceinline__ void gemm_phase(LAS unsigned char* lds, const Gemm g, const Sched& S, const Epi& E, int wave_id) {
;     ...
;             const bool last = (t == nt - 2);
;             const GAS char* a1 = cA + (size_t)(t + 1) * kstep;
;             const GAS char* a2 = last ? nA : cA + (size_t)(t + 2) * kstep; const GAS char* b2 = last ? nB : cB + (size_t)(t + 2) * kstep;
;             const GAS char* a3 = a2 + kstep; const GAS char* b3 = b2 + kstep;
;             PG8_LDB(B0, 0, 0); PG8_LDB(B1, 0, 1); PG8_SCHED; PG8_LDA(At, 0, 0); PG8_STAGE(PG8_SA(1, 1), a1 + hsA, voffA);
;             PG8_WAIT_V(8); PG8_WAIT_L(0); PG8_BAR; PG8_MMA(0, 0, At, B0); PG8_MMA(0, 1, At, B1); PG8_BAR; PG8_SCHED;
;             PG8_LDA(At, 0, 1); PG8_STAGE(PG8_SB(0, 0), b2, voffB); PG8_STAGE(PG8_SB(0, 1), b2 + hsB, voffB); PG8_STAGE(PG8_SA(0, 0), a2, voffA);
;             PG8_WAIT_V(8); PG8_WAIT_L(0); PG8_BAR; PG8_MMA(1, 0, At, B0); PG8_MMA(1, 1, At, B1); PG8_BAR; PG8_SCHED;
.LBB0_1837:
	s_add_u32 s42, s40, 0xfffc0080
	s_addc_u32 s43, s41, -1
	s_cmp_eq_u32 s67, 12
	s_cselect_b32 s45, s5, s43
	s_cselect_b32 s44, s25, s42
	s_cselect_b32 s43, s27, s66
	s_cselect_b32 s42, s37, s39
	v_lshl_add_u64 v[196:197], s[40:41], 0, v[182:183]
	s_add_i32 m0, s1, 0xc400
	s_nop 0
	global_load_lds_dwordx4 v[196:197], off
	v_lshl_add_u64 v[196:197], s[40:41], 0, v[180:181]
	s_add_i32 m0, s1, 0xe400
	s_nop 0
	global_load_lds_dwordx4 v[196:197], off
	v_add_u32_e32 v142, 0x10400, v199
	v_add_u32_e32 v158, 0x14400, v199
	ds_read_b128 v[130:133], v142
	ds_read_b128 v[134:137], v142 offset:1024
	ds_read_b128 v[138:141], v142 offset:2048
	ds_read_b128 v[142:145], v142 offset:3072
	ds_read_b128 v[146:149], v158
	ds_read_b128 v[150:153], v158 offset:1024
	ds_read_b128 v[154:157], v158 offset:2048
	ds_read_b128 v[158:161], v158 offset:3072
	ds_read_b128 v[162:165], v198 offset:1024
	ds_read_b128 v[166:169], v198 offset:2048
	ds_read_b128 v[170:173], v198 offset:3072
	ds_read_b128 v[184:187], v198 offset:4096
	ds_read_b128 v[188:191], v198 offset:5120
	ds_read_b128 v[192:195], v198 offset:6144
	ds_read_b128 v[200:203], v198 offset:7168
	ds_read_b128 v[204:207], v198 offset:8192
	s_setprio 1
	s_waitcnt vmcnt(8) lgkmcnt(0)
	s_barrier
	v_mfma_f32_16x16x32_bf16 v[126:129], v[130:133], v[162:165], v[126:129]
	v_mfma_f32_16x16x32_bf16 v[122:125], v[138:141], v[162:165], v[122:125]
	v_mfma_f32_16x16x32_bf16 v[114:117], v[130:133], v[170:173], v[114:117]
	v_mfma_f32_16x16x32_bf16 v[106:109], v[138:141], v[170:173], v[106:109]
	v_mfma_f32_16x16x32_bf16 v[98:101], v[130:133], v[188:191], v[98:101]
	v_mfma_f32_16x16x32_bf16 v[90:93], v[138:141], v[188:191], v[90:93]
	v_mfma_f32_16x16x32_bf16 v[82:85], v[130:133], v[200:203], v[82:85]
	v_mfma_f32_16x16x32_bf16 v[74:77], v[138:141], v[200:203], v[74:77]
	v_mfma_f32_16x16x32_bf16 v[126:129], v[134:137], v[166:169], v[126:129]
	v_mfma_f32_16x16x32_bf16 v[122:125], v[142:145], v[166:169], v[122:125]
	v_mfma_f32_16x16x32_bf16 v[114:117], v[134:137], v[184:187], v[114:117]
	v_mfma_f32_16x16x32_bf16 v[106:109], v[142:145], v[184:187], v[106:109]
	v_mfma_f32_16x16x32_bf16 v[98:101], v[134:137], v[192:195], v[98:101]
	v_mfma_f32_16x16x32_bf16 v[90:93], v[142:145], v[192:195], v[90:93]
	v_mfma_f32_16x16x32_bf16 v[82:85], v[134:137], v[204:207], v[82:85]
	v_mfma_f32_16x16x32_bf16 v[74:77], v[142:145], v[204:207], v[74:77]
	s_setprio 0
	s_setprio 1
	v_mfma_f32_16x16x32_bf16 v[118:121], v[146:149], v[162:165], v[118:121]
	v_mfma_f32_16x16x32_bf16 v[110:113], v[154:157], v[162:165], v[110:113]
	v_mfma_f32_16x16x32_bf16 v[102:105], v[146:149], v[170:173], v[102:105]
	v_mfma_f32_16x16x32_bf16 v[94:97], v[154:157], v[170:173], v[94:97]
	v_mfma_f32_16x16x32_bf16 v[86:89], v[146:149], v[188:191], v[86:89]
	v_mfma_f32_16x16x32_bf16 v[78:81], v[154:157], v[188:191], v[78:81]
	v_mfma_f32_16x16x32_bf16 v[70:73], v[146:149], v[200:203], v[70:73]
	v_mfma_f32_16x16x32_bf16 v[66:69], v[154:157], v[200:203], v[66:69]
	v_mfma_f32_16x16x32_bf16 v[118:121], v[150:153], v[166:169], v[118:121]
	v_mfma_f32_16x16x32_bf16 v[110:113], v[158:161], v[166:169], v[110:113]
	v_mfma_f32_16x16x32_bf16 v[102:105], v[150:153], v[184:187], v[102:105]
	v_mfma_f32_16x16x32_bf16 v[94:97], v[158:161], v[184:187], v[94:97]
	v_mfma_f32_16x16x32_bf16 v[86:89], v[150:153], v[192:195], v[86:89]
	v_mfma_f32_16x16x32_bf16 v[78:81], v[158:161], v[192:195], v[78:81]
	v_mfma_f32_16x16x32_bf16 v[70:73], v[150:153], v[204:207], v[70:73]
	v_mfma_f32_16x16x32_bf16 v[66:69], v[158:161], v[204:207], v[66:69]
	s_setprio 0
	s_barrier
	s_mov_b32 m0, s48
	v_lshl_add_u64 v[196:197], s[42:43], 0, v[0:1]
	s_add_u32 s68, s42, 0x40000
	global_load_lds_dwordx4 v[196:197], off
	v_lshl_add_u64 v[208:209], s[42:43], 0, v[178:179]
	s_mov_b32 m0, s49
	s_addc_u32 s69, s43, 0
	global_load_lds_dwordx4 v[208:209], off
	v_lshl_add_u64 v[210:211], s[68:69], 0, v[0:1]
	s_mov_b32 m0, s50
	v_lshl_add_u64 v[212:213], s[44:45], 0, v[176:177]
	global_load_lds_dwordx4 v[210:211], off
	v_lshl_add_u64 v[210:211], s[68:69], 0, v[178:179]
	s_mov_b32 m0, s51
	s_nop 0
	global_load_lds_dwordx4 v[210:211], off
	v_lshl_add_u64 v[210:211], s[44:45], 0, v[174:175]
	s_mov_b32 m0, s52
	s_nop 0
	global_load_lds_dwordx4 v[210:211], off
	s_mov_b32 m0, s53
	s_nop 0
	global_load_lds_dwordx4 v[212:213], off
	ds_read_b128 v[162:165], v198 offset:17408
	ds_read_b128 v[166:169], v198 offset:18432
	ds_read_b128 v[170:173], v198 offset:19456
	ds_read_b128 v[184:187], v198 offset:20480
	ds_read_b128 v[188:191], v198 offset:21504
	ds_read_b128 v[192:195], v198 offset:22528
	ds_read_b128 v[200:203], v198 offset:23552
	ds_read_b128 v[204:207], v198 offset:24576
	s_setprio 1
	s_waitcnt vmcnt(8) lgkmcnt(0)
	s_barrier
; #define PG8_STAGE(bufoff, gbase, voff) do { _Pragma("unroll") for (int _i = 0; _i < 2; ++_i) \
;         __builtin_amdgcn_global_load_lds((const GAS unsigned*)((const GAS char*)(gbase) + (voff)[_i]), (LAS unsigned*)(lds + (bufoff) + ldsw + _i * 8192), 16, 0, 0); } while (0)
; #define PG8_LDA(dst, b, h) do { _Pragma("unroll") for (int m = 0; m < 4; ++m) _Pragma("unroll") for (int k = 0; k < 2; ++k) dst[m][k] = *(const LAS bf16x8*)(lds + PG8_SA(b, h) + aoff + m * 2048 + k * 1024); } while (0)
; #define PG8_LDB(dst, b, h) do { _Pragma("unroll") for (int n = 0; n < 2; ++n) _Pragma("unroll") for (int k = 0; k < 2; ++k) dst[n][k] = *(const LAS bf16x8*)(lds + PG8_SB(b, h) + boff + n * 2048 + k * 1024); } while (0)
; #define PG8_MMA(ai, bj, At, Bt) do { __builtin_amdgcn_s_setprio(1); _Pragma("unroll") for (int m = 0; m < 4; ++m) _Pragma("unroll") for (int n = 0; n < 2; ++n) _Pragma("unroll") for (int k = 0; k < 2; ++k) \
;         acc[ai][bj][m][n] = __builtin_amdgcn_mfma_f32_16x16x32_bf16(Bt[n][k], At[m][k], acc[ai][bj][m][n], 0, 0, 0); __builtin_amdgcn_s_setprio(0); } while (0)
; #define PG8_WAIT_V(n) asm volatile("s_waitcnt vmcnt(" #n ")" ::: "memory")
; #define PG8_WAIT_L(n) asm volatile("s_waitcnt lgkmcnt(" #n ")" ::: "memory")
; #define PG8_BAR __builtin_amdgcn_s_barrier()
; #define PG8_SCHED __builtin_amdgcn_sched_barrier(0)
; template <class Epi, class Sched, bool ALIGN_EPI>
; __device__ __forceinline__ void gemm_phase(LAS unsigned char* lds, const Gemm g, const Sched& S, const Epi& E, int wave_id) {
;     ...
;             PG8_WAIT_V(8); PG8_WAIT_L(0); PG8_BAR; PG8_MMA(1, 0, At, B0); PG8_MMA(1, 1, At, B1); PG8_BAR; PG8_SCHED;
;             PG8_LDB(B0, 1, 0); PG8_LDB(B1, 1, 1); PG8_SCHED; PG8_LDA(At, 1, 0); PG8_STAGE(PG8_SA(0, 1), a2 + hsA, voffA);
;             PG8_WAIT_V(8); PG8_WAIT_L(0); PG8_BAR; PG8_MMA(0, 0, At, B0); PG8_MMA(0, 1, At, B1); PG8_BAR; PG8_SCHED;
	v_mfma_f32_16x16x32_bf16 v[62:65], v[130:133], v[162:165], v[62:65]
	v_mfma_f32_16x16x32_bf16 v[58:61], v[138:141], v[162:165], v[58:61]
	v_mfma_f32_16x16x32_bf16 v[50:53], v[130:133], v[170:173], v[50:53]
	v_mfma_f32_16x16x32_bf16 v[42:45], v[138:141], v[170:173], v[42:45]
	v_mfma_f32_16x16x32_bf16 v[34:37], v[130:133], v[188:191], v[34:37]
	v_mfma_f32_16x16x32_bf16 v[26:29], v[138:141], v[188:191], v[26:29]
	v_mfma_f32_16x16x32_bf16 v[18:21], v[130:133], v[200:203], v[18:21]
	v_mfma_f32_16x16x32_bf16 v[10:13], v[138:141], v[200:203], v[10:13]
	v_mfma_f32_16x16x32_bf16 v[62:65], v[134:137], v[166:169], v[62:65]
	v_mfma_f32_16x16x32_bf16 v[58:61], v[142:145], v[166:169], v[58:61]
	v_mfma_f32_16x16x32_bf16 v[50:53], v[134:137], v[184:187], v[50:53]
	v_mfma_f32_16x16x32_bf16 v[42:45], v[142:145], v[184:187], v[42:45]
	v_mfma_f32_16x16x32_bf16 v[34:37], v[134:137], v[192:195], v[34:37]
	v_mfma_f32_16x16x32_bf16 v[26:29], v[142:145], v[192:195], v[26:29]
	v_mfma_f32_16x16x32_bf16 v[18:21], v[134:137], v[204:207], v[18:21]
	v_mfma_f32_16x16x32_bf16 v[10:13], v[142:145], v[204:207], v[10:13]
	s_setprio 0
	s_setprio 1
	v_mfma_f32_16x16x32_bf16 v[54:57], v[146:149], v[162:165], v[54:57]
	v_mfma_f32_16x16x32_bf16 v[46:49], v[154:157], v[162:165], v[46:49]
	v_mfma_f32_16x16x32_bf16 v[38:41], v[146:149], v[170:173], v[38:41]
	v_mfma_f32_16x16x32_bf16 v[30:33], v[154:157], v[170:173], v[30:33]
	v_mfma_f32_16x16x32_bf16 v[22:25], v[146:149], v[188:191], v[22:25]
	v_mfma_f32_16x16x32_bf16 v[14:17], v[154:157], v[188:191], v[14:17]
	v_mfma_f32_16x16x32_bf16 v[6:9], v[146:149], v[200:203], v[6:9]
	v_mfma_f32_16x16x32_bf16 v[2:5], v[154:157], v[200:203], v[2:5]
	v_mfma_f32_16x16x32_bf16 v[54:57], v[150:153], v[166:169], v[54:57]
	v_mfma_f32_16x16x32_bf16 v[46:49], v[158:161], v[166:169], v[46:49]
	v_mfma_f32_16x16x32_bf16 v[38:41], v[150:153], v[184:187], v[38:41]
	v_mfma_f32_16x16x32_bf16 v[30:33], v[158:161], v[184:187], v[30:33]
	v_mfma_f32_16x16x32_bf16 v[22:25], v[150:153], v[192:195], v[22:25]
	v_mfma_f32_16x16x32_bf16 v[14:17], v[158:161], v[192:195], v[14:17]
	v_mfma_f32_16x16x32_bf16 v[6:9], v[150:153], v[204:207], v[6:9]
	v_mfma_f32_16x16x32_bf16 v[2:5], v[158:161], v[204:207], v[2:5]
	s_setprio 0
	s_barrier
	s_add_u32 s44, s44, 0x40000
	s_addc_u32 s45, s45, 0
	s_mov_b32 m0, s54
	v_lshl_add_u64 v[214:215], s[44:45], 0, v[174:175]
	global_load_lds_dwordx4 v[214:215], off
	v_lshl_add_u64 v[214:215], s[44:45], 0, v[176:177]
	s_mov_b32 m0, s55
	s_nop 0
	global_load_lds_dwordx4 v[214:215], off
	v_add_u32_e32 v142, 0x18400, v199
	v_add_u32_e32 v158, 0x1c400, v199
	ds_read_b128 v[130:133], v142
	ds_read_b128 v[134:137], v142 offset:1024
	ds_read_b128 v[138:141], v142 offset:2048
	ds_read_b128 v[142:145], v142 offset:3072
	ds_read_b128 v[146:149], v158
	ds_read_b128 v[150:153], v158 offset:1024
	ds_read_b128 v[154:157], v158 offset:2048
	ds_read_b128 v[158:161], v158 offset:3072
	ds_read_b128 v[162:165], v198 offset:33792
	ds_read_b128 v[166:169], v198 offset:34816
	ds_read_b128 v[170:173], v198 offset:35840
	ds_read_b128 v[184:187], v198 offset:36864
	ds_read_b128 v[188:191], v198 offset:37888
	ds_read_b128 v[192:195], v198 offset:38912
	ds_read_b128 v[200:203], v198 offset:39936
	ds_read_b128 v[204:207], v198 offset:40960
	s_setprio 1
	s_waitcnt vmcnt(8) lgkmcnt(0)
	s_barrier
	v_mfma_f32_16x16x32_bf16 v[126:129], v[130:133], v[162:165], v[126:129]
	v_mfma_f32_16x16x32_bf16 v[122:125], v[138:141], v[162:165], v[122:125]
	v_mfma_f32_16x16x32_bf16 v[114:117], v[130:133], v[170:173], v[114:117]
	v_mfma_f32_16x16x32_bf16 v[106:109], v[138:141], v[170:173], v[106:109]
	v_mfma_f32_16x16x32_bf16 v[98:101], v[130:133], v[188:191], v[98:101]
	v_mfma_f32_16x16x32_bf16 v[90:93], v[138:141], v[188:191], v[90:93]
	v_mfma_f32_16x16x32_bf16 v[82:85], v[130:133], v[200:203], v[82:85]
	v_mfma_f32_16x16x32_bf16 v[74:77], v[138:141], v[200:203], v[74:77]
	v_mfma_f32_16x16x32_bf16 v[126:129], v[134:137], v[166:169], v[126:129]
	v_mfma_f32_16x16x32_bf16 v[122:125], v[142:145], v[166:169], v[122:125]
	v_mfma_f32_16x16x32_bf16 v[114:117], v[134:137], v[184:187], v[114:117]
	v_mfma_f32_16x16x32_bf16 v[106:109], v[142:145], v[184:187], v[106:109]
	v_mfma_f32_16x16x32_bf16 v[98:101], v[134:137], v[192:195], v[98:101]
	v_mfma_f32_16x16x32_bf16 v[90:93], v[142:145], v[192:195], v[90:93]
	v_mfma_f32_16x16x32_bf16 v[82:85], v[134:137], v[204:207], v[82:85]
	v_mfma_f32_16x16x32_bf16 v[74:77], v[142:145], v[204:207], v[74:77]
	s_setprio 0
	s_setprio 1
	v_mfma_f32_16x16x32_bf16 v[118:121], v[146:149], v[162:165], v[118:121]
	v_mfma_f32_16x16x32_bf16 v[110:113], v[154:157], v[162:165], v[110:113]
	v_mfma_f32_16x16x32_bf16 v[102:105], v[146:149], v[170:173], v[102:105]
	v_mfma_f32_16x16x32_bf16 v[94:97], v[154:157], v[170:173], v[94:97]
	v_mfma_f32_16x16x32_bf16 v[86:89], v[146:149], v[188:191], v[86:89]
	v_mfma_f32_16x16x32_bf16 v[78:81], v[154:157], v[188:191], v[78:81]
	v_mfma_f32_16x16x32_bf16 v[70:73], v[146:149], v[200:203], v[70:73]
	v_mfma_f32_16x16x32_bf16 v[66:69], v[154:157], v[200:203], v[66:69]
	v_mfma_f32_16x16x32_bf16 v[118:121], v[150:153], v[166:169], v[118:121]
	v_mfma_f32_16x16x32_bf16 v[110:113], v[158:161], v[166:169], v[110:113]
	v_mfma_f32_16x16x32_bf16 v[102:105], v[150:153], v[184:187], v[102:105]
	v_mfma_f32_16x16x32_bf16 v[94:97], v[158:161], v[184:187], v[94:97]
	v_mfma_f32_16x16x32_bf16 v[86:89], v[150:153], v[192:195], v[86:89]
	v_mfma_f32_16x16x32_bf16 v[78:81], v[158:161], v[192:195], v[78:81]
	v_mfma_f32_16x16x32_bf16 v[70:73], v[150:153], v[204:207], v[70:73]
	v_mfma_f32_16x16x32_bf16 v[66:69], v[158:161], v[204:207], v[66:69]
	s_setprio 0
	s_barrier
; #define PG8_STAGE(bufoff, gbase, voff) do { _Pragma("unroll") for (int _i = 0; _i < 2; ++_i) \
;         __builtin_amdgcn_global_load_lds((const GAS unsigned*)((const GAS char*)(gbase) + (voff)[_i]), (LAS unsigned*)(lds + (bufoff) + ldsw + _i * 8192), 16, 0, 0); } while (0)
; #define PG8_LDA(dst, b, h) do { _Pragma("unroll") for (int m = 0; m < 4; ++m) _Pragma("unroll") for (int k = 0; k < 2; ++k) dst[m][k] = *(const LAS bf16x8*)(lds + PG8_SA(b, h) + aoff + m * 2048 + k * 1024); } while (0)
; #define PG8_MMA(ai, bj, At, Bt) do { __builtin_amdgcn_s_setprio(1); _Pragma("unroll") for (int m = 0; m < 4; ++m) _Pragma("unroll") for (int n = 0; n < 2; ++n) _Pragma("unroll") for (int k = 0; k < 2; ++k) \
;         acc[ai][bj][m][n] = __builtin_amdgcn_mfma_f32_16x16x32_bf16(Bt[n][k], At[m][k], acc[ai][bj][m][n], 0, 0, 0); __builtin_amdgcn_s_setprio(0); } while (0)
; #define PG8_WAIT_V(n) asm volatile("s_waitcnt vmcnt(" #n ")" ::: "memory")
; #define PG8_WAIT_L(n) asm volatile("s_waitcnt lgkmcnt(" #n ")" ::: "memory")
; #define PG8_BAR __builtin_amdgcn_s_barrier()
; #define PG8_SCHED __builtin_amdgcn_sched_barrier(0)
; template <class Epi, class Sched, bool ALIGN_EPI>
; __device__ __forceinline__ void gemm_phase(LAS unsigned char* lds, const Gemm g, const Sched& S, const Epi& E, int wave_id) {
;     ...
;             PG8_LDA(At, 1, 1); PG8_STAGE(PG8_SB(1, 0), b3, voffB); PG8_STAGE(PG8_SB(1, 1), b3 + hsB, voffB); PG8_STAGE(PG8_SA(1, 0), a3, voffA);
;             PG8_WAIT_V(8); PG8_WAIT_L(0); PG8_BAR; PG8_MMA(1, 0, At, B0); PG8_MMA(1, 1, At, B1); PG8_BAR; PG8_SCHED;
;         }
	s_mov_b32 m0, s58
	v_lshl_add_u64 v[196:197], v[196:197], 0, s[92:93]
	s_add_u32 s42, s42, 0x40080
	global_load_lds_dwordx4 v[196:197], off
	v_lshl_add_u64 v[196:197], v[208:209], 0, s[92:93]
	s_mov_b32 m0, s59
	s_addc_u32 s43, s43, 0
	global_load_lds_dwordx4 v[196:197], off
	v_lshl_add_u64 v[196:197], s[42:43], 0, v[0:1]
	s_mov_b32 m0, s62
	s_nop 0
	global_load_lds_dwordx4 v[196:197], off
	v_lshl_add_u64 v[196:197], s[42:43], 0, v[178:179]
	s_mov_b32 m0, s63
	s_nop 0
	global_load_lds_dwordx4 v[196:197], off
	v_lshl_add_u64 v[196:197], v[210:211], 0, s[92:93]
	s_mov_b32 m0, s60
	s_nop 0
	global_load_lds_dwordx4 v[196:197], off
	v_lshl_add_u64 v[196:197], v[212:213], 0, s[92:93]
	s_mov_b32 m0, s61
	s_nop 0
	global_load_lds_dwordx4 v[196:197], off
	ds_read_b128 v[162:165], v198 offset:50176
	ds_read_b128 v[166:169], v198 offset:51200
	ds_read_b128 v[170:173], v198 offset:52224
	ds_read_b128 v[184:187], v198 offset:53248
	ds_read_b128 v[188:191], v198 offset:54272
	ds_read_b128 v[192:195], v198 offset:55296
	ds_read_b128 v[200:203], v198 offset:56320
	ds_read_b128 v[204:207], v198 offset:57344
	s_setprio 1
	s_waitcnt vmcnt(8) lgkmcnt(0)
	s_barrier
	v_mfma_f32_16x16x32_bf16 v[62:65], v[130:133], v[162:165], v[62:65]
	v_mfma_f32_16x16x32_bf16 v[58:61], v[138:141], v[162:165], v[58:61]
	v_mfma_f32_16x16x32_bf16 v[50:53], v[130:133], v[170:173], v[50:53]
	v_mfma_f32_16x16x32_bf16 v[42:45], v[138:141], v[170:173], v[42:45]
	v_mfma_f32_16x16x32_bf16 v[34:37], v[130:133], v[188:191], v[34:37]
	v_mfma_f32_16x16x32_bf16 v[26:29], v[138:141], v[188:191], v[26:29]
	v_mfma_f32_16x16x32_bf16 v[18:21], v[130:133], v[200:203], v[18:21]
	v_mfma_f32_16x16x32_bf16 v[10:13], v[138:141], v[200:203], v[10:13]
	v_mfma_f32_16x16x32_bf16 v[62:65], v[134:137], v[166:169], v[62:65]
	v_mfma_f32_16x16x32_bf16 v[58:61], v[142:145], v[166:169], v[58:61]
	v_mfma_f32_16x16x32_bf16 v[50:53], v[134:137], v[184:187], v[50:53]
	v_mfma_f32_16x16x32_bf16 v[42:45], v[142:145], v[184:187], v[42:45]
	v_mfma_f32_16x16x32_bf16 v[34:37], v[134:137], v[192:195], v[34:37]
	v_mfma_f32_16x16x32_bf16 v[26:29], v[142:145], v[192:195], v[26:29]
	v_mfma_f32_16x16x32_bf16 v[18:21], v[134:137], v[204:207], v[18:21]
	v_mfma_f32_16x16x32_bf16 v[10:13], v[142:145], v[204:207], v[10:13]
	s_setprio 0
	s_setprio 1
	v_mfma_f32_16x16x32_bf16 v[54:57], v[146:149], v[162:165], v[54:57]
	v_mfma_f32_16x16x32_bf16 v[46:49], v[154:157], v[162:165], v[46:49]
	v_mfma_f32_16x16x32_bf16 v[38:41], v[146:149], v[170:173], v[38:41]
	v_mfma_f32_16x16x32_bf16 v[30:33], v[154:157], v[170:173], v[30:33]
	v_mfma_f32_16x16x32_bf16 v[22:25], v[146:149], v[188:191], v[22:25]
	v_mfma_f32_16x16x32_bf16 v[14:17], v[154:157], v[188:191], v[14:17]
	v_mfma_f32_16x16x32_bf16 v[6:9], v[146:149], v[200:203], v[6:9]
	v_mfma_f32_16x16x32_bf16 v[2:5], v[154:157], v[200:203], v[2:5]
	v_mfma_f32_16x16x32_bf16 v[54:57], v[150:153], v[166:169], v[54:57]
	v_mfma_f32_16x16x32_bf16 v[46:49], v[158:161], v[166:169], v[46:49]
	v_mfma_f32_16x16x32_bf16 v[38:41], v[150:153], v[184:187], v[38:41]
	v_mfma_f32_16x16x32_bf16 v[30:33], v[158:161], v[184:187], v[30:33]
	v_mfma_f32_16x16x32_bf16 v[22:25], v[150:153], v[192:195], v[22:25]
	v_mfma_f32_16x16x32_bf16 v[14:17], v[158:161], v[192:195], v[14:17]
	v_mfma_f32_16x16x32_bf16 v[6:9], v[150:153], v[204:207], v[6:9]
	v_mfma_f32_16x16x32_bf16 v[2:5], v[158:161], v[204:207], v[2:5]
	s_setprio 0
	s_barrier
	s_add_i32 s67, s67, 2
	s_add_u32 s39, s39, 0x100
	s_addc_u32 s66, s66, 0
	s_add_u32 s40, s40, 0x100
	s_addc_u32 s41, s41, 0
	s_cmp_gt_u32 s67, 13
	s_cbranch_scc0 .LBB0_1837
	s_and_b64 vcc, exec, s[22:23]
	s_cbranch_vccz .LBB0_1840
	s_barrier

; #define GAS __attribute__((address_space(1)))
; #define PG8_STAGE(bufoff, gbase, voff) do { _Pragma("unroll") for (int _i = 0; _i < 2; ++_i) \
;         __builtin_amdgcn_global_load_lds((const GAS unsigned*)((const GAS char*)(gbase) + (voff)[_i]), (LAS unsigned*)(lds + (bufoff) + ldsw + _i * 8192), 16, 0, 0); } while (0)
; #define PG8_LDA(dst, b, h) do { _Pragma("unroll") for (int m = 0; m < 4; ++m) _Pragma("unroll") for (int k = 0; k < 2; ++k) dst[m][k] = *(const LAS bf16x8*)(lds + PG8_SA(b, h) + aoff + m * 2048 + k * 1024); } while (0)
; #define PG8_LDB(dst, b, h) do { _Pragma("unroll") for (int n = 0; n < 2; ++n) _Pragma("unroll") for (int k = 0; k < 2; ++k) dst[n][k] = *(const LAS bf16x8*)(lds + PG8_SB(b, h) + boff + n * 2048 + k * 1024); } while (0)
; #define PG8_MMA(ai, bj, At, Bt) do { __builtin_amdgcn_s_setprio(1); _Pragma("unroll") for (int m = 0; m < 4; ++m) _Pragma("unroll") for (int n = 0; n < 2; ++n) _Pragma("unroll") for (int k = 0; k < 2; ++k) \
;         acc[ai][bj][m][n] = __builtin_amdgcn_mfma_f32_16x16x32_bf16(Bt[n][k], At[m][k], acc[ai][bj][m][n], 0, 0, 0); __builtin_amdgcn_s_setprio(0); } while (0)
; #define PG8_WAIT_V(n) asm volatile("s_waitcnt vmcnt(" #n ")" ::: "memory")
; #define PG8_WAIT_L(n) asm volatile("s_waitcnt lgkmcnt(" #n ")" ::: "memory")
; #define PG8_BAR __builtin_amdgcn_s_barrier()
; template <class Epi, class Sched, bool ALIGN_EPI>
; __device__ __forceinline__ void gemm_phase(LAS unsigned char* lds, const Gemm g, const Sched& S, const Epi& E, int wave_id) {
;     ...
;             const bool last = (t == nt - 2);
;             const GAS char* a1 = cA + (size_t)(t + 1) * kstep;
;             const GAS char* a2 = last ? nA : cA + (size_t)(t + 2) * kstep; const GAS char* b2 = last ? nB : cB + (size_t)(t + 2) * kstep;
;             const GAS char* a3 = a2 + kstep; const GAS char* b3 = b2 + kstep;
;             PG8_LDB(B0, 0, 0); PG8_LDB(B1, 0, 1); PG8_SCHED; PG8_LDA(At, 0, 0); PG8_STAGE(PG8_SA(1, 1), a1 + hsA, voffA);
;             PG8_WAIT_V(8); PG8_WAIT_L(0); PG8_BAR; PG8_MMA(0, 0, At, B0); PG8_MMA(0, 1, At, B1); PG8_BAR; PG8_SCHED;
;             PG8_LDA(At, 0, 1); PG8_STAGE(PG8_SB(0, 0), b2, voffB); PG8_STAGE(PG8_SB(0, 1), b2 + hsB, voffB); PG8_STAGE(PG8_SA(0, 0), a2, voffA);
;             PG8_WAIT_V(8); PG8_WAIT_L(0); PG8_BAR; PG8_MMA(1, 0, At, B0); PG8_MMA(1, 1, At, B1); PG8_BAR; PG8_SCHED;
.LBB0_2565:
	s_add_u32 s28, s26, 0xfffc0080
	s_addc_u32 s29, s27, -1
	s_cmp_eq_u32 s60, 12
	s_cselect_b32 s31, s19, s29
	s_cselect_b32 s30, s33, s28
	s_cselect_b32 s29, s17, s59
	s_cselect_b32 s28, s57, s58
	v_lshl_add_u64 v[206:207], s[26:27], 0, v[138:139]
	s_add_i32 m0, s40, 0xc400
	s_nop 0
	global_load_lds_dwordx4 v[206:207], off
	v_lshl_add_u64 v[206:207], s[26:27], 0, v[136:137]
	s_add_i32 m0, s40, 0xe400
	s_nop 0
	global_load_lds_dwordx4 v[206:207], off
	v_add_u32_e32 v154, 0x10400, v153
	v_add_u32_e32 v170, 0x14400, v153
	ds_read_b128 v[140:143], v154
	ds_read_b128 v[144:147], v154 offset:1024
	ds_read_b128 v[148:151], v154 offset:2048
	ds_read_b128 v[154:157], v154 offset:3072
	ds_read_b128 v[158:161], v170
	ds_read_b128 v[162:165], v170 offset:1024
	ds_read_b128 v[166:169], v170 offset:2048
	ds_read_b128 v[170:173], v170 offset:3072
	ds_read_b128 v[174:177], v152 offset:1024
	ds_read_b128 v[178:181], v152 offset:2048
	ds_read_b128 v[182:185], v152 offset:3072
	ds_read_b128 v[186:189], v152 offset:4096
	ds_read_b128 v[190:193], v152 offset:5120
	ds_read_b128 v[194:197], v152 offset:6144
	ds_read_b128 v[198:201], v152 offset:7168
	ds_read_b128 v[202:205], v152 offset:8192
	s_setprio 1
	s_waitcnt vmcnt(8) lgkmcnt(0)
	s_barrier
	v_mfma_f32_16x16x32_bf16 v[126:129], v[140:143], v[174:177], v[126:129]
	v_mfma_f32_16x16x32_bf16 v[122:125], v[148:151], v[174:177], v[122:125]
	v_mfma_f32_16x16x32_bf16 v[110:113], v[140:143], v[182:185], v[110:113]
	v_mfma_f32_16x16x32_bf16 v[106:109], v[148:151], v[182:185], v[106:109]
	v_mfma_f32_16x16x32_bf16 v[94:97], v[140:143], v[190:193], v[94:97]
	v_mfma_f32_16x16x32_bf16 v[90:93], v[148:151], v[190:193], v[90:93]
	v_mfma_f32_16x16x32_bf16 v[78:81], v[140:143], v[198:201], v[78:81]
	v_mfma_f32_16x16x32_bf16 v[74:77], v[148:151], v[198:201], v[74:77]
	v_mfma_f32_16x16x32_bf16 v[126:129], v[144:147], v[178:181], v[126:129]
	v_mfma_f32_16x16x32_bf16 v[122:125], v[154:157], v[178:181], v[122:125]
	v_mfma_f32_16x16x32_bf16 v[110:113], v[144:147], v[186:189], v[110:113]
	v_mfma_f32_16x16x32_bf16 v[106:109], v[154:157], v[186:189], v[106:109]
	v_mfma_f32_16x16x32_bf16 v[94:97], v[144:147], v[194:197], v[94:97]
	v_mfma_f32_16x16x32_bf16 v[90:93], v[154:157], v[194:197], v[90:93]
	v_mfma_f32_16x16x32_bf16 v[78:81], v[144:147], v[202:205], v[78:81]
	v_mfma_f32_16x16x32_bf16 v[74:77], v[154:157], v[202:205], v[74:77]
	s_setprio 0
	s_setprio 1
	v_mfma_f32_16x16x32_bf16 v[118:121], v[158:161], v[174:177], v[118:121]
	v_mfma_f32_16x16x32_bf16 v[114:117], v[166:169], v[174:177], v[114:117]
	v_mfma_f32_16x16x32_bf16 v[102:105], v[158:161], v[182:185], v[102:105]
	v_mfma_f32_16x16x32_bf16 v[98:101], v[166:169], v[182:185], v[98:101]
	v_mfma_f32_16x16x32_bf16 v[86:89], v[158:161], v[190:193], v[86:89]
	v_mfma_f32_16x16x32_bf16 v[82:85], v[166:169], v[190:193], v[82:85]
	v_mfma_f32_16x16x32_bf16 v[70:73], v[158:161], v[198:201], v[70:73]
	v_mfma_f32_16x16x32_bf16 v[66:69], v[166:169], v[198:201], v[66:69]
	v_mfma_f32_16x16x32_bf16 v[118:121], v[162:165], v[178:181], v[118:121]
	v_mfma_f32_16x16x32_bf16 v[114:117], v[170:173], v[178:181], v[114:117]
	v_mfma_f32_16x16x32_bf16 v[102:105], v[162:165], v[186:189], v[102:105]
	v_mfma_f32_16x16x32_bf16 v[98:101], v[170:173], v[186:189], v[98:101]
	v_mfma_f32_16x16x32_bf16 v[86:89], v[162:165], v[194:197], v[86:89]
	v_mfma_f32_16x16x32_bf16 v[82:85], v[170:173], v[194:197], v[82:85]
	v_mfma_f32_16x16x32_bf16 v[70:73], v[162:165], v[202:205], v[70:73]
	v_mfma_f32_16x16x32_bf16 v[66:69], v[170:173], v[202:205], v[66:69]
	s_setprio 0
	s_barrier
	s_mov_b32 m0, s25
	v_lshl_add_u64 v[206:207], s[28:29], 0, v[0:1]
	s_add_u32 s62, s28, 0x40000
	global_load_lds_dwordx4 v[206:207], off
	v_lshl_add_u64 v[208:209], s[28:29], 0, v[130:131]
	s_mov_b32 m0, s41
	s_addc_u32 s63, s29, 0
	global_load_lds_dwordx4 v[208:209], off
	v_lshl_add_u64 v[210:211], s[62:63], 0, v[0:1]
	s_mov_b32 m0, s42
	v_lshl_add_u64 v[212:213], s[30:31], 0, v[132:133]
	global_load_lds_dwordx4 v[210:211], off
	v_lshl_add_u64 v[210:211], s[62:63], 0, v[130:131]
	s_mov_b32 m0, s43
	s_nop 0
	global_load_lds_dwordx4 v[210:211], off
	v_lshl_add_u64 v[210:211], s[30:31], 0, v[134:135]
	s_mov_b32 m0, s44
	s_nop 0
	global_load_lds_dwordx4 v[210:211], off
	s_mov_b32 m0, s45
	s_nop 0
	global_load_lds_dwordx4 v[212:213], off
	ds_read_b128 v[174:177], v152 offset:17408
	ds_read_b128 v[178:181], v152 offset:18432
	ds_read_b128 v[182:185], v152 offset:19456
	ds_read_b128 v[186:189], v152 offset:20480
	ds_read_b128 v[190:193], v152 offset:21504
	ds_read_b128 v[194:197], v152 offset:22528
	ds_read_b128 v[198:201], v152 offset:23552
	ds_read_b128 v[202:205], v152 offset:24576
	s_setprio 1
	s_waitcnt vmcnt(8) lgkmcnt(0)
	s_barrier
; #define PG8_STAGE(bufoff, gbase, voff) do { _Pragma("unroll") for (int _i = 0; _i < 2; ++_i) \
;         __builtin_amdgcn_global_load_lds((const GAS unsigned*)((const GAS char*)(gbase) + (voff)[_i]), (LAS unsigned*)(lds + (bufoff) + ldsw + _i * 8192), 16, 0, 0); } while (0)
; #define PG8_LDA(dst, b, h) do { _Pragma("unroll") for (int m = 0; m < 4; ++m) _Pragma("unroll") for (int k = 0; k < 2; ++k) dst[m][k] = *(const LAS bf16x8*)(lds + PG8_SA(b, h) + aoff + m * 2048 + k * 1024); } while (0)
; #define PG8_LDB(dst, b, h) do { _Pragma("unroll") for (int n = 0; n < 2; ++n) _Pragma("unroll") for (int k = 0; k < 2; ++k) dst[n][k] = *(const LAS bf16x8*)(lds + PG8_SB(b, h) + boff + n * 2048 + k * 1024); } while (0)
; #define PG8_MMA(ai, bj, At, Bt) do { __builtin_amdgcn_s_setprio(1); _Pragma("unroll") for (int m = 0; m < 4; ++m) _Pragma("unroll") for (int n = 0; n < 2; ++n) _Pragma("unroll") for (int k = 0; k < 2; ++k) \
;         acc[ai][bj][m][n] = __builtin_amdgcn_mfma_f32_16x16x32_bf16(Bt[n][k], At[m][k], acc[ai][bj][m][n], 0, 0, 0); __builtin_amdgcn_s_setprio(0); } while (0)
; #define PG8_WAIT_V(n) asm volatile("s_waitcnt vmcnt(" #n ")" ::: "memory")
; #define PG8_WAIT_L(n) asm volatile("s_waitcnt lgkmcnt(" #n ")" ::: "memory")
; #define PG8_BAR __builtin_amdgcn_s_barrier()
; #define PG8_SCHED __builtin_amdgcn_sched_barrier(0)
; template <class Epi, class Sched, bool ALIGN_EPI>
; __device__ __forceinline__ void gemm_phase(LAS unsigned char* lds, const Gemm g, const Sched& S, const Epi& E, int wave_id) {
;     ...
;             PG8_WAIT_V(8); PG8_WAIT_L(0); PG8_BAR; PG8_MMA(1, 0, At, B0); PG8_MMA(1, 1, At, B1); PG8_BAR; PG8_SCHED;
;             PG8_LDB(B0, 1, 0); PG8_LDB(B1, 1, 1); PG8_SCHED; PG8_LDA(At, 1, 0); PG8_STAGE(PG8_SA(0, 1), a2 + hsA, voffA);
;             PG8_WAIT_V(8); PG8_WAIT_L(0); PG8_BAR; PG8_MMA(0, 0, At, B0); PG8_MMA(0, 1, At, B1); PG8_BAR; PG8_SCHED;
	v_mfma_f32_16x16x32_bf16 v[62:65], v[140:143], v[174:177], v[62:65]
	v_mfma_f32_16x16x32_bf16 v[58:61], v[148:151], v[174:177], v[58:61]
	v_mfma_f32_16x16x32_bf16 v[46:49], v[140:143], v[182:185], v[46:49]
	v_mfma_f32_16x16x32_bf16 v[42:45], v[148:151], v[182:185], v[42:45]
	v_mfma_f32_16x16x32_bf16 v[30:33], v[140:143], v[190:193], v[30:33]
	v_mfma_f32_16x16x32_bf16 v[26:29], v[148:151], v[190:193], v[26:29]
	v_mfma_f32_16x16x32_bf16 v[14:17], v[140:143], v[198:201], v[14:17]
	v_mfma_f32_16x16x32_bf16 v[10:13], v[148:151], v[198:201], v[10:13]
	v_mfma_f32_16x16x32_bf16 v[62:65], v[144:147], v[178:181], v[62:65]
	v_mfma_f32_16x16x32_bf16 v[58:61], v[154:157], v[178:181], v[58:61]
	v_mfma_f32_16x16x32_bf16 v[46:49], v[144:147], v[186:189], v[46:49]
	v_mfma_f32_16x16x32_bf16 v[42:45], v[154:157], v[186:189], v[42:45]
	v_mfma_f32_16x16x32_bf16 v[30:33], v[144:147], v[194:197], v[30:33]
	v_mfma_f32_16x16x32_bf16 v[26:29], v[154:157], v[194:197], v[26:29]
	v_mfma_f32_16x16x32_bf16 v[14:17], v[144:147], v[202:205], v[14:17]
	v_mfma_f32_16x16x32_bf16 v[10:13], v[154:157], v[202:205], v[10:13]
	s_setprio 0
	s_setprio 1
	v_mfma_f32_16x16x32_bf16 v[54:57], v[158:161], v[174:177], v[54:57]
	v_mfma_f32_16x16x32_bf16 v[50:53], v[166:169], v[174:177], v[50:53]
	v_mfma_f32_16x16x32_bf16 v[38:41], v[158:161], v[182:185], v[38:41]
	v_mfma_f32_16x16x32_bf16 v[34:37], v[166:169], v[182:185], v[34:37]
	v_mfma_f32_16x16x32_bf16 v[22:25], v[158:161], v[190:193], v[22:25]
	v_mfma_f32_16x16x32_bf16 v[18:21], v[166:169], v[190:193], v[18:21]
	v_mfma_f32_16x16x32_bf16 v[6:9], v[158:161], v[198:201], v[6:9]
	v_mfma_f32_16x16x32_bf16 v[2:5], v[166:169], v[198:201], v[2:5]
	v_mfma_f32_16x16x32_bf16 v[54:57], v[162:165], v[178:181], v[54:57]
	v_mfma_f32_16x16x32_bf16 v[50:53], v[170:173], v[178:181], v[50:53]
	v_mfma_f32_16x16x32_bf16 v[38:41], v[162:165], v[186:189], v[38:41]
	v_mfma_f32_16x16x32_bf16 v[34:37], v[170:173], v[186:189], v[34:37]
	v_mfma_f32_16x16x32_bf16 v[22:25], v[162:165], v[194:197], v[22:25]
	v_mfma_f32_16x16x32_bf16 v[18:21], v[170:173], v[194:197], v[18:21]
	v_mfma_f32_16x16x32_bf16 v[6:9], v[162:165], v[202:205], v[6:9]
	v_mfma_f32_16x16x32_bf16 v[2:5], v[170:173], v[202:205], v[2:5]
	s_setprio 0
	s_barrier
	s_add_u32 s30, s30, 0x40000
	s_addc_u32 s31, s31, 0
	s_mov_b32 m0, s46
	v_lshl_add_u64 v[214:215], s[30:31], 0, v[134:135]
	global_load_lds_dwordx4 v[214:215], off
	v_lshl_add_u64 v[214:215], s[30:31], 0, v[132:133]
	s_mov_b32 m0, s47
	s_nop 0
	global_load_lds_dwordx4 v[214:215], off
	v_add_u32_e32 v154, 0x18400, v153
	v_add_u32_e32 v170, 0x1c400, v153
	ds_read_b128 v[140:143], v154
	ds_read_b128 v[144:147], v154 offset:1024
	ds_read_b128 v[148:151], v154 offset:2048
	ds_read_b128 v[154:157], v154 offset:3072
	ds_read_b128 v[158:161], v170
	ds_read_b128 v[162:165], v170 offset:1024
	ds_read_b128 v[166:169], v170 offset:2048
	ds_read_b128 v[170:173], v170 offset:3072
	ds_read_b128 v[174:177], v152 offset:33792
	ds_read_b128 v[178:181], v152 offset:34816
	ds_read_b128 v[182:185], v152 offset:35840
	ds_read_b128 v[186:189], v152 offset:36864
	ds_read_b128 v[190:193], v152 offset:37888
	ds_read_b128 v[194:197], v152 offset:38912
	ds_read_b128 v[198:201], v152 offset:39936
	ds_read_b128 v[202:205], v152 offset:40960
	s_setprio 1
	s_waitcnt vmcnt(8) lgkmcnt(0)
	s_barrier
	v_mfma_f32_16x16x32_bf16 v[126:129], v[140:143], v[174:177], v[126:129]
	v_mfma_f32_16x16x32_bf16 v[122:125], v[148:151], v[174:177], v[122:125]
	v_mfma_f32_16x16x32_bf16 v[110:113], v[140:143], v[182:185], v[110:113]
	v_mfma_f32_16x16x32_bf16 v[106:109], v[148:151], v[182:185], v[106:109]
	v_mfma_f32_16x16x32_bf16 v[94:97], v[140:143], v[190:193], v[94:97]
	v_mfma_f32_16x16x32_bf16 v[90:93], v[148:151], v[190:193], v[90:93]
	v_mfma_f32_16x16x32_bf16 v[78:81], v[140:143], v[198:201], v[78:81]
	v_mfma_f32_16x16x32_bf16 v[74:77], v[148:151], v[198:201], v[74:77]
	v_mfma_f32_16x16x32_bf16 v[126:129], v[144:147], v[178:181], v[126:129]
	v_mfma_f32_16x16x32_bf16 v[122:125], v[154:157], v[178:181], v[122:125]
	v_mfma_f32_16x16x32_bf16 v[110:113], v[144:147], v[186:189], v[110:113]
	v_mfma_f32_16x16x32_bf16 v[106:109], v[154:157], v[186:189], v[106:109]
	v_mfma_f32_16x16x32_bf16 v[94:97], v[144:147], v[194:197], v[94:97]
	v_mfma_f32_16x16x32_bf16 v[90:93], v[154:157], v[194:197], v[90:93]
	v_mfma_f32_16x16x32_bf16 v[78:81], v[144:147], v[202:205], v[78:81]
	v_mfma_f32_16x16x32_bf16 v[74:77], v[154:157], v[202:205], v[74:77]
	s_setprio 0
	s_setprio 1
	v_mfma_f32_16x16x32_bf16 v[118:121], v[158:161], v[174:177], v[118:121]
	v_mfma_f32_16x16x32_bf16 v[114:117], v[166:169], v[174:177], v[114:117]
	v_mfma_f32_16x16x32_bf16 v[102:105], v[158:161], v[182:185], v[102:105]
	v_mfma_f32_16x16x32_bf16 v[98:101], v[166:169], v[182:185], v[98:101]
	v_mfma_f32_16x16x32_bf16 v[86:89], v[158:161], v[190:193], v[86:89]
	v_mfma_f32_16x16x32_bf16 v[82:85], v[166:169], v[190:193], v[82:85]
	v_mfma_f32_16x16x32_bf16 v[70:73], v[158:161], v[198:201], v[70:73]
	v_mfma_f32_16x16x32_bf16 v[66:69], v[166:169], v[198:201], v[66:69]
	v_mfma_f32_16x16x32_bf16 v[118:121], v[162:165], v[178:181], v[118:121]
	v_mfma_f32_16x16x32_bf16 v[114:117], v[170:173], v[178:181], v[114:117]
	v_mfma_f32_16x16x32_bf16 v[102:105], v[162:165], v[186:189], v[102:105]
	v_mfma_f32_16x16x32_bf16 v[98:101], v[170:173], v[186:189], v[98:101]
	v_mfma_f32_16x16x32_bf16 v[86:89], v[162:165], v[194:197], v[86:89]
	v_mfma_f32_16x16x32_bf16 v[82:85], v[170:173], v[194:197], v[82:85]
	v_mfma_f32_16x16x32_bf16 v[70:73], v[162:165], v[202:205], v[70:73]
	v_mfma_f32_16x16x32_bf16 v[66:69], v[170:173], v[202:205], v[66:69]
	s_setprio 0
	s_barrier
; #define PG8_STAGE(bufoff, gbase, voff) do { _Pragma("unroll") for (int _i = 0; _i < 2; ++_i) \
;         __builtin_amdgcn_global_load_lds((const GAS unsigned*)((const GAS char*)(gbase) + (voff)[_i]), (LAS unsigned*)(lds + (bufoff) + ldsw + _i * 8192), 16, 0, 0); } while (0)
; #define PG8_LDA(dst, b, h) do { _Pragma("unroll") for (int m = 0; m < 4; ++m) _Pragma("unroll") for (int k = 0; k < 2; ++k) dst[m][k] = *(const LAS bf16x8*)(lds + PG8_SA(b, h) + aoff + m * 2048 + k * 1024); } while (0)
; #define PG8_MMA(ai, bj, At, Bt) do { __builtin_amdgcn_s_setprio(1); _Pragma("unroll") for (int m = 0; m < 4; ++m) _Pragma("unroll") for (int n = 0; n < 2; ++n) _Pragma("unroll") for (int k = 0; k < 2; ++k) \
;         acc[ai][bj][m][n] = __builtin_amdgcn_mfma_f32_16x16x32_bf16(Bt[n][k], At[m][k], acc[ai][bj][m][n], 0, 0, 0); __builtin_amdgcn_s_setprio(0); } while (0)
; #define PG8_WAIT_V(n) asm volatile("s_waitcnt vmcnt(" #n ")" ::: "memory")
; #define PG8_WAIT_L(n) asm volatile("s_waitcnt lgkmcnt(" #n ")" ::: "memory")
; #define PG8_BAR __builtin_amdgcn_s_barrier()
; #define PG8_SCHED __builtin_amdgcn_sched_barrier(0)
; template <class Epi, class Sched, bool ALIGN_EPI>
; __device__ __forceinline__ void gemm_phase(LAS unsigned char* lds, const Gemm g, const Sched& S, const Epi& E, int wave_id) {
;     ...
;             PG8_LDA(At, 1, 1); PG8_STAGE(PG8_SB(1, 0), b3, voffB); PG8_STAGE(PG8_SB(1, 1), b3 + hsB, voffB); PG8_STAGE(PG8_SA(1, 0), a3, voffA);
;             PG8_WAIT_V(8); PG8_WAIT_L(0); PG8_BAR; PG8_MMA(1, 0, At, B0); PG8_MMA(1, 1, At, B1); PG8_BAR; PG8_SCHED;
;         }
	s_mov_b32 m0, s50
	v_lshl_add_u64 v[206:207], v[206:207], 0, s[92:93]
	s_add_u32 s28, s28, 0x40080
	global_load_lds_dwordx4 v[206:207], off
	v_lshl_add_u64 v[206:207], v[208:209], 0, s[92:93]
	s_mov_b32 m0, s51
	s_addc_u32 s29, s29, 0
	global_load_lds_dwordx4 v[206:207], off
	v_lshl_add_u64 v[206:207], s[28:29], 0, v[0:1]
	s_mov_b32 m0, s54
	s_nop 0
	global_load_lds_dwordx4 v[206:207], off
	v_lshl_add_u64 v[206:207], s[28:29], 0, v[130:131]
	s_mov_b32 m0, s55
	s_nop 0
	global_load_lds_dwordx4 v[206:207], off
	v_lshl_add_u64 v[206:207], v[210:211], 0, s[92:93]
	s_mov_b32 m0, s52
	s_nop 0
	global_load_lds_dwordx4 v[206:207], off
	v_lshl_add_u64 v[206:207], v[212:213], 0, s[92:93]
	s_mov_b32 m0, s53
	s_nop 0
	global_load_lds_dwordx4 v[206:207], off
	ds_read_b128 v[174:177], v152 offset:50176
	ds_read_b128 v[178:181], v152 offset:51200
	ds_read_b128 v[182:185], v152 offset:52224
	ds_read_b128 v[186:189], v152 offset:53248
	ds_read_b128 v[190:193], v152 offset:54272
	ds_read_b128 v[194:197], v152 offset:55296
	ds_read_b128 v[198:201], v152 offset:56320
	ds_read_b128 v[202:205], v152 offset:57344
	s_setprio 1
	s_waitcnt vmcnt(8) lgkmcnt(0)
	s_barrier
	v_mfma_f32_16x16x32_bf16 v[62:65], v[140:143], v[174:177], v[62:65]
	v_mfma_f32_16x16x32_bf16 v[58:61], v[148:151], v[174:177], v[58:61]
	v_mfma_f32_16x16x32_bf16 v[46:49], v[140:143], v[182:185], v[46:49]
	v_mfma_f32_16x16x32_bf16 v[42:45], v[148:151], v[182:185], v[42:45]
	v_mfma_f32_16x16x32_bf16 v[30:33], v[140:143], v[190:193], v[30:33]
	v_mfma_f32_16x16x32_bf16 v[26:29], v[148:151], v[190:193], v[26:29]
	v_mfma_f32_16x16x32_bf16 v[14:17], v[140:143], v[198:201], v[14:17]
	v_mfma_f32_16x16x32_bf16 v[10:13], v[148:151], v[198:201], v[10:13]
	v_mfma_f32_16x16x32_bf16 v[62:65], v[144:147], v[178:181], v[62:65]
	v_mfma_f32_16x16x32_bf16 v[58:61], v[154:157], v[178:181], v[58:61]
	v_mfma_f32_16x16x32_bf16 v[46:49], v[144:147], v[186:189], v[46:49]
	v_mfma_f32_16x16x32_bf16 v[42:45], v[154:157], v[186:189], v[42:45]
	v_mfma_f32_16x16x32_bf16 v[30:33], v[144:147], v[194:197], v[30:33]
	v_mfma_f32_16x16x32_bf16 v[26:29], v[154:157], v[194:197], v[26:29]
	v_mfma_f32_16x16x32_bf16 v[14:17], v[144:147], v[202:205], v[14:17]
	v_mfma_f32_16x16x32_bf16 v[10:13], v[154:157], v[202:205], v[10:13]
	s_setprio 0
	s_setprio 1
	v_mfma_f32_16x16x32_bf16 v[54:57], v[158:161], v[174:177], v[54:57]
	v_mfma_f32_16x16x32_bf16 v[50:53], v[166:169], v[174:177], v[50:53]
	v_mfma_f32_16x16x32_bf16 v[38:41], v[158:161], v[182:185], v[38:41]
	v_mfma_f32_16x16x32_bf16 v[34:37], v[166:169], v[182:185], v[34:37]
	v_mfma_f32_16x16x32_bf16 v[22:25], v[158:161], v[190:193], v[22:25]
	v_mfma_f32_16x16x32_bf16 v[18:21], v[166:169], v[190:193], v[18:21]
	v_mfma_f32_16x16x32_bf16 v[6:9], v[158:161], v[198:201], v[6:9]
	v_mfma_f32_16x16x32_bf16 v[2:5], v[166:169], v[198:201], v[2:5]
	v_mfma_f32_16x16x32_bf16 v[54:57], v[162:165], v[178:181], v[54:57]
	v_mfma_f32_16x16x32_bf16 v[50:53], v[170:173], v[178:181], v[50:53]
	v_mfma_f32_16x16x32_bf16 v[38:41], v[162:165], v[186:189], v[38:41]
	v_mfma_f32_16x16x32_bf16 v[34:37], v[170:173], v[186:189], v[34:37]
	v_mfma_f32_16x16x32_bf16 v[22:25], v[162:165], v[194:197], v[22:25]
	v_mfma_f32_16x16x32_bf16 v[18:21], v[170:173], v[194:197], v[18:21]
	v_mfma_f32_16x16x32_bf16 v[6:9], v[162:165], v[202:205], v[6:9]
	v_mfma_f32_16x16x32_bf16 v[2:5], v[170:173], v[202:205], v[2:5]
	s_setprio 0
	s_barrier
	s_add_i32 s60, s60, 2
	s_add_u32 s58, s58, 0x100
	s_addc_u32 s59, s59, 0
	s_add_u32 s26, s26, 0x100
	s_addc_u32 s27, s27, 0
	s_cmp_gt_u32 s60, 13
	s_cbranch_scc0 .LBB0_2565
	s_and_b64 vcc, exec, s[14:15]
	s_cbranch_vccz .LBB0_2568
	s_barrier

; #define GAS __attribute__((address_space(1)))
; #define PG8_STAGE(bufoff, gbase, voff) do { _Pragma("unroll") for (int _i = 0; _i < 2; ++_i) \
;         __builtin_amdgcn_global_load_lds((const GAS unsigned*)((const GAS char*)(gbase) + (voff)[_i]), (LAS unsigned*)(lds + (bufoff) + ldsw + _i * 8192), 16, 0, 0); } while (0)
; #define PG8_LDA(dst, b, h) do { _Pragma("unroll") for (int m = 0; m < 4; ++m) _Pragma("unroll") for (int k = 0; k < 2; ++k) dst[m][k] = *(const LAS bf16x8*)(lds + PG8_SA(b, h) + aoff + m * 2048 + k * 1024); } while (0)
; #define PG8_LDB(dst, b, h) do { _Pragma("unroll") for (int n = 0; n < 2; ++n) _Pragma("unroll") for (int k = 0; k < 2; ++k) dst[n][k] = *(const LAS bf16x8*)(lds + PG8_SB(b, h) + boff + n * 2048 + k * 1024); } while (0)
; #define PG8_MMA(ai, bj, At, Bt) do { __builtin_amdgcn_s_setprio(1); _Pragma("unroll") for (int m = 0; m < 4; ++m) _Pragma("unroll") for (int n = 0; n < 2; ++n) _Pragma("unroll") for (int k = 0; k < 2; ++k) \
;         acc[ai][bj][m][n] = __builtin_amdgcn_mfma_f32_16x16x32_bf16(Bt[n][k], At[m][k], acc[ai][bj][m][n], 0, 0, 0); __builtin_amdgcn_s_setprio(0); } while (0)
; #define PG8_WAIT_V(n) asm volatile("s_waitcnt vmcnt(" #n ")" ::: "memory")
; #define PG8_WAIT_L(n) asm volatile("s_waitcnt lgkmcnt(" #n ")" ::: "memory")
; #define PG8_BAR __builtin_amdgcn_s_barrier()
; template <class Epi, class Sched, bool ALIGN_EPI>
; __device__ __forceinline__ void gemm_phase(LAS unsigned char* lds, const Gemm g, const Sched& S, const Epi& E, int wave_id) {
;     ...
;             const bool last = (t == nt - 2);
;             const GAS char* a1 = cA + (size_t)(t + 1) * kstep;
;             const GAS char* a2 = last ? nA : cA + (size_t)(t + 2) * kstep; const GAS char* b2 = last ? nB : cB + (size_t)(t + 2) * kstep;
;             const GAS char* a3 = a2 + kstep; const GAS char* b3 = b2 + kstep;
;             PG8_LDB(B0, 0, 0); PG8_LDB(B1, 0, 1); PG8_SCHED; PG8_LDA(At, 0, 0); PG8_STAGE(PG8_SA(1, 1), a1 + hsA, voffA);
;             PG8_WAIT_V(8); PG8_WAIT_L(0); PG8_BAR; PG8_MMA(0, 0, At, B0); PG8_MMA(0, 1, At, B1); PG8_BAR; PG8_SCHED;
;             PG8_LDA(At, 0, 1); PG8_STAGE(PG8_SB(0, 0), b2, voffB); PG8_STAGE(PG8_SB(0, 1), b2 + hsB, voffB); PG8_STAGE(PG8_SA(0, 0), a2, voffA);
;             PG8_WAIT_V(8); PG8_WAIT_L(0); PG8_BAR; PG8_MMA(1, 0, At, B0); PG8_MMA(1, 1, At, B1); PG8_BAR; PG8_SCHED;
.LBB0_2620:
	s_add_u32 s38, s36, 0xfff80080
	s_addc_u32 s39, s37, -1
	s_cmp_eq_u32 s65, 28
	s_cselect_b32 s41, s1, s39
	s_cselect_b32 s40, s5, s38
	s_cselect_b32 s39, s7, s33
	s_cselect_b32 s38, s27, s29
	v_lshl_add_u64 v[194:195], s[36:37], 0, v[218:219]
	s_add_i32 m0, s43, 0xc400
	s_nop 0
	global_load_lds_dwordx4 v[194:195], off
	v_lshl_add_u64 v[194:195], s[36:37], 0, v[216:217]
	s_add_i32 m0, s43, 0xe400
	s_nop 0
	global_load_lds_dwordx4 v[194:195], off
	v_add_u32_e32 v46, 0x10400, v235
	v_add_u32_e32 v62, 0x14400, v235
	ds_read_b128 v[34:37], v46
	ds_read_b128 v[38:41], v46 offset:1024
	ds_read_b128 v[42:45], v46 offset:2048
	ds_read_b128 v[46:49], v46 offset:3072
	ds_read_b128 v[50:53], v62
	ds_read_b128 v[54:57], v62 offset:1024
	ds_read_b128 v[58:61], v62 offset:2048
	ds_read_b128 v[62:65], v62 offset:3072
	ds_read_b128 v[82:85], v234 offset:1024
	ds_read_b128 v[94:97], v234 offset:2048
	ds_read_b128 v[170:173], v234 offset:3072
	ds_read_b128 v[174:177], v234 offset:4096
	ds_read_b128 v[178:181], v234 offset:5120
	ds_read_b128 v[182:185], v234 offset:6144
	ds_read_b128 v[186:189], v234 offset:7168
	ds_read_b128 v[190:193], v234 offset:8192
	s_setprio 1
	s_waitcnt vmcnt(8) lgkmcnt(0)
	s_barrier
	v_mfma_f32_16x16x32_bf16 v[166:169], v[34:37], v[82:85], v[166:169]
	v_mfma_f32_16x16x32_bf16 v[162:165], v[42:45], v[82:85], v[162:165]
	v_mfma_f32_16x16x32_bf16 v[150:153], v[34:37], v[170:173], v[150:153]
	v_mfma_f32_16x16x32_bf16 v[146:149], v[42:45], v[170:173], v[146:149]
	v_mfma_f32_16x16x32_bf16 v[134:137], v[34:37], v[178:181], v[134:137]
	v_mfma_f32_16x16x32_bf16 v[130:133], v[42:45], v[178:181], v[130:133]
	v_mfma_f32_16x16x32_bf16 v[118:121], v[34:37], v[186:189], v[118:121]
	v_mfma_f32_16x16x32_bf16 v[114:117], v[42:45], v[186:189], v[114:117]
	v_mfma_f32_16x16x32_bf16 v[166:169], v[38:41], v[94:97], v[166:169]
	v_mfma_f32_16x16x32_bf16 v[162:165], v[46:49], v[94:97], v[162:165]
	v_mfma_f32_16x16x32_bf16 v[150:153], v[38:41], v[174:177], v[150:153]
	v_mfma_f32_16x16x32_bf16 v[146:149], v[46:49], v[174:177], v[146:149]
	v_mfma_f32_16x16x32_bf16 v[134:137], v[38:41], v[182:185], v[134:137]
	v_mfma_f32_16x16x32_bf16 v[130:133], v[46:49], v[182:185], v[130:133]
	v_mfma_f32_16x16x32_bf16 v[118:121], v[38:41], v[190:193], v[118:121]
	v_mfma_f32_16x16x32_bf16 v[114:117], v[46:49], v[190:193], v[114:117]
	s_setprio 0
	s_setprio 1
	v_mfma_f32_16x16x32_bf16 v[158:161], v[50:53], v[82:85], v[158:161]
	v_mfma_f32_16x16x32_bf16 v[82:85], v[58:61], v[82:85], v[154:157]
	v_mfma_f32_16x16x32_bf16 v[138:141], v[58:61], v[170:173], v[138:141]
	v_mfma_f32_16x16x32_bf16 v[126:129], v[50:53], v[178:181], v[126:129]
	v_mfma_f32_16x16x32_bf16 v[122:125], v[58:61], v[178:181], v[122:125]
	v_mfma_f32_16x16x32_bf16 v[110:113], v[50:53], v[186:189], v[110:113]
	v_mfma_f32_16x16x32_bf16 v[106:109], v[58:61], v[186:189], v[106:109]
	v_mfma_f32_16x16x32_bf16 v[158:161], v[54:57], v[94:97], v[158:161]
	v_mfma_f32_16x16x32_bf16 v[82:85], v[62:65], v[94:97], v[82:85]
	v_mfma_f32_16x16x32_bf16 v[94:97], v[50:53], v[170:173], v[142:145]
	v_mfma_f32_16x16x32_bf16 v[138:141], v[62:65], v[174:177], v[138:141]
	v_mfma_f32_16x16x32_bf16 v[126:129], v[54:57], v[182:185], v[126:129]
	v_mfma_f32_16x16x32_bf16 v[122:125], v[62:65], v[182:185], v[122:125]
	v_mfma_f32_16x16x32_bf16 v[110:113], v[54:57], v[190:193], v[110:113]
	v_mfma_f32_16x16x32_bf16 v[106:109], v[62:65], v[190:193], v[106:109]
	v_mfma_f32_16x16x32_bf16 v[94:97], v[54:57], v[174:177], v[94:97]
	s_setprio 0
	s_barrier
	s_mov_b32 m0, s48
	v_lshl_add_u64 v[202:203], s[38:39], 0, v[0:1]
	s_add_u32 s66, s38, 0x80000
	global_load_lds_dwordx4 v[202:203], off
	v_lshl_add_u64 v[204:205], s[38:39], 0, v[210:211]
	s_mov_b32 m0, s49
	s_addc_u32 s67, s39, 0
	global_load_lds_dwordx4 v[204:205], off
	v_lshl_add_u64 v[194:195], s[66:67], 0, v[0:1]
	s_mov_b32 m0, s50
	v_lshl_add_u64 v[220:221], s[40:41], 0, v[206:207]
	global_load_lds_dwordx4 v[194:195], off
	v_lshl_add_u64 v[194:195], s[66:67], 0, v[210:211]
	s_mov_b32 m0, s51
	v_lshl_add_u64 v[224:225], s[40:41], 0, v[208:209]
	global_load_lds_dwordx4 v[194:195], off
	s_mov_b32 m0, s52
	s_nop 0
	global_load_lds_dwordx4 v[220:221], off
	s_mov_b32 m0, s53
	s_nop 0
	global_load_lds_dwordx4 v[224:225], off
	ds_read_b128 v[142:145], v234 offset:17408
	ds_read_b128 v[154:157], v234 offset:18432
	ds_read_b128 v[170:173], v234 offset:19456
	ds_read_b128 v[174:177], v234 offset:20480
	ds_read_b128 v[178:181], v234 offset:21504
	ds_read_b128 v[182:185], v234 offset:22528
	ds_read_b128 v[186:189], v234 offset:23552
	ds_read_b128 v[190:193], v234 offset:24576
	s_setprio 1
	s_waitcnt vmcnt(8) lgkmcnt(0)
	s_barrier
; #define PG8_STAGE(bufoff, gbase, voff) do { _Pragma("unroll") for (int _i = 0; _i < 2; ++_i) \
;         __builtin_amdgcn_global_load_lds((const GAS unsigned*)((const GAS char*)(gbase) + (voff)[_i]), (LAS unsigned*)(lds + (bufoff) + ldsw + _i * 8192), 16, 0, 0); } while (0)
; #define PG8_LDA(dst, b, h) do { _Pragma("unroll") for (int m = 0; m < 4; ++m) _Pragma("unroll") for (int k = 0; k < 2; ++k) dst[m][k] = *(const LAS bf16x8*)(lds + PG8_SA(b, h) + aoff + m * 2048 + k * 1024); } while (0)
; #define PG8_LDB(dst, b, h) do { _Pragma("unroll") for (int n = 0; n < 2; ++n) _Pragma("unroll") for (int k = 0; k < 2; ++k) dst[n][k] = *(const LAS bf16x8*)(lds + PG8_SB(b, h) + boff + n * 2048 + k * 1024); } while (0)
; #define PG8_MMA(ai, bj, At, Bt) do { __builtin_amdgcn_s_setprio(1); _Pragma("unroll") for (int m = 0; m < 4; ++m) _Pragma("unroll") for (int n = 0; n < 2; ++n) _Pragma("unroll") for (int k = 0; k < 2; ++k) \
;         acc[ai][bj][m][n] = __builtin_amdgcn_mfma_f32_16x16x32_bf16(Bt[n][k], At[m][k], acc[ai][bj][m][n], 0, 0, 0); __builtin_amdgcn_s_setprio(0); } while (0)
; #define PG8_WAIT_V(n) asm volatile("s_waitcnt vmcnt(" #n ")" ::: "memory")
; #define PG8_WAIT_L(n) asm volatile("s_waitcnt lgkmcnt(" #n ")" ::: "memory")
; #define PG8_BAR __builtin_amdgcn_s_barrier()
; #define PG8_SCHED __builtin_amdgcn_sched_barrier(0)
; template <class Epi, class Sched, bool ALIGN_EPI>
; __device__ __forceinline__ void gemm_phase(LAS unsigned char* lds, const Gemm g, const Sched& S, const Epi& E, int wave_id) {
;     ...
;             PG8_WAIT_V(8); PG8_WAIT_L(0); PG8_BAR; PG8_MMA(1, 0, At, B0); PG8_MMA(1, 1, At, B1); PG8_BAR; PG8_SCHED;
;             PG8_LDB(B0, 1, 0); PG8_LDB(B1, 1, 1); PG8_SCHED; PG8_LDA(At, 1, 0); PG8_STAGE(PG8_SA(0, 1), a2 + hsA, voffA);
;             PG8_WAIT_V(8); PG8_WAIT_L(0); PG8_BAR; PG8_MMA(0, 0, At, B0); PG8_MMA(0, 1, At, B1); PG8_BAR; PG8_SCHED;
	v_mfma_f32_16x16x32_bf16 v[102:105], v[34:37], v[142:145], v[102:105]
	v_mfma_f32_16x16x32_bf16 v[98:101], v[42:45], v[142:145], v[98:101]
	v_mfma_f32_16x16x32_bf16 v[78:81], v[34:37], v[170:173], v[78:81]
	v_mfma_f32_16x16x32_bf16 v[74:77], v[42:45], v[170:173], v[74:77]
	v_mfma_f32_16x16x32_bf16 v[30:33], v[34:37], v[178:181], v[30:33]
	v_mfma_f32_16x16x32_bf16 v[26:29], v[42:45], v[178:181], v[26:29]
	v_mfma_f32_16x16x32_bf16 v[14:17], v[34:37], v[186:189], v[14:17]
	v_mfma_f32_16x16x32_bf16 v[10:13], v[42:45], v[186:189], v[10:13]
	v_mfma_f32_16x16x32_bf16 v[102:105], v[38:41], v[154:157], v[102:105]
	v_mfma_f32_16x16x32_bf16 v[98:101], v[46:49], v[154:157], v[98:101]
	v_mfma_f32_16x16x32_bf16 v[78:81], v[38:41], v[174:177], v[78:81]
	v_mfma_f32_16x16x32_bf16 v[74:77], v[46:49], v[174:177], v[74:77]
	v_mfma_f32_16x16x32_bf16 v[30:33], v[38:41], v[182:185], v[30:33]
	v_mfma_f32_16x16x32_bf16 v[26:29], v[46:49], v[182:185], v[26:29]
	v_mfma_f32_16x16x32_bf16 v[14:17], v[38:41], v[190:193], v[14:17]
	v_mfma_f32_16x16x32_bf16 v[10:13], v[46:49], v[190:193], v[10:13]
	s_setprio 0
	s_setprio 1
	v_mfma_f32_16x16x32_bf16 v[22:25], v[50:53], v[178:181], v[22:25]
	v_mfma_f32_16x16x32_bf16 v[18:21], v[58:61], v[178:181], v[18:21]
	v_mfma_f32_16x16x32_bf16 v[6:9], v[50:53], v[186:189], v[6:9]
	v_mfma_f32_16x16x32_bf16 v[2:5], v[58:61], v[186:189], v[2:5]
	v_mfma_f32_16x16x32_bf16 v[34:37], v[50:53], v[142:145], v[90:93]
	v_mfma_f32_16x16x32_bf16 v[38:41], v[58:61], v[142:145], v[86:89]
	v_mfma_f32_16x16x32_bf16 v[42:45], v[50:53], v[170:173], v[70:73]
	v_mfma_f32_16x16x32_bf16 v[46:49], v[58:61], v[170:173], v[66:69]
	v_mfma_f32_16x16x32_bf16 v[22:25], v[54:57], v[182:185], v[22:25]
	v_mfma_f32_16x16x32_bf16 v[18:21], v[62:65], v[182:185], v[18:21]
	v_mfma_f32_16x16x32_bf16 v[6:9], v[54:57], v[190:193], v[6:9]
	v_mfma_f32_16x16x32_bf16 v[2:5], v[62:65], v[190:193], v[2:5]
	v_mfma_f32_16x16x32_bf16 v[34:37], v[54:57], v[154:157], v[34:37]
	v_mfma_f32_16x16x32_bf16 v[38:41], v[62:65], v[154:157], v[38:41]
	v_mfma_f32_16x16x32_bf16 v[42:45], v[54:57], v[174:177], v[42:45]
	v_mfma_f32_16x16x32_bf16 v[46:49], v[62:65], v[174:177], v[46:49]
	s_setprio 0
	s_barrier
	s_add_u32 s40, s40, 0x80000
	s_addc_u32 s41, s41, 0
	s_mov_b32 m0, s54
	v_lshl_add_u64 v[142:143], s[40:41], 0, v[206:207]
	global_load_lds_dwordx4 v[142:143], off
	v_lshl_add_u64 v[142:143], s[40:41], 0, v[208:209]
	s_mov_b32 m0, s55
	s_nop 0
	global_load_lds_dwordx4 v[142:143], off
	v_add_u32_e32 v62, 0x18400, v235
	v_add_u32_e32 v66, 0x1c400, v235
	ds_read_b128 v[50:53], v62
	ds_read_b128 v[54:57], v62 offset:1024
	ds_read_b128 v[58:61], v62 offset:2048
	ds_read_b128 v[62:65], v62 offset:3072
	ds_read_b128 v[170:173], v66
	ds_read_b128 v[174:177], v66 offset:1024
	ds_read_b128 v[178:181], v66 offset:2048
	ds_read_b128 v[182:185], v66 offset:3072
	ds_read_b128 v[66:69], v234 offset:33792
	ds_read_b128 v[70:73], v234 offset:34816
	ds_read_b128 v[86:89], v234 offset:35840
	ds_read_b128 v[90:93], v234 offset:36864
	ds_read_b128 v[186:189], v234 offset:37888
	ds_read_b128 v[190:193], v234 offset:38912
	ds_read_b128 v[194:197], v234 offset:39936
	ds_read_b128 v[198:201], v234 offset:40960
	s_setprio 1
	s_waitcnt vmcnt(8) lgkmcnt(0)
	s_barrier
	v_mfma_f32_16x16x32_bf16 v[142:145], v[50:53], v[66:69], v[166:169]
	v_mfma_f32_16x16x32_bf16 v[166:169], v[54:57], v[70:73], v[142:145]
	v_mfma_f32_16x16x32_bf16 v[142:145], v[58:61], v[66:69], v[162:165]
	v_mfma_f32_16x16x32_bf16 v[162:165], v[62:65], v[70:73], v[142:145]
	v_mfma_f32_16x16x32_bf16 v[142:145], v[50:53], v[86:89], v[150:153]
	v_mfma_f32_16x16x32_bf16 v[150:153], v[54:57], v[90:93], v[142:145]
	v_mfma_f32_16x16x32_bf16 v[142:145], v[58:61], v[86:89], v[146:149]
	v_mfma_f32_16x16x32_bf16 v[134:137], v[50:53], v[186:189], v[134:137]
	v_mfma_f32_16x16x32_bf16 v[130:133], v[58:61], v[186:189], v[130:133]
	v_mfma_f32_16x16x32_bf16 v[118:121], v[50:53], v[194:197], v[118:121]
	v_mfma_f32_16x16x32_bf16 v[114:117], v[58:61], v[194:197], v[114:117]
	v_mfma_f32_16x16x32_bf16 v[146:149], v[62:65], v[90:93], v[142:145]
	v_mfma_f32_16x16x32_bf16 v[134:137], v[54:57], v[190:193], v[134:137]
	v_mfma_f32_16x16x32_bf16 v[130:133], v[62:65], v[190:193], v[130:133]
	v_mfma_f32_16x16x32_bf16 v[118:121], v[54:57], v[198:201], v[118:121]
	v_mfma_f32_16x16x32_bf16 v[114:117], v[62:65], v[198:201], v[114:117]
	s_setprio 0
	s_setprio 1
	v_mfma_f32_16x16x32_bf16 v[142:145], v[170:173], v[66:69], v[158:161]
	v_mfma_f32_16x16x32_bf16 v[66:69], v[178:181], v[66:69], v[82:85]
	v_mfma_f32_16x16x32_bf16 v[154:157], v[182:185], v[70:73], v[66:69]
	v_mfma_f32_16x16x32_bf16 v[66:69], v[170:173], v[86:89], v[94:97]
	v_mfma_f32_16x16x32_bf16 v[158:161], v[174:177], v[70:73], v[142:145]
	v_mfma_f32_16x16x32_bf16 v[142:145], v[174:177], v[90:93], v[66:69]
	v_mfma_f32_16x16x32_bf16 v[66:69], v[178:181], v[86:89], v[138:141]
	v_mfma_f32_16x16x32_bf16 v[138:141], v[182:185], v[90:93], v[66:69]
	v_mfma_f32_16x16x32_bf16 v[66:69], v[170:173], v[186:189], v[126:129]
	v_mfma_f32_16x16x32_bf16 v[126:129], v[174:177], v[190:193], v[66:69]
	v_mfma_f32_16x16x32_bf16 v[66:69], v[178:181], v[186:189], v[122:125]
	v_mfma_f32_16x16x32_bf16 v[122:125], v[182:185], v[190:193], v[66:69]
	v_mfma_f32_16x16x32_bf16 v[66:69], v[170:173], v[194:197], v[110:113]
	v_mfma_f32_16x16x32_bf16 v[110:113], v[174:177], v[198:201], v[66:69]
	v_mfma_f32_16x16x32_bf16 v[66:69], v[178:181], v[194:197], v[106:109]
	v_mfma_f32_16x16x32_bf16 v[106:109], v[182:185], v[198:201], v[66:69]
	s_setprio 0
	s_barrier
; #define PG8_STAGE(bufoff, gbase, voff) do { _Pragma("unroll") for (int _i = 0; _i < 2; ++_i) \
;         __builtin_amdgcn_global_load_lds((const GAS unsigned*)((const GAS char*)(gbase) + (voff)[_i]), (LAS unsigned*)(lds + (bufoff) + ldsw + _i * 8192), 16, 0, 0); } while (0)
; #define PG8_LDA(dst, b, h) do { _Pragma("unroll") for (int m = 0; m < 4; ++m) _Pragma("unroll") for (int k = 0; k < 2; ++k) dst[m][k] = *(const LAS bf16x8*)(lds + PG8_SA(b, h) + aoff + m * 2048 + k * 1024); } while (0)
; #define PG8_MMA(ai, bj, At, Bt) do { __builtin_amdgcn_s_setprio(1); _Pragma("unroll") for (int m = 0; m < 4; ++m) _Pragma("unroll") for (int n = 0; n < 2; ++n) _Pragma("unroll") for (int k = 0; k < 2; ++k) \
;         acc[ai][bj][m][n] = __builtin_amdgcn_mfma_f32_16x16x32_bf16(Bt[n][k], At[m][k], acc[ai][bj][m][n], 0, 0, 0); __builtin_amdgcn_s_setprio(0); } while (0)
; #define PG8_WAIT_V(n) asm volatile("s_waitcnt vmcnt(" #n ")" ::: "memory")
; #define PG8_WAIT_L(n) asm volatile("s_waitcnt lgkmcnt(" #n ")" ::: "memory")
; #define PG8_BAR __builtin_amdgcn_s_barrier()
; #define PG8_SCHED __builtin_amdgcn_sched_barrier(0)
; template <class Epi, class Sched, bool ALIGN_EPI>
; __device__ __forceinline__ void gemm_phase(LAS unsigned char* lds, const Gemm g, const Sched& S, const Epi& E, int wave_id) {
;     ...
;             PG8_LDA(At, 1, 1); PG8_STAGE(PG8_SB(1, 0), b3, voffB); PG8_STAGE(PG8_SB(1, 1), b3 + hsB, voffB); PG8_STAGE(PG8_SA(1, 0), a3, voffA);
;             PG8_WAIT_V(8); PG8_WAIT_L(0); PG8_BAR; PG8_MMA(1, 0, At, B0); PG8_MMA(1, 1, At, B1); PG8_BAR; PG8_SCHED;
;         }
	s_mov_b32 m0, s58
	v_lshl_add_u64 v[86:87], v[202:203], 0, s[92:93]
	s_add_u32 s38, s38, 0x80080
	s_nop 1
	global_load_lds_dwordx4 v[86:87], off
	v_lshl_add_u64 v[86:87], v[204:205], 0, s[92:93]
	s_mov_b32 m0, s59
	s_addc_u32 s39, s39, 0
	global_load_lds_dwordx4 v[86:87], off
	v_lshl_add_u64 v[86:87], s[38:39], 0, v[0:1]
	s_mov_b32 m0, s62
	s_nop 0
	global_load_lds_dwordx4 v[86:87], off
	v_lshl_add_u64 v[86:87], s[38:39], 0, v[210:211]
	s_mov_b32 m0, s63
	s_nop 0
	global_load_lds_dwordx4 v[86:87], off
	v_lshl_add_u64 v[86:87], v[220:221], 0, s[92:93]
	s_mov_b32 m0, s60
	s_nop 0
	global_load_lds_dwordx4 v[86:87], off
	v_lshl_add_u64 v[86:87], v[224:225], 0, s[92:93]
	s_mov_b32 m0, s61
	s_nop 0
	global_load_lds_dwordx4 v[86:87], off
	ds_read_b128 v[66:69], v234 offset:50176
	ds_read_b128 v[70:73], v234 offset:51200
	ds_read_b128 v[82:85], v234 offset:52224
	ds_read_b128 v[94:97], v234 offset:53248
	ds_read_b128 v[186:189], v234 offset:54272
	ds_read_b128 v[190:193], v234 offset:55296
	ds_read_b128 v[194:197], v234 offset:56320
	ds_read_b128 v[198:201], v234 offset:57344
	s_setprio 1
	s_waitcnt vmcnt(8) lgkmcnt(0)
	s_barrier
	v_mfma_f32_16x16x32_bf16 v[86:89], v[50:53], v[66:69], v[102:105]
	v_mfma_f32_16x16x32_bf16 v[102:105], v[54:57], v[70:73], v[86:89]
	v_mfma_f32_16x16x32_bf16 v[86:89], v[58:61], v[66:69], v[98:101]
	v_mfma_f32_16x16x32_bf16 v[78:81], v[50:53], v[82:85], v[78:81]
	v_mfma_f32_16x16x32_bf16 v[74:77], v[58:61], v[82:85], v[74:77]
	v_mfma_f32_16x16x32_bf16 v[30:33], v[50:53], v[186:189], v[30:33]
	v_mfma_f32_16x16x32_bf16 v[26:29], v[58:61], v[186:189], v[26:29]
	v_mfma_f32_16x16x32_bf16 v[14:17], v[50:53], v[194:197], v[14:17]
	v_mfma_f32_16x16x32_bf16 v[10:13], v[58:61], v[194:197], v[10:13]
	v_mfma_f32_16x16x32_bf16 v[98:101], v[62:65], v[70:73], v[86:89]
	v_mfma_f32_16x16x32_bf16 v[78:81], v[54:57], v[94:97], v[78:81]
	v_mfma_f32_16x16x32_bf16 v[74:77], v[62:65], v[94:97], v[74:77]
	v_mfma_f32_16x16x32_bf16 v[30:33], v[54:57], v[190:193], v[30:33]
	v_mfma_f32_16x16x32_bf16 v[26:29], v[62:65], v[190:193], v[26:29]
	v_mfma_f32_16x16x32_bf16 v[14:17], v[54:57], v[198:201], v[14:17]
	v_mfma_f32_16x16x32_bf16 v[10:13], v[62:65], v[198:201], v[10:13]
	s_setprio 0
	s_setprio 1
	v_mfma_f32_16x16x32_bf16 v[34:37], v[170:173], v[66:69], v[34:37]
	v_mfma_f32_16x16x32_bf16 v[90:93], v[174:177], v[70:73], v[34:37]
	v_mfma_f32_16x16x32_bf16 v[34:37], v[178:181], v[66:69], v[38:41]
	v_mfma_f32_16x16x32_bf16 v[86:89], v[182:185], v[70:73], v[34:37]
	v_mfma_f32_16x16x32_bf16 v[34:37], v[170:173], v[82:85], v[42:45]
	v_mfma_f32_16x16x32_bf16 v[70:73], v[174:177], v[94:97], v[34:37]
	v_mfma_f32_16x16x32_bf16 v[34:37], v[178:181], v[82:85], v[46:49]
	v_mfma_f32_16x16x32_bf16 v[22:25], v[170:173], v[186:189], v[22:25]
	v_mfma_f32_16x16x32_bf16 v[18:21], v[178:181], v[186:189], v[18:21]
	v_mfma_f32_16x16x32_bf16 v[6:9], v[170:173], v[194:197], v[6:9]
	v_mfma_f32_16x16x32_bf16 v[2:5], v[178:181], v[194:197], v[2:5]
	v_mfma_f32_16x16x32_bf16 v[66:69], v[182:185], v[94:97], v[34:37]
	v_mfma_f32_16x16x32_bf16 v[22:25], v[174:177], v[190:193], v[22:25]
	v_mfma_f32_16x16x32_bf16 v[18:21], v[182:185], v[190:193], v[18:21]
	v_mfma_f32_16x16x32_bf16 v[6:9], v[174:177], v[198:201], v[6:9]
	v_mfma_f32_16x16x32_bf16 v[2:5], v[182:185], v[198:201], v[2:5]
	s_setprio 0
	s_barrier
	s_add_i32 s65, s65, 2
	s_add_u32 s29, s29, 0x100
	s_addc_u32 s33, s33, 0
	s_add_u32 s36, s36, 0x100
	s_addc_u32 s37, s37, 0
	s_cmp_gt_u32 s65, 29
	s_cbranch_scc0 .LBB0_2620
	s_and_b64 vcc, exec, s[22:23]
	s_cbranch_vccz .LBB0_2623
	s_barrier

; #define GAS __attribute__((address_space(1)))
; #define PG8_STAGE(bufoff, gbase, voff) do { _Pragma("unroll") for (int _i = 0; _i < 2; ++_i) \
;         __builtin_amdgcn_global_load_lds((const GAS unsigned*)((const GAS char*)(gbase) + (voff)[_i]), (LAS unsigned*)(lds + (bufoff) + ldsw + _i * 8192), 16, 0, 0); } while (0)
; #define PG8_LDA(dst, b, h) do { _Pragma("unroll") for (int m = 0; m < 4; ++m) _Pragma("unroll") for (int k = 0; k < 2; ++k) dst[m][k] = *(const LAS bf16x8*)(lds + PG8_SA(b, h) + aoff + m * 2048 + k * 1024); } while (0)
; #define PG8_LDB(dst, b, h) do { _Pragma("unroll") for (int n = 0; n < 2; ++n) _Pragma("unroll") for (int k = 0; k < 2; ++k) dst[n][k] = *(const LAS bf16x8*)(lds + PG8_SB(b, h) + boff + n * 2048 + k * 1024); } while (0)
; #define PG8_MMA(ai, bj, At, Bt) do { __builtin_amdgcn_s_setprio(1); _Pragma("unroll") for (int m = 0; m < 4; ++m) _Pragma("unroll") for (int n = 0; n < 2; ++n) _Pragma("unroll") for (int k = 0; k < 2; ++k) \
;         acc[ai][bj][m][n] = __builtin_amdgcn_mfma_f32_16x16x32_bf16(Bt[n][k], At[m][k], acc[ai][bj][m][n], 0, 0, 0); __builtin_amdgcn_s_setprio(0); } while (0)
; #define PG8_WAIT_V(n) asm volatile("s_waitcnt vmcnt(" #n ")" ::: "memory")
; #define PG8_WAIT_L(n) asm volatile("s_waitcnt lgkmcnt(" #n ")" ::: "memory")
; #define PG8_BAR __builtin_amdgcn_s_barrier()
; template <class Epi, class Sched, bool ALIGN_EPI>
; __device__ __forceinline__ void gemm_phase(LAS unsigned char* lds, const Gemm g, const Sched& S, const Epi& E, int wave_id) {
;     ...
;             const bool last = (t == nt - 2);
;             const GAS char* a1 = cA + (size_t)(t + 1) * kstep;
;             const GAS char* a2 = last ? nA : cA + (size_t)(t + 2) * kstep; const GAS char* b2 = last ? nB : cB + (size_t)(t + 2) * kstep;
;             const GAS char* a3 = a2 + kstep; const GAS char* b3 = b2 + kstep;
;             PG8_LDB(B0, 0, 0); PG8_LDB(B1, 0, 1); PG8_SCHED; PG8_LDA(At, 0, 0); PG8_STAGE(PG8_SA(1, 1), a1 + hsA, voffA);
;             PG8_WAIT_V(8); PG8_WAIT_L(0); PG8_BAR; PG8_MMA(0, 0, At, B0); PG8_MMA(0, 1, At, B1); PG8_BAR; PG8_SCHED;
;             PG8_LDA(At, 0, 1); PG8_STAGE(PG8_SB(0, 0), b2, voffB); PG8_STAGE(PG8_SB(0, 1), b2 + hsB, voffB); PG8_STAGE(PG8_SA(0, 0), a2, voffA);
;             PG8_WAIT_V(8); PG8_WAIT_L(0); PG8_BAR; PG8_MMA(1, 0, At, B0); PG8_MMA(1, 1, At, B1); PG8_BAR; PG8_SCHED;
.LBB0_2874:
	s_add_u32 s28, s2, 0xfff80080
	s_addc_u32 s29, s3, -1
	s_cmp_eq_u32 s67, 28
	s_cselect_b32 s31, s23, s29
	s_cselect_b32 s30, s22, s28
	s_cselect_b32 s29, s21, s66
	s_cselect_b32 s28, s27, s33
	v_lshl_add_u64 v[208:209], s[2:3], 0, v[232:233]
	s_add_i32 m0, s40, 0xc400
	s_nop 0
	global_load_lds_dwordx4 v[208:209], off
	v_lshl_add_u64 v[208:209], s[2:3], 0, v[230:231]
	s_add_i32 m0, s40, 0xe400
	s_nop 0
	global_load_lds_dwordx4 v[208:209], off
	v_add_u32_e32 v82, 0x10400, v240
	ds_read_b128 v[18:21], v82
	ds_read_b128 v[88:91], v82 offset:1024
	ds_read_b128 v[108:111], v82 offset:2048
	ds_read_b128 v[112:115], v82 offset:3072
	v_add_u32_e32 v82, 0x14400, v240
	ds_read_b128 v[116:119], v82
	ds_read_b128 v[120:123], v82 offset:1024
	ds_read_b128 v[128:131], v82 offset:2048
	ds_read_b128 v[132:135], v82 offset:3072
	ds_read_b128 v[136:139], v239 offset:1024
	ds_read_b128 v[140:143], v239 offset:2048
	ds_read_b128 v[144:147], v239 offset:3072
	ds_read_b128 v[164:167], v239 offset:4096
	ds_read_b128 v[180:183], v239 offset:5120
	ds_read_b128 v[184:187], v239 offset:6144
	ds_read_b128 v[188:191], v239 offset:7168
	ds_read_b128 v[192:195], v239 offset:8192
	s_setprio 1
	s_waitcnt vmcnt(8) lgkmcnt(0)
	s_barrier
	v_mfma_f32_16x16x32_bf16 v[176:179], v[18:21], v[136:139], v[176:179]
	v_mfma_f32_16x16x32_bf16 v[30:33], v[108:111], v[136:139], v[30:33]
	v_mfma_f32_16x16x32_bf16 v[172:175], v[18:21], v[144:147], v[172:175]
	v_mfma_f32_16x16x32_bf16 v[50:53], v[108:111], v[144:147], v[50:53]
	v_mfma_f32_16x16x32_bf16 v[156:159], v[18:21], v[180:183], v[156:159]
	v_mfma_f32_16x16x32_bf16 v[78:81], v[108:111], v[180:183], v[78:81]
	v_mfma_f32_16x16x32_bf16 v[124:127], v[18:21], v[188:191], v[124:127]
	v_mfma_f32_16x16x32_bf16 v[104:107], v[108:111], v[188:191], v[104:107]
	v_mfma_f32_16x16x32_bf16 v[176:179], v[88:91], v[140:143], v[176:179]
	v_mfma_f32_16x16x32_bf16 v[30:33], v[112:115], v[140:143], v[30:33]
	v_mfma_f32_16x16x32_bf16 v[172:175], v[88:91], v[164:167], v[172:175]
	v_mfma_f32_16x16x32_bf16 v[50:53], v[112:115], v[164:167], v[50:53]
	v_mfma_f32_16x16x32_bf16 v[156:159], v[88:91], v[184:187], v[156:159]
	v_mfma_f32_16x16x32_bf16 v[78:81], v[112:115], v[184:187], v[78:81]
	v_mfma_f32_16x16x32_bf16 v[124:127], v[88:91], v[192:195], v[124:127]
	v_mfma_f32_16x16x32_bf16 v[104:107], v[112:115], v[192:195], v[104:107]
	s_setprio 0
	s_setprio 1
	v_mfma_f32_16x16x32_bf16 v[160:163], v[116:119], v[136:139], v[160:163]
	v_mfma_f32_16x16x32_bf16 v[62:65], v[128:131], v[136:139], v[62:65]
	v_mfma_f32_16x16x32_bf16 v[92:95], v[128:131], v[144:147], v[92:95]
	v_mfma_f32_16x16x32_bf16 v[100:103], v[116:119], v[188:191], v[100:103]
	v_mfma_f32_16x16x32_bf16 v[96:99], v[128:131], v[188:191], v[96:99]
	v_mfma_f32_16x16x32_bf16 v[160:163], v[120:123], v[140:143], v[160:163]
	v_mfma_f32_16x16x32_bf16 v[62:65], v[132:135], v[140:143], v[62:65]
	v_mfma_f32_16x16x32_bf16 v[136:139], v[116:119], v[144:147], v[168:171]
	v_mfma_f32_16x16x32_bf16 v[92:95], v[132:135], v[164:167], v[92:95]
	v_mfma_f32_16x16x32_bf16 v[140:143], v[116:119], v[180:183], v[152:155]
	v_mfma_f32_16x16x32_bf16 v[144:147], v[128:131], v[180:183], v[148:151]
	v_mfma_f32_16x16x32_bf16 v[100:103], v[120:123], v[192:195], v[100:103]
	v_mfma_f32_16x16x32_bf16 v[96:99], v[132:135], v[192:195], v[96:99]
	v_mfma_f32_16x16x32_bf16 v[136:139], v[120:123], v[164:167], v[136:139]
	v_mfma_f32_16x16x32_bf16 v[140:143], v[120:123], v[184:187], v[140:143]
	v_mfma_f32_16x16x32_bf16 v[144:147], v[132:135], v[184:187], v[144:147]
	s_setprio 0
	s_barrier
	s_mov_b32 m0, s41
	v_lshl_add_u64 v[200:201], s[28:29], 0, v[0:1]
	s_add_u32 s68, s28, 0x80000
	global_load_lds_dwordx4 v[200:201], off
	v_lshl_add_u64 v[202:203], s[28:29], 0, v[228:229]
	s_mov_b32 m0, s42
	s_addc_u32 s69, s29, 0
	global_load_lds_dwordx4 v[202:203], off
	v_lshl_add_u64 v[82:83], s[68:69], 0, v[0:1]
	s_mov_b32 m0, s43
	v_lshl_add_u64 v[204:205], s[30:31], 0, v[224:225]
	global_load_lds_dwordx4 v[82:83], off
	v_lshl_add_u64 v[82:83], s[68:69], 0, v[228:229]
	s_mov_b32 m0, s44
	v_lshl_add_u64 v[206:207], s[30:31], 0, v[226:227]
	global_load_lds_dwordx4 v[82:83], off
	s_mov_b32 m0, s45
	s_nop 0
	global_load_lds_dwordx4 v[204:205], off
	s_mov_b32 m0, s46
	s_nop 0
	global_load_lds_dwordx4 v[206:207], off
	ds_read_b128 v[148:151], v239 offset:17408
	ds_read_b128 v[152:155], v239 offset:18432
	ds_read_b128 v[164:167], v239 offset:19456
	ds_read_b128 v[168:171], v239 offset:20480
	ds_read_b128 v[180:183], v239 offset:21504
	ds_read_b128 v[184:187], v239 offset:22528
	ds_read_b128 v[188:191], v239 offset:23552
	ds_read_b128 v[192:195], v239 offset:24576
	s_setprio 1
	s_waitcnt vmcnt(8) lgkmcnt(0)
	s_barrier
; #define PG8_STAGE(bufoff, gbase, voff) do { _Pragma("unroll") for (int _i = 0; _i < 2; ++_i) \
;         __builtin_amdgcn_global_load_lds((const GAS unsigned*)((const GAS char*)(gbase) + (voff)[_i]), (LAS unsigned*)(lds + (bufoff) + ldsw + _i * 8192), 16, 0, 0); } while (0)
; #define PG8_LDA(dst, b, h) do { _Pragma("unroll") for (int m = 0; m < 4; ++m) _Pragma("unroll") for (int k = 0; k < 2; ++k) dst[m][k] = *(const LAS bf16x8*)(lds + PG8_SA(b, h) + aoff + m * 2048 + k * 1024); } while (0)
; #define PG8_LDB(dst, b, h) do { _Pragma("unroll") for (int n = 0; n < 2; ++n) _Pragma("unroll") for (int k = 0; k < 2; ++k) dst[n][k] = *(const LAS bf16x8*)(lds + PG8_SB(b, h) + boff + n * 2048 + k * 1024); } while (0)
; #define PG8_MMA(ai, bj, At, Bt) do { __builtin_amdgcn_s_setprio(1); _Pragma("unroll") for (int m = 0; m < 4; ++m) _Pragma("unroll") for (int n = 0; n < 2; ++n) _Pragma("unroll") for (int k = 0; k < 2; ++k) \
;         acc[ai][bj][m][n] = __builtin_amdgcn_mfma_f32_16x16x32_bf16(Bt[n][k], At[m][k], acc[ai][bj][m][n], 0, 0, 0); __builtin_amdgcn_s_setprio(0); } while (0)
; #define PG8_WAIT_V(n) asm volatile("s_waitcnt vmcnt(" #n ")" ::: "memory")
; #define PG8_WAIT_L(n) asm volatile("s_waitcnt lgkmcnt(" #n ")" ::: "memory")
; #define PG8_BAR __builtin_amdgcn_s_barrier()
; #define PG8_SCHED __builtin_amdgcn_sched_barrier(0)
; template <class Epi, class Sched, bool ALIGN_EPI>
; __device__ __forceinline__ void gemm_phase(LAS unsigned char* lds, const Gemm g, const Sched& S, const Epi& E, int wave_id) {
;     ...
;             PG8_WAIT_V(8); PG8_WAIT_L(0); PG8_BAR; PG8_MMA(1, 0, At, B0); PG8_MMA(1, 1, At, B1); PG8_BAR; PG8_SCHED;
;             PG8_LDB(B0, 1, 0); PG8_LDB(B1, 1, 1); PG8_SCHED; PG8_LDA(At, 1, 0); PG8_STAGE(PG8_SA(0, 1), a2 + hsA, voffA);
;             PG8_WAIT_V(8); PG8_WAIT_L(0); PG8_BAR; PG8_MMA(0, 0, At, B0); PG8_MMA(0, 1, At, B1); PG8_BAR; PG8_SCHED;
	v_mfma_f32_16x16x32_bf16 v[82:85], v[18:21], v[148:151], v[84:87]
	v_mfma_f32_16x16x32_bf16 v[70:73], v[108:111], v[148:151], v[70:73]
	v_mfma_f32_16x16x32_bf16 v[58:61], v[18:21], v[164:167], v[58:61]
	v_mfma_f32_16x16x32_bf16 v[54:57], v[108:111], v[164:167], v[54:57]
	v_mfma_f32_16x16x32_bf16 v[38:41], v[18:21], v[180:183], v[38:41]
	v_mfma_f32_16x16x32_bf16 v[34:37], v[108:111], v[180:183], v[34:37]
	v_mfma_f32_16x16x32_bf16 v[14:17], v[18:21], v[188:191], v[14:17]
	v_mfma_f32_16x16x32_bf16 v[10:13], v[108:111], v[188:191], v[10:13]
	v_mfma_f32_16x16x32_bf16 v[82:85], v[88:91], v[152:155], v[82:85]
	v_mfma_f32_16x16x32_bf16 v[70:73], v[112:115], v[152:155], v[70:73]
	v_mfma_f32_16x16x32_bf16 v[58:61], v[88:91], v[168:171], v[58:61]
	v_mfma_f32_16x16x32_bf16 v[54:57], v[112:115], v[168:171], v[54:57]
	v_mfma_f32_16x16x32_bf16 v[38:41], v[88:91], v[184:187], v[38:41]
	v_mfma_f32_16x16x32_bf16 v[34:37], v[112:115], v[184:187], v[34:37]
	v_mfma_f32_16x16x32_bf16 v[14:17], v[88:91], v[192:195], v[14:17]
	v_mfma_f32_16x16x32_bf16 v[10:13], v[112:115], v[192:195], v[10:13]
	s_setprio 0
	s_setprio 1
	v_mfma_f32_16x16x32_bf16 v[66:69], v[128:131], v[148:151], v[66:69]
	v_mfma_f32_16x16x32_bf16 v[46:49], v[116:119], v[164:167], v[46:49]
	v_mfma_f32_16x16x32_bf16 v[42:45], v[128:131], v[164:167], v[42:45]
	v_mfma_f32_16x16x32_bf16 v[26:29], v[116:119], v[180:183], v[26:29]
	v_mfma_f32_16x16x32_bf16 v[22:25], v[128:131], v[180:183], v[22:25]
	v_mfma_f32_16x16x32_bf16 v[6:9], v[116:119], v[188:191], v[6:9]
	v_mfma_f32_16x16x32_bf16 v[2:5], v[128:131], v[188:191], v[2:5]
	v_mfma_f32_16x16x32_bf16 v[18:21], v[116:119], v[148:151], v[74:77]
	v_mfma_f32_16x16x32_bf16 v[66:69], v[132:135], v[152:155], v[66:69]
	v_mfma_f32_16x16x32_bf16 v[46:49], v[120:123], v[168:171], v[46:49]
	v_mfma_f32_16x16x32_bf16 v[42:45], v[132:135], v[168:171], v[42:45]
	v_mfma_f32_16x16x32_bf16 v[26:29], v[120:123], v[184:187], v[26:29]
	v_mfma_f32_16x16x32_bf16 v[22:25], v[132:135], v[184:187], v[22:25]
	v_mfma_f32_16x16x32_bf16 v[6:9], v[120:123], v[192:195], v[6:9]
	v_mfma_f32_16x16x32_bf16 v[2:5], v[132:135], v[192:195], v[2:5]
	v_mfma_f32_16x16x32_bf16 v[18:21], v[120:123], v[152:155], v[18:21]
	s_setprio 0
	s_barrier
	s_add_u32 s30, s30, 0x80000
	s_addc_u32 s31, s31, 0
	s_mov_b32 m0, s47
	v_lshl_add_u64 v[210:211], s[30:31], 0, v[224:225]
	global_load_lds_dwordx4 v[210:211], off
	v_lshl_add_u64 v[210:211], s[30:31], 0, v[226:227]
	s_mov_b32 m0, s48
	s_nop 0
	global_load_lds_dwordx4 v[210:211], off
	v_add_u32_e32 v86, 0x18400, v240
	ds_read_b128 v[74:77], v86
	ds_read_b128 v[88:91], v86 offset:1024
	ds_read_b128 v[108:111], v86 offset:2048
	ds_read_b128 v[112:115], v86 offset:3072
	v_add_u32_e32 v86, 0x1c400, v240
	ds_read_b128 v[116:119], v86
	ds_read_b128 v[120:123], v86 offset:1024
	ds_read_b128 v[128:131], v86 offset:2048
	ds_read_b128 v[132:135], v86 offset:3072
	ds_read_b128 v[148:151], v239 offset:33792
	ds_read_b128 v[152:155], v239 offset:34816
	ds_read_b128 v[164:167], v239 offset:35840
	ds_read_b128 v[180:183], v239 offset:36864
	ds_read_b128 v[184:187], v239 offset:37888
	ds_read_b128 v[188:191], v239 offset:38912
	ds_read_b128 v[192:195], v239 offset:39936
	ds_read_b128 v[196:199], v239 offset:40960
	s_setprio 1
	s_waitcnt vmcnt(8) lgkmcnt(0)
	s_barrier
	v_mfma_f32_16x16x32_bf16 v[168:171], v[74:77], v[148:151], v[176:179]
	v_mfma_f32_16x16x32_bf16 v[176:179], v[88:91], v[152:155], v[168:171]
	v_mfma_f32_16x16x32_bf16 v[30:33], v[108:111], v[148:151], v[30:33]
	v_mfma_f32_16x16x32_bf16 v[168:171], v[74:77], v[164:167], v[172:175]
	v_mfma_f32_16x16x32_bf16 v[50:53], v[108:111], v[164:167], v[50:53]
	v_mfma_f32_16x16x32_bf16 v[156:159], v[74:77], v[184:187], v[156:159]
	v_mfma_f32_16x16x32_bf16 v[78:81], v[108:111], v[184:187], v[78:81]
	v_mfma_f32_16x16x32_bf16 v[124:127], v[74:77], v[192:195], v[124:127]
	v_mfma_f32_16x16x32_bf16 v[104:107], v[108:111], v[192:195], v[104:107]
	v_mfma_f32_16x16x32_bf16 v[30:33], v[112:115], v[152:155], v[30:33]
	v_mfma_f32_16x16x32_bf16 v[172:175], v[88:91], v[180:183], v[168:171]
	v_mfma_f32_16x16x32_bf16 v[50:53], v[112:115], v[180:183], v[50:53]
	v_mfma_f32_16x16x32_bf16 v[156:159], v[88:91], v[188:191], v[156:159]
	v_mfma_f32_16x16x32_bf16 v[78:81], v[112:115], v[188:191], v[78:81]
	v_mfma_f32_16x16x32_bf16 v[124:127], v[88:91], v[196:199], v[124:127]
	v_mfma_f32_16x16x32_bf16 v[104:107], v[112:115], v[196:199], v[104:107]
	s_setprio 0
	s_setprio 1
	v_mfma_f32_16x16x32_bf16 v[136:139], v[116:119], v[164:167], v[136:139]
	v_mfma_f32_16x16x32_bf16 v[160:163], v[116:119], v[148:151], v[160:163]
	v_mfma_f32_16x16x32_bf16 v[62:65], v[128:131], v[148:151], v[62:65]
	v_mfma_f32_16x16x32_bf16 v[168:171], v[120:123], v[180:183], v[136:139]
	v_mfma_f32_16x16x32_bf16 v[136:139], v[116:119], v[184:187], v[140:143]
	v_mfma_f32_16x16x32_bf16 v[160:163], v[120:123], v[152:155], v[160:163]
	v_mfma_f32_16x16x32_bf16 v[62:65], v[132:135], v[152:155], v[62:65]
	v_mfma_f32_16x16x32_bf16 v[92:95], v[128:131], v[164:167], v[92:95]
	v_mfma_f32_16x16x32_bf16 v[152:155], v[120:123], v[188:191], v[136:139]
	v_mfma_f32_16x16x32_bf16 v[136:139], v[128:131], v[184:187], v[144:147]
	v_mfma_f32_16x16x32_bf16 v[100:103], v[116:119], v[192:195], v[100:103]
	v_mfma_f32_16x16x32_bf16 v[96:99], v[128:131], v[192:195], v[96:99]
	v_mfma_f32_16x16x32_bf16 v[92:95], v[132:135], v[180:183], v[92:95]
	v_mfma_f32_16x16x32_bf16 v[148:151], v[132:135], v[188:191], v[136:139]
	v_mfma_f32_16x16x32_bf16 v[100:103], v[120:123], v[196:199], v[100:103]
	v_mfma_f32_16x16x32_bf16 v[96:99], v[132:135], v[196:199], v[96:99]
	s_setprio 0
	s_barrier
; #define PG8_STAGE(bufoff, gbase, voff) do { _Pragma("unroll") for (int _i = 0; _i < 2; ++_i) \
;         __builtin_amdgcn_global_load_lds((const GAS unsigned*)((const GAS char*)(gbase) + (voff)[_i]), (LAS unsigned*)(lds + (bufoff) + ldsw + _i * 8192), 16, 0, 0); } while (0)
; #define PG8_LDA(dst, b, h) do { _Pragma("unroll") for (int m = 0; m < 4; ++m) _Pragma("unroll") for (int k = 0; k < 2; ++k) dst[m][k] = *(const LAS bf16x8*)(lds + PG8_SA(b, h) + aoff + m * 2048 + k * 1024); } while (0)
; #define PG8_MMA(ai, bj, At, Bt) do { __builtin_amdgcn_s_setprio(1); _Pragma("unroll") for (int m = 0; m < 4; ++m) _Pragma("unroll") for (int n = 0; n < 2; ++n) _Pragma("unroll") for (int k = 0; k < 2; ++k) \
;         acc[ai][bj][m][n] = __builtin_amdgcn_mfma_f32_16x16x32_bf16(Bt[n][k], At[m][k], acc[ai][bj][m][n], 0, 0, 0); __builtin_amdgcn_s_setprio(0); } while (0)
; #define PG8_WAIT_V(n) asm volatile("s_waitcnt vmcnt(" #n ")" ::: "memory")
; #define PG8_WAIT_L(n) asm volatile("s_waitcnt lgkmcnt(" #n ")" ::: "memory")
; #define PG8_BAR __builtin_amdgcn_s_barrier()
; #define PG8_SCHED __builtin_amdgcn_sched_barrier(0)
; template <class Epi, class Sched, bool ALIGN_EPI>
; __device__ __forceinline__ void gemm_phase(LAS unsigned char* lds, const Gemm g, const Sched& S, const Epi& E, int wave_id) {
;     ...
;             PG8_LDA(At, 1, 1); PG8_STAGE(PG8_SB(1, 0), b3, voffB); PG8_STAGE(PG8_SB(1, 1), b3 + hsB, voffB); PG8_STAGE(PG8_SA(1, 0), a3, voffA);
;             PG8_WAIT_V(8); PG8_WAIT_L(0); PG8_BAR; PG8_MMA(1, 0, At, B0); PG8_MMA(1, 1, At, B1); PG8_BAR; PG8_SCHED;
;         }
	s_mov_b32 m0, s52
	v_lshl_add_u64 v[86:87], v[200:201], 0, s[92:93]
	s_add_u32 s28, s28, 0x80080
	global_load_lds_dwordx4 v[86:87], off
	v_lshl_add_u64 v[86:87], v[202:203], 0, s[92:93]
	s_mov_b32 m0, s53
	s_addc_u32 s29, s29, 0
	global_load_lds_dwordx4 v[86:87], off
	v_lshl_add_u64 v[86:87], s[28:29], 0, v[0:1]
	s_mov_b32 m0, s56
	s_nop 0
	global_load_lds_dwordx4 v[86:87], off
	v_lshl_add_u64 v[86:87], s[28:29], 0, v[228:229]
	s_mov_b32 m0, s57
	s_nop 0
	global_load_lds_dwordx4 v[86:87], off
	v_lshl_add_u64 v[86:87], v[204:205], 0, s[92:93]
	s_mov_b32 m0, s54
	s_nop 0
	global_load_lds_dwordx4 v[86:87], off
	v_lshl_add_u64 v[86:87], v[206:207], 0, s[92:93]
	s_mov_b32 m0, s55
	s_nop 0
	global_load_lds_dwordx4 v[86:87], off
	ds_read_b128 v[136:139], v239 offset:50176
	ds_read_b128 v[140:143], v239 offset:51200
	ds_read_b128 v[144:147], v239 offset:52224
	ds_read_b128 v[164:167], v239 offset:53248
	ds_read_b128 v[180:183], v239 offset:54272
	ds_read_b128 v[184:187], v239 offset:55296
	ds_read_b128 v[188:191], v239 offset:56320
	ds_read_b128 v[192:195], v239 offset:57344
	s_setprio 1
	s_waitcnt vmcnt(8) lgkmcnt(0)
	s_barrier
	v_mfma_f32_16x16x32_bf16 v[82:85], v[74:77], v[136:139], v[82:85]
	v_mfma_f32_16x16x32_bf16 v[70:73], v[108:111], v[136:139], v[70:73]
	v_mfma_f32_16x16x32_bf16 v[58:61], v[74:77], v[144:147], v[58:61]
	v_mfma_f32_16x16x32_bf16 v[54:57], v[108:111], v[144:147], v[54:57]
	v_mfma_f32_16x16x32_bf16 v[38:41], v[74:77], v[180:183], v[38:41]
	v_mfma_f32_16x16x32_bf16 v[34:37], v[108:111], v[180:183], v[34:37]
	v_mfma_f32_16x16x32_bf16 v[14:17], v[74:77], v[188:191], v[14:17]
	v_mfma_f32_16x16x32_bf16 v[10:13], v[108:111], v[188:191], v[10:13]
	v_mfma_f32_16x16x32_bf16 v[84:87], v[88:91], v[140:143], v[82:85]
	v_mfma_f32_16x16x32_bf16 v[70:73], v[112:115], v[140:143], v[70:73]
	v_mfma_f32_16x16x32_bf16 v[58:61], v[88:91], v[164:167], v[58:61]
	v_mfma_f32_16x16x32_bf16 v[54:57], v[112:115], v[164:167], v[54:57]
	v_mfma_f32_16x16x32_bf16 v[38:41], v[88:91], v[184:187], v[38:41]
	v_mfma_f32_16x16x32_bf16 v[34:37], v[112:115], v[184:187], v[34:37]
	v_mfma_f32_16x16x32_bf16 v[14:17], v[88:91], v[192:195], v[14:17]
	v_mfma_f32_16x16x32_bf16 v[10:13], v[112:115], v[192:195], v[10:13]
	s_setprio 0
	s_setprio 1
	v_mfma_f32_16x16x32_bf16 v[18:21], v[116:119], v[136:139], v[18:21]
	v_mfma_f32_16x16x32_bf16 v[74:77], v[120:123], v[140:143], v[18:21]
	v_mfma_f32_16x16x32_bf16 v[18:21], v[128:131], v[136:139], v[66:69]
	v_mfma_f32_16x16x32_bf16 v[66:69], v[132:135], v[140:143], v[18:21]
	v_mfma_f32_16x16x32_bf16 v[18:21], v[116:119], v[144:147], v[46:49]
	v_mfma_f32_16x16x32_bf16 v[46:49], v[120:123], v[164:167], v[18:21]
	v_mfma_f32_16x16x32_bf16 v[18:21], v[128:131], v[144:147], v[42:45]
	v_mfma_f32_16x16x32_bf16 v[42:45], v[132:135], v[164:167], v[18:21]
	v_mfma_f32_16x16x32_bf16 v[18:21], v[116:119], v[180:183], v[26:29]
	v_mfma_f32_16x16x32_bf16 v[26:29], v[120:123], v[184:187], v[18:21]
	v_mfma_f32_16x16x32_bf16 v[18:21], v[128:131], v[180:183], v[22:25]
	v_mfma_f32_16x16x32_bf16 v[6:9], v[116:119], v[188:191], v[6:9]
	v_mfma_f32_16x16x32_bf16 v[2:5], v[128:131], v[188:191], v[2:5]
	v_mfma_f32_16x16x32_bf16 v[22:25], v[132:135], v[184:187], v[18:21]
	v_mfma_f32_16x16x32_bf16 v[6:9], v[120:123], v[192:195], v[6:9]
	v_mfma_f32_16x16x32_bf16 v[2:5], v[132:135], v[192:195], v[2:5]
	s_setprio 0
	s_barrier
	s_add_i32 s67, s67, 2
	s_add_u32 s33, s33, 0x100
	s_addc_u32 s66, s66, 0
	s_add_u32 s2, s2, 0x100
	s_addc_u32 s3, s3, 0
	s_cmp_gt_u32 s67, 29
	s_cbranch_scc0 .LBB0_2874
	s_and_b64 vcc, exec, s[16:17]
	s_cbranch_vccz .LBB0_2877
	s_barrier

; #define GAS __attribute__((address_space(1)))
; #define PG8_STAGE(bufoff, gbase, voff) do { _Pragma("unroll") for (int _i = 0; _i < 2; ++_i) \
;         __builtin_amdgcn_global_load_lds((const GAS unsigned*)((const GAS char*)(gbase) + (voff)[_i]), (LAS unsigned*)(lds + (bufoff) + ldsw + _i * 8192), 16, 0, 0); } while (0)
; #define PG8_LDA(dst, b, h) do { _Pragma("unroll") for (int m = 0; m < 4; ++m) _Pragma("unroll") for (int k = 0; k < 2; ++k) dst[m][k] = *(const LAS bf16x8*)(lds + PG8_SA(b, h) + aoff + m * 2048 + k * 1024); } while (0)
; #define PG8_LDB(dst, b, h) do { _Pragma("unroll") for (int n = 0; n < 2; ++n) _Pragma("unroll") for (int k = 0; k < 2; ++k) dst[n][k] = *(const LAS bf16x8*)(lds + PG8_SB(b, h) + boff + n * 2048 + k * 1024); } while (0)
; #define PG8_MMA(ai, bj, At, Bt) do { __builtin_amdgcn_s_setprio(1); _Pragma("unroll") for (int m = 0; m < 4; ++m) _Pragma("unroll") for (int n = 0; n < 2; ++n) _Pragma("unroll") for (int k = 0; k < 2; ++k) \
;         acc[ai][bj][m][n] = __builtin_amdgcn_mfma_f32_16x16x32_bf16(Bt[n][k], At[m][k], acc[ai][bj][m][n], 0, 0, 0); __builtin_amdgcn_s_setprio(0); } while (0)
; #define PG8_WAIT_V(n) asm volatile("s_waitcnt vmcnt(" #n ")" ::: "memory")
; #define PG8_WAIT_L(n) asm volatile("s_waitcnt lgkmcnt(" #n ")" ::: "memory")
; #define PG8_BAR __builtin_amdgcn_s_barrier()
; template <class Epi, class Sched, bool ALIGN_EPI>
; __device__ __forceinline__ void gemm_phase(LAS unsigned char* lds, const Gemm g, const Sched& S, const Epi& E, int wave_id) {
;     ...
;             const bool last = (t == nt - 2);
;             const GAS char* a1 = cA + (size_t)(t + 1) * kstep;
;             const GAS char* a2 = last ? nA : cA + (size_t)(t + 2) * kstep; const GAS char* b2 = last ? nB : cB + (size_t)(t + 2) * kstep;
;             const GAS char* a3 = a2 + kstep; const GAS char* b3 = b2 + kstep;
;             PG8_LDB(B0, 0, 0); PG8_LDB(B1, 0, 1); PG8_SCHED; PG8_LDA(At, 0, 0); PG8_STAGE(PG8_SA(1, 1), a1 + hsA, voffA);
;             PG8_WAIT_V(8); PG8_WAIT_L(0); PG8_BAR; PG8_MMA(0, 0, At, B0); PG8_MMA(0, 1, At, B1); PG8_BAR; PG8_SCHED;
;             PG8_LDA(At, 0, 1); PG8_STAGE(PG8_SB(0, 0), b2, voffB); PG8_STAGE(PG8_SB(0, 1), b2 + hsB, voffB); PG8_STAGE(PG8_SA(0, 0), a2, voffA);
;             PG8_WAIT_V(8); PG8_WAIT_L(0); PG8_BAR; PG8_MMA(1, 0, At, B0); PG8_MMA(1, 1, At, B1); PG8_BAR; PG8_SCHED;
.LBB0_3681:
	s_add_u32 s0, s28, 0x100
	s_addc_u32 s1, s29, 0
	s_cmpk_eq_i32 s63, 0x54
	s_cselect_b32 s35, s25, s1
	s_cselect_b32 s34, s24, s0
	s_cselect_b32 s31, s27, s62
	s_cselect_b32 s30, s26, s61
	v_lshl_add_u64 v[204:205], s[28:29], 0, v[190:191]
	s_add_i32 m0, s41, 0xc400
	s_nop 0
	global_load_lds_dwordx4 v[204:205], off
	v_lshl_add_u64 v[204:205], s[28:29], 0, v[188:189]
	s_add_i32 m0, s41, 0xe400
	s_nop 0
	global_load_lds_dwordx4 v[204:205], off
	v_add_u32_e32 v46, 0x10400, v208
	v_add_u32_e32 v62, 0x14400, v208
	ds_read_b128 v[34:37], v46
	ds_read_b128 v[38:41], v46 offset:1024
	ds_read_b128 v[42:45], v46 offset:2048
	ds_read_b128 v[46:49], v46 offset:3072
	ds_read_b128 v[50:53], v62
	ds_read_b128 v[54:57], v62 offset:1024
	ds_read_b128 v[58:61], v62 offset:2048
	ds_read_b128 v[62:65], v62 offset:3072
	ds_read_b128 v[162:165], v207 offset:1024
	ds_read_b128 v[166:169], v207 offset:2048
	ds_read_b128 v[170:173], v207 offset:3072
	ds_read_b128 v[174:177], v207 offset:4096
	ds_read_b128 v[178:181], v207 offset:5120
	ds_read_b128 v[192:195], v207 offset:6144
	ds_read_b128 v[196:199], v207 offset:7168
	ds_read_b128 v[200:203], v207 offset:8192
	s_setprio 1
	s_waitcnt vmcnt(8) lgkmcnt(0)
	s_barrier
	v_mfma_f32_16x16x32_bf16 v[158:161], v[34:37], v[162:165], v[158:161]
	v_mfma_f32_16x16x32_bf16 v[154:157], v[42:45], v[162:165], v[154:157]
	v_mfma_f32_16x16x32_bf16 v[142:145], v[34:37], v[170:173], v[142:145]
	v_mfma_f32_16x16x32_bf16 v[138:141], v[42:45], v[170:173], v[138:141]
	v_mfma_f32_16x16x32_bf16 v[126:129], v[34:37], v[178:181], v[126:129]
	v_mfma_f32_16x16x32_bf16 v[122:125], v[42:45], v[178:181], v[122:125]
	v_mfma_f32_16x16x32_bf16 v[110:113], v[34:37], v[196:199], v[110:113]
	v_mfma_f32_16x16x32_bf16 v[106:109], v[42:45], v[196:199], v[106:109]
	v_mfma_f32_16x16x32_bf16 v[158:161], v[38:41], v[166:169], v[158:161]
	v_mfma_f32_16x16x32_bf16 v[154:157], v[46:49], v[166:169], v[154:157]
	v_mfma_f32_16x16x32_bf16 v[142:145], v[38:41], v[174:177], v[142:145]
	v_mfma_f32_16x16x32_bf16 v[138:141], v[46:49], v[174:177], v[138:141]
	v_mfma_f32_16x16x32_bf16 v[126:129], v[38:41], v[192:195], v[126:129]
	v_mfma_f32_16x16x32_bf16 v[122:125], v[46:49], v[192:195], v[122:125]
	v_mfma_f32_16x16x32_bf16 v[110:113], v[38:41], v[200:203], v[110:113]
	v_mfma_f32_16x16x32_bf16 v[106:109], v[46:49], v[200:203], v[106:109]
	s_setprio 0
	s_setprio 1
	v_mfma_f32_16x16x32_bf16 v[150:153], v[50:53], v[162:165], v[150:153]
	v_mfma_f32_16x16x32_bf16 v[146:149], v[58:61], v[162:165], v[146:149]
	v_mfma_f32_16x16x32_bf16 v[134:137], v[50:53], v[170:173], v[134:137]
	v_mfma_f32_16x16x32_bf16 v[130:133], v[58:61], v[170:173], v[130:133]
	v_mfma_f32_16x16x32_bf16 v[118:121], v[50:53], v[178:181], v[118:121]
	v_mfma_f32_16x16x32_bf16 v[114:117], v[58:61], v[178:181], v[114:117]
	v_mfma_f32_16x16x32_bf16 v[102:105], v[50:53], v[196:199], v[102:105]
	v_mfma_f32_16x16x32_bf16 v[98:101], v[58:61], v[196:199], v[98:101]
	v_mfma_f32_16x16x32_bf16 v[150:153], v[54:57], v[166:169], v[150:153]
	v_mfma_f32_16x16x32_bf16 v[146:149], v[62:65], v[166:169], v[146:149]
	v_mfma_f32_16x16x32_bf16 v[134:137], v[54:57], v[174:177], v[134:137]
	v_mfma_f32_16x16x32_bf16 v[130:133], v[62:65], v[174:177], v[130:133]
	v_mfma_f32_16x16x32_bf16 v[118:121], v[54:57], v[192:195], v[118:121]
	v_mfma_f32_16x16x32_bf16 v[114:117], v[62:65], v[192:195], v[114:117]
	v_mfma_f32_16x16x32_bf16 v[102:105], v[54:57], v[200:203], v[102:105]
	v_mfma_f32_16x16x32_bf16 v[98:101], v[62:65], v[200:203], v[98:101]
	s_setprio 0
	s_barrier
	s_mov_b32 m0, s42
	v_lshl_add_u64 v[204:205], s[30:31], 0, v[0:1]
	s_add_u32 s28, s30, 0x160000
	global_load_lds_dwordx4 v[204:205], off
	v_lshl_add_u64 v[218:219], s[30:31], 0, v[186:187]
	s_mov_b32 m0, s43
	s_addc_u32 s29, s31, 0
	global_load_lds_dwordx4 v[218:219], off
	v_lshl_add_u64 v[210:211], s[28:29], 0, v[0:1]
	s_mov_b32 m0, s44
	v_lshl_add_u64 v[220:221], s[34:35], 0, v[182:183]
	global_load_lds_dwordx4 v[210:211], off
	v_lshl_add_u64 v[210:211], s[28:29], 0, v[186:187]
	s_mov_b32 m0, s45
	v_lshl_add_u64 v[224:225], s[34:35], 0, v[184:185]
	global_load_lds_dwordx4 v[210:211], off
	s_mov_b32 m0, s46
	s_nop 0
	global_load_lds_dwordx4 v[220:221], off
	s_mov_b32 m0, s47
	s_nop 0
	global_load_lds_dwordx4 v[224:225], off
	ds_read_b128 v[162:165], v207 offset:17408
	ds_read_b128 v[166:169], v207 offset:18432
	ds_read_b128 v[170:173], v207 offset:19456
	ds_read_b128 v[174:177], v207 offset:20480
	ds_read_b128 v[178:181], v207 offset:21504
	ds_read_b128 v[192:195], v207 offset:22528
	ds_read_b128 v[196:199], v207 offset:23552
	ds_read_b128 v[200:203], v207 offset:24576
	s_setprio 1
	s_waitcnt vmcnt(8) lgkmcnt(0)
	s_barrier
; #define PG8_STAGE(bufoff, gbase, voff) do { _Pragma("unroll") for (int _i = 0; _i < 2; ++_i) \
;         __builtin_amdgcn_global_load_lds((const GAS unsigned*)((const GAS char*)(gbase) + (voff)[_i]), (LAS unsigned*)(lds + (bufoff) + ldsw + _i * 8192), 16, 0, 0); } while (0)
; #define PG8_LDA(dst, b, h) do { _Pragma("unroll") for (int m = 0; m < 4; ++m) _Pragma("unroll") for (int k = 0; k < 2; ++k) dst[m][k] = *(const LAS bf16x8*)(lds + PG8_SA(b, h) + aoff + m * 2048 + k * 1024); } while (0)
; #define PG8_LDB(dst, b, h) do { _Pragma("unroll") for (int n = 0; n < 2; ++n) _Pragma("unroll") for (int k = 0; k < 2; ++k) dst[n][k] = *(const LAS bf16x8*)(lds + PG8_SB(b, h) + boff + n * 2048 + k * 1024); } while (0)
; #define PG8_MMA(ai, bj, At, Bt) do { __builtin_amdgcn_s_setprio(1); _Pragma("unroll") for (int m = 0; m < 4; ++m) _Pragma("unroll") for (int n = 0; n < 2; ++n) _Pragma("unroll") for (int k = 0; k < 2; ++k) \
;         acc[ai][bj][m][n] = __builtin_amdgcn_mfma_f32_16x16x32_bf16(Bt[n][k], At[m][k], acc[ai][bj][m][n], 0, 0, 0); __builtin_amdgcn_s_setprio(0); } while (0)
; #define PG8_WAIT_V(n) asm volatile("s_waitcnt vmcnt(" #n ")" ::: "memory")
; #define PG8_WAIT_L(n) asm volatile("s_waitcnt lgkmcnt(" #n ")" ::: "memory")
; #define PG8_BAR __builtin_amdgcn_s_barrier()
; #define PG8_SCHED __builtin_amdgcn_sched_barrier(0)
; template <class Epi, class Sched, bool ALIGN_EPI>
; __device__ __forceinline__ void gemm_phase(LAS unsigned char* lds, const Gemm g, const Sched& S, const Epi& E, int wave_id) {
;     ...
;             PG8_WAIT_V(8); PG8_WAIT_L(0); PG8_BAR; PG8_MMA(1, 0, At, B0); PG8_MMA(1, 1, At, B1); PG8_BAR; PG8_SCHED;
;             PG8_LDB(B0, 1, 0); PG8_LDB(B1, 1, 1); PG8_SCHED; PG8_LDA(At, 1, 0); PG8_STAGE(PG8_SA(0, 1), a2 + hsA, voffA);
;             PG8_WAIT_V(8); PG8_WAIT_L(0); PG8_BAR; PG8_MMA(0, 0, At, B0); PG8_MMA(0, 1, At, B1); PG8_BAR; PG8_SCHED;
	v_mfma_f32_16x16x32_bf16 v[94:97], v[34:37], v[162:165], v[94:97]
	v_mfma_f32_16x16x32_bf16 v[90:93], v[42:45], v[162:165], v[90:93]
	v_mfma_f32_16x16x32_bf16 v[78:81], v[34:37], v[170:173], v[78:81]
	v_mfma_f32_16x16x32_bf16 v[74:77], v[42:45], v[170:173], v[74:77]
	v_mfma_f32_16x16x32_bf16 v[30:33], v[34:37], v[178:181], v[30:33]
	v_mfma_f32_16x16x32_bf16 v[26:29], v[42:45], v[178:181], v[26:29]
	v_mfma_f32_16x16x32_bf16 v[14:17], v[34:37], v[196:199], v[14:17]
	v_mfma_f32_16x16x32_bf16 v[10:13], v[42:45], v[196:199], v[10:13]
	v_mfma_f32_16x16x32_bf16 v[94:97], v[38:41], v[166:169], v[94:97]
	v_mfma_f32_16x16x32_bf16 v[90:93], v[46:49], v[166:169], v[90:93]
	v_mfma_f32_16x16x32_bf16 v[78:81], v[38:41], v[174:177], v[78:81]
	v_mfma_f32_16x16x32_bf16 v[74:77], v[46:49], v[174:177], v[74:77]
	v_mfma_f32_16x16x32_bf16 v[30:33], v[38:41], v[192:195], v[30:33]
	v_mfma_f32_16x16x32_bf16 v[26:29], v[46:49], v[192:195], v[26:29]
	v_mfma_f32_16x16x32_bf16 v[14:17], v[38:41], v[200:203], v[14:17]
	v_mfma_f32_16x16x32_bf16 v[10:13], v[46:49], v[200:203], v[10:13]
	s_setprio 0
	s_setprio 1
	v_mfma_f32_16x16x32_bf16 v[22:25], v[50:53], v[178:181], v[22:25]
	v_mfma_f32_16x16x32_bf16 v[18:21], v[58:61], v[178:181], v[18:21]
	v_mfma_f32_16x16x32_bf16 v[6:9], v[50:53], v[196:199], v[6:9]
	v_mfma_f32_16x16x32_bf16 v[2:5], v[58:61], v[196:199], v[2:5]
	v_mfma_f32_16x16x32_bf16 v[34:37], v[50:53], v[162:165], v[86:89]
	v_mfma_f32_16x16x32_bf16 v[38:41], v[58:61], v[162:165], v[82:85]
	v_mfma_f32_16x16x32_bf16 v[42:45], v[50:53], v[170:173], v[70:73]
	v_mfma_f32_16x16x32_bf16 v[46:49], v[58:61], v[170:173], v[66:69]
	v_mfma_f32_16x16x32_bf16 v[22:25], v[54:57], v[192:195], v[22:25]
	v_mfma_f32_16x16x32_bf16 v[18:21], v[62:65], v[192:195], v[18:21]
	v_mfma_f32_16x16x32_bf16 v[6:9], v[54:57], v[200:203], v[6:9]
	v_mfma_f32_16x16x32_bf16 v[2:5], v[62:65], v[200:203], v[2:5]
	v_mfma_f32_16x16x32_bf16 v[34:37], v[54:57], v[166:169], v[34:37]
	v_mfma_f32_16x16x32_bf16 v[38:41], v[62:65], v[166:169], v[38:41]
	v_mfma_f32_16x16x32_bf16 v[42:45], v[54:57], v[174:177], v[42:45]
	v_mfma_f32_16x16x32_bf16 v[46:49], v[62:65], v[174:177], v[46:49]
	s_setprio 0
	s_barrier
	s_add_u32 s28, s34, 0x160000
	s_addc_u32 s29, s35, 0
	s_mov_b32 m0, s48
	v_lshl_add_u64 v[210:211], s[28:29], 0, v[182:183]
	global_load_lds_dwordx4 v[210:211], off
	v_lshl_add_u64 v[210:211], s[28:29], 0, v[184:185]
	s_mov_b32 m0, s49
	s_nop 0
	global_load_lds_dwordx4 v[210:211], off
	v_add_u32_e32 v62, 0x18400, v208
	v_add_u32_e32 v66, 0x1c400, v208
	ds_read_b128 v[50:53], v62
	ds_read_b128 v[54:57], v62 offset:1024
	ds_read_b128 v[58:61], v62 offset:2048
	ds_read_b128 v[62:65], v62 offset:3072
	ds_read_b128 v[162:165], v66
	ds_read_b128 v[166:169], v66 offset:1024
	ds_read_b128 v[170:173], v66 offset:2048
	ds_read_b128 v[174:177], v66 offset:3072
	ds_read_b128 v[66:69], v207 offset:33792
	ds_read_b128 v[70:73], v207 offset:34816
	ds_read_b128 v[82:85], v207 offset:35840
	ds_read_b128 v[86:89], v207 offset:36864
	ds_read_b128 v[178:181], v207 offset:37888
	ds_read_b128 v[192:195], v207 offset:38912
	ds_read_b128 v[196:199], v207 offset:39936
	ds_read_b128 v[200:203], v207 offset:40960
	s_setprio 1
	s_waitcnt vmcnt(8) lgkmcnt(0)
	s_barrier
	v_mfma_f32_16x16x32_bf16 v[158:161], v[50:53], v[66:69], v[158:161]
	v_mfma_f32_16x16x32_bf16 v[154:157], v[58:61], v[66:69], v[154:157]
	v_mfma_f32_16x16x32_bf16 v[142:145], v[50:53], v[82:85], v[142:145]
	v_mfma_f32_16x16x32_bf16 v[138:141], v[58:61], v[82:85], v[138:141]
	v_mfma_f32_16x16x32_bf16 v[126:129], v[50:53], v[178:181], v[126:129]
	v_mfma_f32_16x16x32_bf16 v[122:125], v[58:61], v[178:181], v[122:125]
	v_mfma_f32_16x16x32_bf16 v[110:113], v[50:53], v[196:199], v[110:113]
	v_mfma_f32_16x16x32_bf16 v[106:109], v[58:61], v[196:199], v[106:109]
	v_mfma_f32_16x16x32_bf16 v[158:161], v[54:57], v[70:73], v[158:161]
	v_mfma_f32_16x16x32_bf16 v[154:157], v[62:65], v[70:73], v[154:157]
	v_mfma_f32_16x16x32_bf16 v[142:145], v[54:57], v[86:89], v[142:145]
	v_mfma_f32_16x16x32_bf16 v[138:141], v[62:65], v[86:89], v[138:141]
	v_mfma_f32_16x16x32_bf16 v[126:129], v[54:57], v[192:195], v[126:129]
	v_mfma_f32_16x16x32_bf16 v[122:125], v[62:65], v[192:195], v[122:125]
	v_mfma_f32_16x16x32_bf16 v[110:113], v[54:57], v[200:203], v[110:113]
	v_mfma_f32_16x16x32_bf16 v[106:109], v[62:65], v[200:203], v[106:109]
	s_setprio 0
	s_setprio 1
	v_mfma_f32_16x16x32_bf16 v[150:153], v[162:165], v[66:69], v[150:153]
	v_mfma_f32_16x16x32_bf16 v[66:69], v[170:173], v[66:69], v[146:149]
	v_mfma_f32_16x16x32_bf16 v[146:149], v[174:177], v[70:73], v[66:69]
	v_mfma_f32_16x16x32_bf16 v[66:69], v[162:165], v[82:85], v[134:137]
	v_mfma_f32_16x16x32_bf16 v[134:137], v[166:169], v[86:89], v[66:69]
	v_mfma_f32_16x16x32_bf16 v[66:69], v[170:173], v[82:85], v[130:133]
	v_mfma_f32_16x16x32_bf16 v[130:133], v[174:177], v[86:89], v[66:69]
	v_mfma_f32_16x16x32_bf16 v[66:69], v[162:165], v[178:181], v[118:121]
	v_mfma_f32_16x16x32_bf16 v[118:121], v[166:169], v[192:195], v[66:69]
	v_mfma_f32_16x16x32_bf16 v[66:69], v[170:173], v[178:181], v[114:117]
	v_mfma_f32_16x16x32_bf16 v[114:117], v[174:177], v[192:195], v[66:69]
	v_mfma_f32_16x16x32_bf16 v[66:69], v[162:165], v[196:199], v[102:105]
	v_mfma_f32_16x16x32_bf16 v[102:105], v[166:169], v[200:203], v[66:69]
	v_mfma_f32_16x16x32_bf16 v[66:69], v[170:173], v[196:199], v[98:101]
	v_mfma_f32_16x16x32_bf16 v[150:153], v[166:169], v[70:73], v[150:153]
	v_mfma_f32_16x16x32_bf16 v[98:101], v[174:177], v[200:203], v[66:69]
	s_setprio 0
	s_barrier
; #define PG8_STAGE(bufoff, gbase, voff) do { _Pragma("unroll") for (int _i = 0; _i < 2; ++_i) \
;         __builtin_amdgcn_global_load_lds((const GAS unsigned*)((const GAS char*)(gbase) + (voff)[_i]), (LAS unsigned*)(lds + (bufoff) + ldsw + _i * 8192), 16, 0, 0); } while (0)
; #define PG8_LDA(dst, b, h) do { _Pragma("unroll") for (int m = 0; m < 4; ++m) _Pragma("unroll") for (int k = 0; k < 2; ++k) dst[m][k] = *(const LAS bf16x8*)(lds + PG8_SA(b, h) + aoff + m * 2048 + k * 1024); } while (0)
; #define PG8_MMA(ai, bj, At, Bt) do { __builtin_amdgcn_s_setprio(1); _Pragma("unroll") for (int m = 0; m < 4; ++m) _Pragma("unroll") for (int n = 0; n < 2; ++n) _Pragma("unroll") for (int k = 0; k < 2; ++k) \
;         acc[ai][bj][m][n] = __builtin_amdgcn_mfma_f32_16x16x32_bf16(Bt[n][k], At[m][k], acc[ai][bj][m][n], 0, 0, 0); __builtin_amdgcn_s_setprio(0); } while (0)
; #define PG8_WAIT_V(n) asm volatile("s_waitcnt vmcnt(" #n ")" ::: "memory")
; #define PG8_WAIT_L(n) asm volatile("s_waitcnt lgkmcnt(" #n ")" ::: "memory")
; #define PG8_BAR __builtin_amdgcn_s_barrier()
; #define PG8_SCHED __builtin_amdgcn_sched_barrier(0)
; template <class Epi, class Sched, bool ALIGN_EPI>
; __device__ __forceinline__ void gemm_phase(LAS unsigned char* lds, const Gemm g, const Sched& S, const Epi& E, int wave_id) {
;     ...
;             PG8_LDA(At, 1, 1); PG8_STAGE(PG8_SB(1, 0), b3, voffB); PG8_STAGE(PG8_SB(1, 1), b3 + hsB, voffB); PG8_STAGE(PG8_SA(1, 0), a3, voffA);
;             PG8_WAIT_V(8); PG8_WAIT_L(0); PG8_BAR; PG8_MMA(1, 0, At, B0); PG8_MMA(1, 1, At, B1); PG8_BAR; PG8_SCHED;
;         }
	s_mov_b32 m0, s52
	v_lshl_add_u64 v[82:83], v[204:205], 0, s[92:93]
	s_add_u32 s28, s30, 0x160080
	s_nop 0
	global_load_lds_dwordx4 v[82:83], off
	v_lshl_add_u64 v[82:83], v[218:219], 0, s[92:93]
	s_mov_b32 m0, s53
	s_addc_u32 s29, s31, 0
	global_load_lds_dwordx4 v[82:83], off
	v_lshl_add_u64 v[82:83], s[28:29], 0, v[0:1]
	s_mov_b32 m0, s56
	s_nop 0
	global_load_lds_dwordx4 v[82:83], off
	v_lshl_add_u64 v[82:83], s[28:29], 0, v[186:187]
	s_mov_b32 m0, s57
	s_nop 0
	global_load_lds_dwordx4 v[82:83], off
	v_lshl_add_u64 v[82:83], v[220:221], 0, s[92:93]
	s_mov_b32 m0, s54
	s_nop 0
	global_load_lds_dwordx4 v[82:83], off
	v_lshl_add_u64 v[82:83], v[224:225], 0, s[92:93]
	s_mov_b32 m0, s55
	s_nop 0
	global_load_lds_dwordx4 v[82:83], off
	ds_read_b128 v[66:69], v207 offset:50176
	ds_read_b128 v[70:73], v207 offset:51200
	ds_read_b128 v[178:181], v207 offset:52224
	ds_read_b128 v[192:195], v207 offset:53248
	ds_read_b128 v[196:199], v207 offset:54272
	ds_read_b128 v[200:203], v207 offset:55296
	ds_read_b128 v[210:213], v207 offset:56320
	ds_read_b128 v[214:217], v207 offset:57344
	s_setprio 1
	s_waitcnt vmcnt(8) lgkmcnt(0)
	s_barrier
	v_mfma_f32_16x16x32_bf16 v[82:85], v[50:53], v[66:69], v[94:97]
	v_mfma_f32_16x16x32_bf16 v[94:97], v[54:57], v[70:73], v[82:85]
	v_mfma_f32_16x16x32_bf16 v[82:85], v[58:61], v[66:69], v[90:93]
	v_mfma_f32_16x16x32_bf16 v[78:81], v[50:53], v[178:181], v[78:81]
	v_mfma_f32_16x16x32_bf16 v[74:77], v[58:61], v[178:181], v[74:77]
	v_mfma_f32_16x16x32_bf16 v[30:33], v[50:53], v[196:199], v[30:33]
	v_mfma_f32_16x16x32_bf16 v[26:29], v[58:61], v[196:199], v[26:29]
	v_mfma_f32_16x16x32_bf16 v[14:17], v[50:53], v[210:213], v[14:17]
	v_mfma_f32_16x16x32_bf16 v[10:13], v[58:61], v[210:213], v[10:13]
	v_mfma_f32_16x16x32_bf16 v[90:93], v[62:65], v[70:73], v[82:85]
	v_mfma_f32_16x16x32_bf16 v[78:81], v[54:57], v[192:195], v[78:81]
	v_mfma_f32_16x16x32_bf16 v[74:77], v[62:65], v[192:195], v[74:77]
	v_mfma_f32_16x16x32_bf16 v[30:33], v[54:57], v[200:203], v[30:33]
	v_mfma_f32_16x16x32_bf16 v[26:29], v[62:65], v[200:203], v[26:29]
	v_mfma_f32_16x16x32_bf16 v[14:17], v[54:57], v[214:217], v[14:17]
	v_mfma_f32_16x16x32_bf16 v[10:13], v[62:65], v[214:217], v[10:13]
	s_setprio 0
	s_setprio 1
	v_mfma_f32_16x16x32_bf16 v[34:37], v[162:165], v[66:69], v[34:37]
	v_mfma_f32_16x16x32_bf16 v[86:89], v[166:169], v[70:73], v[34:37]
	v_mfma_f32_16x16x32_bf16 v[34:37], v[170:173], v[66:69], v[38:41]
	v_mfma_f32_16x16x32_bf16 v[82:85], v[174:177], v[70:73], v[34:37]
	v_mfma_f32_16x16x32_bf16 v[34:37], v[162:165], v[178:181], v[42:45]
	v_mfma_f32_16x16x32_bf16 v[70:73], v[166:169], v[192:195], v[34:37]
	v_mfma_f32_16x16x32_bf16 v[34:37], v[170:173], v[178:181], v[46:49]
	v_mfma_f32_16x16x32_bf16 v[22:25], v[162:165], v[196:199], v[22:25]
	v_mfma_f32_16x16x32_bf16 v[18:21], v[170:173], v[196:199], v[18:21]
	v_mfma_f32_16x16x32_bf16 v[6:9], v[162:165], v[210:213], v[6:9]
	v_mfma_f32_16x16x32_bf16 v[2:5], v[170:173], v[210:213], v[2:5]
	v_mfma_f32_16x16x32_bf16 v[66:69], v[174:177], v[192:195], v[34:37]
	v_mfma_f32_16x16x32_bf16 v[22:25], v[166:169], v[200:203], v[22:25]
	v_mfma_f32_16x16x32_bf16 v[18:21], v[174:177], v[200:203], v[18:21]
	v_mfma_f32_16x16x32_bf16 v[6:9], v[166:169], v[214:217], v[6:9]
	v_mfma_f32_16x16x32_bf16 v[2:5], v[174:177], v[214:217], v[2:5]
	s_setprio 0
	s_barrier
	s_add_i32 s63, s63, 2
	s_add_u32 s61, s61, 0x100
	s_addc_u32 s62, s62, 0
	s_cmpk_gt_u32 s63, 0x55
	s_mov_b64 s[28:29], s[0:1]
	s_cbranch_scc0 .LBB0_3681
	s_and_b64 vcc, exec, s[22:23]
	s_cbranch_vccz .LBB0_3684
	s_barrier
